# lever 7: K-loop LDS-DMA in scalar-base form (global_load_lds_dwordx4 vOff, s[base]); 43 of the 64-bit VALU address adds removed from the load segments; no s_setprio
# baseline (speedup 1.0000x reference)
;     __device__ __forceinline__ Pre prefetch(const Unit& u, int tid) const { return prenorm_load(stats, u.pn * BM, sW + (size_t)(u.pn >> 4) * SW_ROWS + u.pm * BM, tid); }
;     __device__ __forceinline__ Pre prefetch(const Unit& u, int tid) const { return prenorm_load(stats, u.pm * BM, sW + (size_t)(u.pm >> 4) * SW_ROWS + u.pn * BM, tid); }
;     __device__ __forceinline__ Pre prefetch(const Unit& u, int tid) const { return prenorm_load(stats, u.pm * BM, sW + (size_t)(u.pm >> 4) * SW_ROWS + u.pn * BM, tid); }
; #define PG8_STAGE(bufoff, gbase, voff) do { _Pragma("unroll") for (int _i = 0; _i < 2; ++_i) \
;         __builtin_amdgcn_global_load_lds((const unsigned*)((const char*)(gbase) + (voff)[_i]), (LAS unsigned*)(lds + (bufoff) + ldsw + _i * 8192), 16, 0, 0); } while (0)
; #define PG8_LDA(dst, b, h) do { _Pragma("unroll") for (int m = 0; m < 4; ++m) _Pragma("unroll") for (int k = 0; k < 2; ++k) dst[m][k] = *(const LAS bf16x8*)(lds + PG8_SA(b, h) + aoff + m * 2048 + k * 1024); } while (0)
; #define PG8_WAIT_V(n) asm volatile("s_waitcnt vmcnt(" #n ")" ::: "memory")
; template <class Epi, class Sched>
; __device__ __forceinline__ void gemm_phase(LAS unsigned char* lds, const Gemm g, const Sched& S, const Epi& E, const int tid) {
;     ...
;         const bool has_next = S.next(ui + 1, nxt);
;         const char* nA = has_next ? (const char*)g.A + (size_t)nxt.pm * tstep : cA; const char* nB = has_next ? (const char*)g.Bt + (size_t)nxt.pn * tstep : cB;
;         const typename Epi::Pre pre = E.prefetch(cur, tid);
;         for (int t = 0; t < nt; t += 2) {
;             const bool last = (t == nt - 2);
;             const char* a1 = cA + (size_t)(t + 1) * kstep;
;             const char* a2 = last ? nA : cA + (size_t)(t + 2) * kstep; const char* b2 = last ? nB : cB + (size_t)(t + 2) * kstep;
;             const char* a3 = a2 + kstep; const char* b3 = b2 + kstep;
;             PG8_LDB(B0, 0, 0); PG8_LDB(B1, 0, 1); PG8_SCHED; PG8_LDA(At, 0, 0); PG8_STAGE(PG8_SA(1, 1), a1 + hstep, voffA);
;             PG8_WAIT_V(8); PG8_WAIT_L(0); PG8_BAR; PG8_MMA(0, 0, At, B0); PG8_MMA(0, 1, At, B1); PG8_BAR; PG8_SCHED;
;             PG8_LDA(At, 0, 1); PG8_STAGE(PG8_SB(0, 0), b2, voffB); PG8_STAGE(PG8_SB(0, 1), b2 + hstep, voffB); PG8_STAGE(PG8_SA(0, 0), a2, voffA);
;             PG8_WAIT_V(8); PG8_WAIT_L(0); PG8_BAR; PG8_MMA(1, 0, At, B0); PG8_MMA(1, 1, At, B1); PG8_BAR; PG8_SCHED;
.LBB0_167:
	s_or_b64 exec, exec, s[22:23]
	s_ashr_i32 s55, s54, 31
	s_lshl_b64 s[22:23], s[54:55], 19
	s_add_u32 s22, s46, s22
	s_addc_u32 s23, s47, s23
	s_and_b64 s[38:39], s[6:7], exec
	s_cselect_b32 s55, s23, s65
	s_cselect_b32 s56, s22, s64
	s_ashr_i32 s63, s62, 31
	s_lshl_b64 s[38:39], s[62:63], 19
	s_add_u32 s38, s12, s38
	s_addc_u32 s39, s73, s39
	s_and_b64 s[58:59], s[6:7], exec
	s_cselect_b32 s57, s39, s67
	s_cselect_b32 s58, s38, s66
	s_add_u32 s64, s64, 0x40080
	s_addc_u32 s65, s65, 0
	s_add_u32 s59, s66, 0x100
	s_addc_u32 s60, s67, 0
	s_mov_b32 s61, -2
	s_add_u32 s63, s64, 0xfffc0080
	s_addc_u32 s66, s65, -1
	s_add_i32 s78, 0, 0x10000
	s_cmp_eq_u32 s61, 12
	s_cselect_b32 s71, s55, s66
	s_cselect_b32 s70, s56, s63
	v_add_u32_e32 v145, s78, v166
	s_cselect_b32 s67, s57, s60
	s_cselect_b32 s66, s58, s59
	s_add_i32 s63, 0, 0x14000
	ds_read_b128 v[146:149], v145
	ds_read_b128 v[150:153], v145 offset:1024
	ds_read_b128 v[154:157], v145 offset:2048
	ds_read_b128 v[158:161], v145 offset:3072
	v_add_u32_e32 v145, s63, v166
	ds_read_b128 v[172:175], v145
	ds_read_b128 v[176:179], v145 offset:1024
	ds_read_b128 v[180:183], v145 offset:2048
	ds_read_b128 v[184:187], v145 offset:3072
	s_add_i32 m0, s75, 0xc000
	ds_read_b128 v[188:191], v171
	ds_read_b128 v[198:201], v171 offset:1024
	ds_read_b128 v[202:205], v171 offset:2048
	ds_read_b128 v[206:209], v171 offset:3072
	ds_read_b128 v[210:213], v171 offset:4096
	ds_read_b128 v[214:217], v171 offset:5120
	ds_read_b128 v[218:221], v171 offset:6144
	ds_read_b128 v[230:233], v171 offset:7168
	global_load_lds_dwordx4 v140, s[64:65]
	s_add_i32 m0, s75, 0xe000
	s_nop 0
	global_load_lds_dwordx4 v142, s[64:65]
	s_waitcnt vmcnt(8)
	s_waitcnt lgkmcnt(0)
	s_barrier
	s_waitcnt lgkmcnt(0)
	v_mfma_f32_16x16x32_bf16 v[128:131], v[146:149], v[188:191], 0
	v_mfma_f32_16x16x32_bf16 v[124:127], v[154:157], v[188:191], 0
	v_mfma_f32_16x16x32_bf16 v[104:107], v[154:157], v[202:205], 0
	v_mfma_f32_16x16x32_bf16 v[108:111], v[146:149], v[202:205], 0
	v_mfma_f32_16x16x32_bf16 v[92:95], v[146:149], v[210:213], 0
	v_mfma_f32_16x16x32_bf16 v[88:91], v[154:157], v[210:213], 0
	v_mfma_f32_16x16x32_bf16 v[72:75], v[154:157], v[218:221], 0
	v_mfma_f32_16x16x32_bf16 v[76:79], v[146:149], v[218:221], 0
	v_mfma_f32_16x16x32_bf16 v[128:131], v[150:153], v[198:201], v[128:131]
	v_mfma_f32_16x16x32_bf16 v[124:127], v[158:161], v[198:201], v[124:127]
	v_mfma_f32_16x16x32_bf16 v[104:107], v[158:161], v[206:209], v[104:107]
	v_mfma_f32_16x16x32_bf16 v[108:111], v[150:153], v[206:209], v[108:111]
	v_mfma_f32_16x16x32_bf16 v[92:95], v[150:153], v[214:217], v[92:95]
	v_mfma_f32_16x16x32_bf16 v[88:91], v[158:161], v[214:217], v[88:91]
	v_mfma_f32_16x16x32_bf16 v[72:75], v[158:161], v[230:233], v[72:75]
	v_mfma_f32_16x16x32_bf16 v[76:79], v[150:153], v[230:233], v[76:79]
	v_mfma_f32_16x16x32_bf16 v[120:123], v[172:175], v[188:191], 0
	v_mfma_f32_16x16x32_bf16 v[116:119], v[180:183], v[188:191], 0
	v_mfma_f32_16x16x32_bf16 v[96:99], v[180:183], v[202:205], 0
	v_mfma_f32_16x16x32_bf16 v[100:103], v[172:175], v[202:205], 0
	v_mfma_f32_16x16x32_bf16 v[84:87], v[172:175], v[210:213], 0
	v_mfma_f32_16x16x32_bf16 v[80:83], v[180:183], v[210:213], 0
	v_mfma_f32_16x16x32_bf16 v[64:67], v[180:183], v[218:221], 0
	v_mfma_f32_16x16x32_bf16 v[68:71], v[172:175], v[218:221], 0
	v_mfma_f32_16x16x32_bf16 v[120:123], v[176:179], v[198:201], v[120:123]
	v_mfma_f32_16x16x32_bf16 v[116:119], v[184:187], v[198:201], v[116:119]
	v_mfma_f32_16x16x32_bf16 v[96:99], v[184:187], v[206:209], v[96:99]
	v_mfma_f32_16x16x32_bf16 v[100:103], v[176:179], v[206:209], v[100:103]
	v_mfma_f32_16x16x32_bf16 v[84:87], v[176:179], v[214:217], v[84:87]
	v_mfma_f32_16x16x32_bf16 v[80:83], v[184:187], v[214:217], v[80:83]
	v_mfma_f32_16x16x32_bf16 v[64:67], v[184:187], v[230:233], v[64:67]
	v_mfma_f32_16x16x32_bf16 v[68:71], v[176:179], v[230:233], v[68:71]
	s_barrier
	s_add_i32 s78, s78, s74
	v_lshl_add_u64 v[162:163], s[66:67], 0, v[192:193]
	s_mov_b32 m0, s78
	ds_read_b128 v[188:191], v171 offset:16384
	ds_read_b128 v[198:201], v171 offset:17408
	ds_read_b128 v[202:205], v171 offset:18432
	ds_read_b128 v[206:209], v171 offset:19456
	ds_read_b128 v[210:213], v171 offset:20480
	ds_read_b128 v[214:217], v171 offset:21504
	ds_read_b128 v[218:221], v171 offset:22528
	ds_read_b128 v[230:233], v171 offset:23552
	global_load_lds_dwordx4 v192, s[66:67]
	s_add_i32 m0, s78, 0x2000
	s_add_u32 s78, s66, 0x40000
	v_lshl_add_u64 v[234:235], s[66:67], 0, v[134:135]
	s_addc_u32 s79, s67, 0
	s_add_i32 s63, s63, s74
	global_load_lds_dwordx4 v134, s[66:67]
	s_mov_b32 m0, s63
	v_lshl_add_u64 v[238:239], s[70:71], 0, v[136:137]
	global_load_lds_dwordx4 v192, s[78:79]
	s_add_i32 m0, s63, 0x2000
	s_nop 0
	global_load_lds_dwordx4 v134, s[78:79]
	v_lshl_add_u64 v[236:237], s[70:71], 0, v[138:139]
	s_mov_b32 m0, s75
	s_nop 0
	global_load_lds_dwordx4 v138, s[70:71]
	s_mov_b32 m0, s81
	s_nop 0
	global_load_lds_dwordx4 v136, s[70:71]
	s_waitcnt vmcnt(8)
	s_waitcnt lgkmcnt(0)
	s_barrier
; #define PG8_STAGE(bufoff, gbase, voff) do { _Pragma("unroll") for (int _i = 0; _i < 2; ++_i) \
;         __builtin_amdgcn_global_load_lds((const unsigned*)((const char*)(gbase) + (voff)[_i]), (LAS unsigned*)(lds + (bufoff) + ldsw + _i * 8192), 16, 0, 0); } while (0)
; #define PG8_LDA(dst, b, h) do { _Pragma("unroll") for (int m = 0; m < 4; ++m) _Pragma("unroll") for (int k = 0; k < 2; ++k) dst[m][k] = *(const LAS bf16x8*)(lds + PG8_SA(b, h) + aoff + m * 2048 + k * 1024); } while (0)
; #define PG8_LDB(dst, b, h) do { _Pragma("unroll") for (int n = 0; n < 2; ++n) _Pragma("unroll") for (int k = 0; k < 2; ++k) dst[n][k] = *(const LAS bf16x8*)(lds + PG8_SB(b, h) + boff + n * 2048 + k * 1024); } while (0)
; #define PG8_MMA(ai, bj, At, Bt) do { __builtin_amdgcn_s_setprio(1); _Pragma("unroll") for (int m = 0; m < 4; ++m) _Pragma("unroll") for (int n = 0; n < 2; ++n) _Pragma("unroll") for (int k = 0; k < 2; ++k) \
;         acc[ai][bj][m][n] = __builtin_amdgcn_mfma_f32_16x16x32_bf16(Bt[n][k], At[m][k], acc[ai][bj][m][n], 0, 0, 0); __builtin_amdgcn_s_setprio(0); } while (0)
; #define PG8_WAIT_V(n) asm volatile("s_waitcnt vmcnt(" #n ")" ::: "memory")
; #define PG8_WAIT_L(n) asm volatile("s_waitcnt lgkmcnt(" #n ")" ::: "memory")
; #define PG8_BAR __builtin_amdgcn_s_barrier()
; #define PG8_SCHED __builtin_amdgcn_sched_barrier(0)
; template <class Epi, class Sched>
; __device__ __forceinline__ void gemm_phase(LAS unsigned char* lds, const Gemm g, const Sched& S, const Epi& E, const int tid) {
;     ...
;             PG8_WAIT_V(8); PG8_WAIT_L(0); PG8_BAR; PG8_MMA(0, 0, At, B0); PG8_MMA(0, 1, At, B1); PG8_BAR; PG8_SCHED;
;             PG8_LDA(At, 0, 1); PG8_STAGE(PG8_SB(0, 0), b2, voffB); PG8_STAGE(PG8_SB(0, 1), b2 + hstep, voffB); PG8_STAGE(PG8_SA(0, 0), a2, voffA);
;             PG8_WAIT_V(8); PG8_WAIT_L(0); PG8_BAR; PG8_MMA(1, 0, At, B0); PG8_MMA(1, 1, At, B1); PG8_BAR; PG8_SCHED;
;             PG8_LDB(B0, 1, 0); PG8_LDB(B1, 1, 1); PG8_SCHED; PG8_LDA(At, 1, 0); PG8_STAGE(PG8_SA(0, 1), a2 + hstep, voffA);
;             PG8_WAIT_V(8); PG8_WAIT_L(0); PG8_BAR; PG8_MMA(0, 0, At, B0); PG8_MMA(0, 1, At, B1); PG8_BAR; PG8_SCHED;
	s_waitcnt lgkmcnt(0)
	v_mfma_f32_16x16x32_bf16 v[60:63], v[146:149], v[188:191], 0
	v_mfma_f32_16x16x32_bf16 v[56:59], v[154:157], v[188:191], 0
	v_mfma_f32_16x16x32_bf16 v[40:43], v[154:157], v[202:205], 0
	v_mfma_f32_16x16x32_bf16 v[44:47], v[146:149], v[202:205], 0
	v_mfma_f32_16x16x32_bf16 v[28:31], v[146:149], v[210:213], 0
	v_mfma_f32_16x16x32_bf16 v[24:27], v[154:157], v[210:213], 0
	v_mfma_f32_16x16x32_bf16 v[8:11], v[154:157], v[218:221], 0
	v_mfma_f32_16x16x32_bf16 v[12:15], v[146:149], v[218:221], 0
	v_mfma_f32_16x16x32_bf16 v[60:63], v[150:153], v[198:201], v[60:63]
	v_mfma_f32_16x16x32_bf16 v[56:59], v[158:161], v[198:201], v[56:59]
	v_mfma_f32_16x16x32_bf16 v[40:43], v[158:161], v[206:209], v[40:43]
	v_mfma_f32_16x16x32_bf16 v[44:47], v[150:153], v[206:209], v[44:47]
	v_mfma_f32_16x16x32_bf16 v[28:31], v[150:153], v[214:217], v[28:31]
	v_mfma_f32_16x16x32_bf16 v[24:27], v[158:161], v[214:217], v[24:27]
	v_mfma_f32_16x16x32_bf16 v[8:11], v[158:161], v[230:233], v[8:11]
	v_mfma_f32_16x16x32_bf16 v[12:15], v[150:153], v[230:233], v[12:15]
	v_mfma_f32_16x16x32_bf16 v[52:55], v[172:175], v[188:191], 0
	v_mfma_f32_16x16x32_bf16 v[48:51], v[180:183], v[188:191], 0
	v_mfma_f32_16x16x32_bf16 v[32:35], v[180:183], v[202:205], 0
	v_mfma_f32_16x16x32_bf16 v[36:39], v[172:175], v[202:205], 0
	v_mfma_f32_16x16x32_bf16 v[20:23], v[172:175], v[210:213], 0
	v_mfma_f32_16x16x32_bf16 v[16:19], v[180:183], v[210:213], 0
	v_mfma_f32_16x16x32_bf16 v[0:3], v[180:183], v[218:221], 0
	v_mfma_f32_16x16x32_bf16 v[4:7], v[172:175], v[218:221], 0
	v_mfma_f32_16x16x32_bf16 v[52:55], v[176:179], v[198:201], v[52:55]
	v_mfma_f32_16x16x32_bf16 v[48:51], v[184:187], v[198:201], v[48:51]
	v_mfma_f32_16x16x32_bf16 v[32:35], v[184:187], v[206:209], v[32:35]
	v_mfma_f32_16x16x32_bf16 v[36:39], v[176:179], v[206:209], v[36:39]
	v_mfma_f32_16x16x32_bf16 v[20:23], v[176:179], v[214:217], v[20:23]
	v_mfma_f32_16x16x32_bf16 v[16:19], v[184:187], v[214:217], v[16:19]
	v_mfma_f32_16x16x32_bf16 v[0:3], v[184:187], v[230:233], v[0:3]
	v_mfma_f32_16x16x32_bf16 v[4:7], v[176:179], v[230:233], v[4:7]
	s_barrier
	s_add_i32 s63, 0, 0x18000
	v_add_u32_e32 v145, s63, v166
	s_add_i32 s78, 0, 0x1c000
	ds_read_b128 v[146:149], v145
	ds_read_b128 v[150:153], v145 offset:1024
	ds_read_b128 v[154:157], v145 offset:2048
	ds_read_b128 v[158:161], v145 offset:3072
	v_add_u32_e32 v145, s78, v166
	ds_read_b128 v[172:175], v145
	ds_read_b128 v[176:179], v145 offset:1024
	ds_read_b128 v[180:183], v145 offset:2048
	ds_read_b128 v[184:187], v145 offset:3072
	s_add_u32 s70, s70, 0x40000
	s_addc_u32 s71, s71, 0
	s_mov_b32 m0, s82
	ds_read_b128 v[188:191], v171 offset:32768
	ds_read_b128 v[198:201], v171 offset:33792
	ds_read_b128 v[202:205], v171 offset:34816
	ds_read_b128 v[206:209], v171 offset:35840
	ds_read_b128 v[210:213], v171 offset:36864
	ds_read_b128 v[214:217], v171 offset:37888
	ds_read_b128 v[218:221], v171 offset:38912
	ds_read_b128 v[230:233], v171 offset:39936
	global_load_lds_dwordx4 v138, s[70:71]
	s_mov_b32 m0, s83
	s_nop 0
	global_load_lds_dwordx4 v136, s[70:71]
	s_waitcnt vmcnt(8)
	s_waitcnt lgkmcnt(0)
	s_barrier
	s_waitcnt lgkmcnt(0)
	v_mfma_f32_16x16x32_bf16 v[128:131], v[146:149], v[188:191], v[128:131]
	v_mfma_f32_16x16x32_bf16 v[124:127], v[154:157], v[188:191], v[124:127]
	v_mfma_f32_16x16x32_bf16 v[104:107], v[154:157], v[202:205], v[104:107]
	v_mfma_f32_16x16x32_bf16 v[108:111], v[146:149], v[202:205], v[108:111]
	v_mfma_f32_16x16x32_bf16 v[92:95], v[146:149], v[210:213], v[92:95]
	v_mfma_f32_16x16x32_bf16 v[88:91], v[154:157], v[210:213], v[88:91]
	v_mfma_f32_16x16x32_bf16 v[72:75], v[154:157], v[218:221], v[72:75]
	v_mfma_f32_16x16x32_bf16 v[76:79], v[146:149], v[218:221], v[76:79]
	v_mfma_f32_16x16x32_bf16 v[128:131], v[150:153], v[198:201], v[128:131]
	v_mfma_f32_16x16x32_bf16 v[124:127], v[158:161], v[198:201], v[124:127]
	v_mfma_f32_16x16x32_bf16 v[104:107], v[158:161], v[206:209], v[104:107]
	v_mfma_f32_16x16x32_bf16 v[108:111], v[150:153], v[206:209], v[108:111]
	v_mfma_f32_16x16x32_bf16 v[92:95], v[150:153], v[214:217], v[92:95]
	v_mfma_f32_16x16x32_bf16 v[88:91], v[158:161], v[214:217], v[88:91]
	v_mfma_f32_16x16x32_bf16 v[72:75], v[158:161], v[230:233], v[72:75]
	v_mfma_f32_16x16x32_bf16 v[76:79], v[150:153], v[230:233], v[76:79]
	v_mfma_f32_16x16x32_bf16 v[120:123], v[172:175], v[188:191], v[120:123]
	v_mfma_f32_16x16x32_bf16 v[116:119], v[180:183], v[188:191], v[116:119]
	v_mfma_f32_16x16x32_bf16 v[96:99], v[180:183], v[202:205], v[96:99]
	v_mfma_f32_16x16x32_bf16 v[100:103], v[172:175], v[202:205], v[100:103]
	v_mfma_f32_16x16x32_bf16 v[84:87], v[172:175], v[210:213], v[84:87]
	v_mfma_f32_16x16x32_bf16 v[80:83], v[180:183], v[210:213], v[80:83]
	v_mfma_f32_16x16x32_bf16 v[64:67], v[180:183], v[218:221], v[64:67]
	v_mfma_f32_16x16x32_bf16 v[68:71], v[172:175], v[218:221], v[68:71]
	v_mfma_f32_16x16x32_bf16 v[120:123], v[176:179], v[198:201], v[120:123]
	v_mfma_f32_16x16x32_bf16 v[116:119], v[184:187], v[198:201], v[116:119]
	v_mfma_f32_16x16x32_bf16 v[96:99], v[184:187], v[206:209], v[96:99]
	v_mfma_f32_16x16x32_bf16 v[100:103], v[176:179], v[206:209], v[100:103]
	v_mfma_f32_16x16x32_bf16 v[84:87], v[176:179], v[214:217], v[84:87]
	v_mfma_f32_16x16x32_bf16 v[80:83], v[184:187], v[214:217], v[80:83]
	v_mfma_f32_16x16x32_bf16 v[64:67], v[184:187], v[230:233], v[64:67]
	v_mfma_f32_16x16x32_bf16 v[68:71], v[176:179], v[230:233], v[68:71]
	s_barrier
; #define PG8_STAGE(bufoff, gbase, voff) do { _Pragma("unroll") for (int _i = 0; _i < 2; ++_i) \
;         __builtin_amdgcn_global_load_lds((const unsigned*)((const char*)(gbase) + (voff)[_i]), (LAS unsigned*)(lds + (bufoff) + ldsw + _i * 8192), 16, 0, 0); } while (0)
; #define PG8_LDA(dst, b, h) do { _Pragma("unroll") for (int m = 0; m < 4; ++m) _Pragma("unroll") for (int k = 0; k < 2; ++k) dst[m][k] = *(const LAS bf16x8*)(lds + PG8_SA(b, h) + aoff + m * 2048 + k * 1024); } while (0)
; #define PG8_LDB(dst, b, h) do { _Pragma("unroll") for (int n = 0; n < 2; ++n) _Pragma("unroll") for (int k = 0; k < 2; ++k) dst[n][k] = *(const LAS bf16x8*)(lds + PG8_SB(b, h) + boff + n * 2048 + k * 1024); } while (0)
; #define PG8_WAIT_V(n) asm volatile("s_waitcnt vmcnt(" #n ")" ::: "memory")
; #define PG8_BAR __builtin_amdgcn_s_barrier()
; template <class Epi, class Sched>
; __device__ __forceinline__ void gemm_phase(LAS unsigned char* lds, const Gemm g, const Sched& S, const Epi& E, const int tid) {
;     ...
;         for (int t = 0; t < nt; t += 2) {
;             const bool last = (t == nt - 2);
;             const char* a1 = cA + (size_t)(t + 1) * kstep;
;             const char* a2 = last ? nA : cA + (size_t)(t + 2) * kstep; const char* b2 = last ? nB : cB + (size_t)(t + 2) * kstep;
;             const char* a3 = a2 + kstep; const char* b3 = b2 + kstep;
;             PG8_LDB(B0, 0, 0); PG8_LDB(B1, 0, 1); PG8_SCHED; PG8_LDA(At, 0, 0); PG8_STAGE(PG8_SA(1, 1), a1 + hstep, voffA);
;             PG8_WAIT_V(8); PG8_WAIT_L(0); PG8_BAR; PG8_MMA(0, 0, At, B0); PG8_MMA(0, 1, At, B1); PG8_BAR; PG8_SCHED;
;             PG8_LDA(At, 0, 1); PG8_STAGE(PG8_SB(0, 0), b2, voffB); PG8_STAGE(PG8_SB(0, 1), b2 + hstep, voffB); PG8_STAGE(PG8_SA(0, 0), a2, voffA);
;             PG8_WAIT_V(8); PG8_WAIT_L(0); PG8_BAR; PG8_MMA(1, 0, At, B0); PG8_MMA(1, 1, At, B1); PG8_BAR; PG8_SCHED;
;             PG8_LDB(B0, 1, 0); PG8_LDB(B1, 1, 1); PG8_SCHED; PG8_LDA(At, 1, 0); PG8_STAGE(PG8_SA(0, 1), a2 + hstep, voffA);
;             PG8_WAIT_V(8); PG8_WAIT_L(0); PG8_BAR; PG8_MMA(0, 0, At, B0); PG8_MMA(0, 1, At, B1); PG8_BAR; PG8_SCHED;
;             PG8_LDA(At, 1, 1); PG8_STAGE(PG8_SB(1, 0), b3, voffB); PG8_STAGE(PG8_SB(1, 1), b3 + hstep, voffB); PG8_STAGE(PG8_SA(1, 0), a3, voffA);
;             PG8_WAIT_V(8); PG8_WAIT_L(0); PG8_BAR; PG8_MMA(1, 0, At, B0); PG8_MMA(1, 1, At, B1); PG8_BAR; PG8_SCHED;
	s_add_i32 s63, s63, s74
	v_lshl_add_u64 v[162:163], v[162:163], 0, s[68:69]
	s_mov_b32 m0, s63
	ds_read_b128 v[188:191], v171 offset:49152
	ds_read_b128 v[198:201], v171 offset:50176
	ds_read_b128 v[202:205], v171 offset:51200
	ds_read_b128 v[206:209], v171 offset:52224
	ds_read_b128 v[210:213], v171 offset:53248
	ds_read_b128 v[214:217], v171 offset:54272
	ds_read_b128 v[218:221], v171 offset:55296
	ds_read_b128 v[230:233], v171 offset:56320
	global_load_lds_dwordx4 v[162:163], off
	s_add_i32 m0, s63, 0x2000
	s_add_u32 s66, s66, 0x40080
	v_lshl_add_u64 v[162:163], v[234:235], 0, s[68:69]
	s_addc_u32 s67, s67, 0
	s_add_i32 s63, s78, s74
	global_load_lds_dwordx4 v[162:163], off
	s_mov_b32 m0, s63
	s_nop 0
	global_load_lds_dwordx4 v192, s[66:67]
	s_add_i32 m0, s63, 0x2000
	s_nop 0
	global_load_lds_dwordx4 v134, s[66:67]
	v_lshl_add_u64 v[162:163], v[236:237], 0, s[68:69]
	s_mov_b32 m0, s93
	s_nop 0
	global_load_lds_dwordx4 v[162:163], off
	v_lshl_add_u64 v[162:163], v[238:239], 0, s[68:69]
	s_mov_b32 m0, s94
	s_nop 0
	global_load_lds_dwordx4 v[162:163], off
	s_waitcnt vmcnt(8)
	s_waitcnt lgkmcnt(0)
	s_barrier
	s_waitcnt lgkmcnt(0)
	v_mfma_f32_16x16x32_bf16 v[60:63], v[146:149], v[188:191], v[60:63]
	v_mfma_f32_16x16x32_bf16 v[56:59], v[154:157], v[188:191], v[56:59]
	v_mfma_f32_16x16x32_bf16 v[40:43], v[154:157], v[202:205], v[40:43]
	v_mfma_f32_16x16x32_bf16 v[44:47], v[146:149], v[202:205], v[44:47]
	v_mfma_f32_16x16x32_bf16 v[28:31], v[146:149], v[210:213], v[28:31]
	v_mfma_f32_16x16x32_bf16 v[24:27], v[154:157], v[210:213], v[24:27]
	v_mfma_f32_16x16x32_bf16 v[8:11], v[154:157], v[218:221], v[8:11]
	v_mfma_f32_16x16x32_bf16 v[12:15], v[146:149], v[218:221], v[12:15]
	v_mfma_f32_16x16x32_bf16 v[60:63], v[150:153], v[198:201], v[60:63]
	v_mfma_f32_16x16x32_bf16 v[56:59], v[158:161], v[198:201], v[56:59]
	v_mfma_f32_16x16x32_bf16 v[40:43], v[158:161], v[206:209], v[40:43]
	v_mfma_f32_16x16x32_bf16 v[44:47], v[150:153], v[206:209], v[44:47]
	v_mfma_f32_16x16x32_bf16 v[28:31], v[150:153], v[214:217], v[28:31]
	v_mfma_f32_16x16x32_bf16 v[24:27], v[158:161], v[214:217], v[24:27]
	v_mfma_f32_16x16x32_bf16 v[8:11], v[158:161], v[230:233], v[8:11]
	v_mfma_f32_16x16x32_bf16 v[12:15], v[150:153], v[230:233], v[12:15]
	v_mfma_f32_16x16x32_bf16 v[52:55], v[172:175], v[188:191], v[52:55]
	v_mfma_f32_16x16x32_bf16 v[48:51], v[180:183], v[188:191], v[48:51]
	v_mfma_f32_16x16x32_bf16 v[32:35], v[180:183], v[202:205], v[32:35]
	v_mfma_f32_16x16x32_bf16 v[36:39], v[172:175], v[202:205], v[36:39]
	v_mfma_f32_16x16x32_bf16 v[20:23], v[172:175], v[210:213], v[20:23]
	v_mfma_f32_16x16x32_bf16 v[16:19], v[180:183], v[210:213], v[16:19]
	v_mfma_f32_16x16x32_bf16 v[0:3], v[180:183], v[218:221], v[0:3]
	v_mfma_f32_16x16x32_bf16 v[4:7], v[172:175], v[218:221], v[4:7]
	v_mfma_f32_16x16x32_bf16 v[52:55], v[176:179], v[198:201], v[52:55]
	v_mfma_f32_16x16x32_bf16 v[48:51], v[184:187], v[198:201], v[48:51]
	v_mfma_f32_16x16x32_bf16 v[32:35], v[184:187], v[206:209], v[32:35]
	v_mfma_f32_16x16x32_bf16 v[36:39], v[176:179], v[206:209], v[36:39]
	v_mfma_f32_16x16x32_bf16 v[20:23], v[176:179], v[214:217], v[20:23]
	v_mfma_f32_16x16x32_bf16 v[16:19], v[184:187], v[214:217], v[16:19]
	v_mfma_f32_16x16x32_bf16 v[0:3], v[184:187], v[230:233], v[0:3]
	v_mfma_f32_16x16x32_bf16 v[4:7], v[176:179], v[230:233], v[4:7]
	s_barrier
	s_add_i32 s61, s61, 2
	s_add_u32 s64, s64, 0x100
	s_addc_u32 s65, s65, 0
	s_add_u32 s59, s59, 0x100
	s_addc_u32 s60, s60, 0
	s_cmp_gt_u32 s61, 13
.LBB0_168:
	s_add_u32 s63, s64, 0xfffc0080
	s_addc_u32 s66, s65, -1
	s_add_i32 s78, 0, 0x10000
	s_cmp_eq_u32 s61, 12
	s_cselect_b32 s71, s55, s66
	s_cselect_b32 s70, s56, s63
	v_add_u32_e32 v145, s78, v166
	s_cselect_b32 s67, s57, s60
	s_cselect_b32 s66, s58, s59
	s_add_i32 s63, 0, 0x14000
	ds_read_b128 v[146:149], v145
	ds_read_b128 v[150:153], v145 offset:1024
	ds_read_b128 v[154:157], v145 offset:2048
	ds_read_b128 v[158:161], v145 offset:3072
	v_add_u32_e32 v145, s63, v166
	ds_read_b128 v[172:175], v145
	ds_read_b128 v[176:179], v145 offset:1024
	ds_read_b128 v[180:183], v145 offset:2048
	ds_read_b128 v[184:187], v145 offset:3072
	s_add_i32 m0, s75, 0xc000
	ds_read_b128 v[188:191], v171
	ds_read_b128 v[198:201], v171 offset:1024
	ds_read_b128 v[202:205], v171 offset:2048
	ds_read_b128 v[206:209], v171 offset:3072
	ds_read_b128 v[210:213], v171 offset:4096
	ds_read_b128 v[214:217], v171 offset:5120
	ds_read_b128 v[218:221], v171 offset:6144
	ds_read_b128 v[230:233], v171 offset:7168
	global_load_lds_dwordx4 v140, s[64:65]
	s_add_i32 m0, s75, 0xe000
	s_nop 0
	global_load_lds_dwordx4 v142, s[64:65]
	s_waitcnt vmcnt(8)
	s_waitcnt lgkmcnt(0)
	s_barrier
; #define PG8_STAGE(bufoff, gbase, voff) do { _Pragma("unroll") for (int _i = 0; _i < 2; ++_i) \
;         __builtin_amdgcn_global_load_lds((const unsigned*)((const char*)(gbase) + (voff)[_i]), (LAS unsigned*)(lds + (bufoff) + ldsw + _i * 8192), 16, 0, 0); } while (0)
; #define PG8_LDA(dst, b, h) do { _Pragma("unroll") for (int m = 0; m < 4; ++m) _Pragma("unroll") for (int k = 0; k < 2; ++k) dst[m][k] = *(const LAS bf16x8*)(lds + PG8_SA(b, h) + aoff + m * 2048 + k * 1024); } while (0)
; #define PG8_MMA(ai, bj, At, Bt) do { __builtin_amdgcn_s_setprio(1); _Pragma("unroll") for (int m = 0; m < 4; ++m) _Pragma("unroll") for (int n = 0; n < 2; ++n) _Pragma("unroll") for (int k = 0; k < 2; ++k) \
;         acc[ai][bj][m][n] = __builtin_amdgcn_mfma_f32_16x16x32_bf16(Bt[n][k], At[m][k], acc[ai][bj][m][n], 0, 0, 0); __builtin_amdgcn_s_setprio(0); } while (0)
; #define PG8_WAIT_V(n) asm volatile("s_waitcnt vmcnt(" #n ")" ::: "memory")
; #define PG8_WAIT_L(n) asm volatile("s_waitcnt lgkmcnt(" #n ")" ::: "memory")
; #define PG8_BAR __builtin_amdgcn_s_barrier()
; #define PG8_SCHED __builtin_amdgcn_sched_barrier(0)
; template <class Epi, class Sched>
; __device__ __forceinline__ void gemm_phase(LAS unsigned char* lds, const Gemm g, const Sched& S, const Epi& E, const int tid) {
;     ...
;             PG8_WAIT_V(8); PG8_WAIT_L(0); PG8_BAR; PG8_MMA(0, 0, At, B0); PG8_MMA(0, 1, At, B1); PG8_BAR; PG8_SCHED;
;             PG8_LDA(At, 0, 1); PG8_STAGE(PG8_SB(0, 0), b2, voffB); PG8_STAGE(PG8_SB(0, 1), b2 + hstep, voffB); PG8_STAGE(PG8_SA(0, 0), a2, voffA);
;             PG8_WAIT_V(8); PG8_WAIT_L(0); PG8_BAR; PG8_MMA(1, 0, At, B0); PG8_MMA(1, 1, At, B1); PG8_BAR; PG8_SCHED;
	s_waitcnt lgkmcnt(0)
	v_mfma_f32_16x16x32_bf16 v[128:131], v[146:149], v[188:191], v[128:131]
	v_mfma_f32_16x16x32_bf16 v[124:127], v[154:157], v[188:191], v[124:127]
	v_mfma_f32_16x16x32_bf16 v[104:107], v[154:157], v[202:205], v[104:107]
	v_mfma_f32_16x16x32_bf16 v[108:111], v[146:149], v[202:205], v[108:111]
	v_mfma_f32_16x16x32_bf16 v[92:95], v[146:149], v[210:213], v[92:95]
	v_mfma_f32_16x16x32_bf16 v[88:91], v[154:157], v[210:213], v[88:91]
	v_mfma_f32_16x16x32_bf16 v[72:75], v[154:157], v[218:221], v[72:75]
	v_mfma_f32_16x16x32_bf16 v[76:79], v[146:149], v[218:221], v[76:79]
	v_mfma_f32_16x16x32_bf16 v[128:131], v[150:153], v[198:201], v[128:131]
	v_mfma_f32_16x16x32_bf16 v[124:127], v[158:161], v[198:201], v[124:127]
	v_mfma_f32_16x16x32_bf16 v[104:107], v[158:161], v[206:209], v[104:107]
	v_mfma_f32_16x16x32_bf16 v[108:111], v[150:153], v[206:209], v[108:111]
	v_mfma_f32_16x16x32_bf16 v[92:95], v[150:153], v[214:217], v[92:95]
	v_mfma_f32_16x16x32_bf16 v[88:91], v[158:161], v[214:217], v[88:91]
	v_mfma_f32_16x16x32_bf16 v[72:75], v[158:161], v[230:233], v[72:75]
	v_mfma_f32_16x16x32_bf16 v[76:79], v[150:153], v[230:233], v[76:79]
	v_mfma_f32_16x16x32_bf16 v[120:123], v[172:175], v[188:191], v[120:123]
	v_mfma_f32_16x16x32_bf16 v[116:119], v[180:183], v[188:191], v[116:119]
	v_mfma_f32_16x16x32_bf16 v[96:99], v[180:183], v[202:205], v[96:99]
	v_mfma_f32_16x16x32_bf16 v[100:103], v[172:175], v[202:205], v[100:103]
	v_mfma_f32_16x16x32_bf16 v[84:87], v[172:175], v[210:213], v[84:87]
	v_mfma_f32_16x16x32_bf16 v[80:83], v[180:183], v[210:213], v[80:83]
	v_mfma_f32_16x16x32_bf16 v[64:67], v[180:183], v[218:221], v[64:67]
	v_mfma_f32_16x16x32_bf16 v[68:71], v[172:175], v[218:221], v[68:71]
	v_mfma_f32_16x16x32_bf16 v[120:123], v[176:179], v[198:201], v[120:123]
	v_mfma_f32_16x16x32_bf16 v[116:119], v[184:187], v[198:201], v[116:119]
	v_mfma_f32_16x16x32_bf16 v[96:99], v[184:187], v[206:209], v[96:99]
	v_mfma_f32_16x16x32_bf16 v[100:103], v[176:179], v[206:209], v[100:103]
	v_mfma_f32_16x16x32_bf16 v[84:87], v[176:179], v[214:217], v[84:87]
	v_mfma_f32_16x16x32_bf16 v[80:83], v[184:187], v[214:217], v[80:83]
	v_mfma_f32_16x16x32_bf16 v[64:67], v[184:187], v[230:233], v[64:67]
	v_mfma_f32_16x16x32_bf16 v[68:71], v[176:179], v[230:233], v[68:71]
	s_barrier
	s_add_i32 s78, s78, s74
	v_lshl_add_u64 v[162:163], s[66:67], 0, v[192:193]
	s_mov_b32 m0, s78
	ds_read_b128 v[188:191], v171 offset:16384
	ds_read_b128 v[198:201], v171 offset:17408
	ds_read_b128 v[202:205], v171 offset:18432
	ds_read_b128 v[206:209], v171 offset:19456
	ds_read_b128 v[210:213], v171 offset:20480
	ds_read_b128 v[214:217], v171 offset:21504
	ds_read_b128 v[218:221], v171 offset:22528
	ds_read_b128 v[230:233], v171 offset:23552
	global_load_lds_dwordx4 v192, s[66:67]
	s_add_i32 m0, s78, 0x2000
	s_add_u32 s78, s66, 0x40000
	v_lshl_add_u64 v[234:235], s[66:67], 0, v[134:135]
	s_addc_u32 s79, s67, 0
	s_add_i32 s63, s63, s74
	global_load_lds_dwordx4 v134, s[66:67]
	s_mov_b32 m0, s63
	v_lshl_add_u64 v[238:239], s[70:71], 0, v[136:137]
	global_load_lds_dwordx4 v192, s[78:79]
	s_add_i32 m0, s63, 0x2000
	s_nop 0
	global_load_lds_dwordx4 v134, s[78:79]
	v_lshl_add_u64 v[236:237], s[70:71], 0, v[138:139]
	s_mov_b32 m0, s75
	s_nop 0
	global_load_lds_dwordx4 v138, s[70:71]
	s_mov_b32 m0, s81
	s_nop 0
	global_load_lds_dwordx4 v136, s[70:71]
	s_waitcnt vmcnt(8)
	s_waitcnt lgkmcnt(0)
	s_barrier
	s_waitcnt lgkmcnt(0)
	v_mfma_f32_16x16x32_bf16 v[60:63], v[146:149], v[188:191], v[60:63]
	v_mfma_f32_16x16x32_bf16 v[56:59], v[154:157], v[188:191], v[56:59]
	v_mfma_f32_16x16x32_bf16 v[40:43], v[154:157], v[202:205], v[40:43]
	v_mfma_f32_16x16x32_bf16 v[44:47], v[146:149], v[202:205], v[44:47]
	v_mfma_f32_16x16x32_bf16 v[28:31], v[146:149], v[210:213], v[28:31]
	v_mfma_f32_16x16x32_bf16 v[24:27], v[154:157], v[210:213], v[24:27]
	v_mfma_f32_16x16x32_bf16 v[8:11], v[154:157], v[218:221], v[8:11]
	v_mfma_f32_16x16x32_bf16 v[12:15], v[146:149], v[218:221], v[12:15]
	v_mfma_f32_16x16x32_bf16 v[60:63], v[150:153], v[198:201], v[60:63]
	v_mfma_f32_16x16x32_bf16 v[56:59], v[158:161], v[198:201], v[56:59]
	v_mfma_f32_16x16x32_bf16 v[40:43], v[158:161], v[206:209], v[40:43]
	v_mfma_f32_16x16x32_bf16 v[44:47], v[150:153], v[206:209], v[44:47]
	v_mfma_f32_16x16x32_bf16 v[28:31], v[150:153], v[214:217], v[28:31]
	v_mfma_f32_16x16x32_bf16 v[24:27], v[158:161], v[214:217], v[24:27]
	v_mfma_f32_16x16x32_bf16 v[8:11], v[158:161], v[230:233], v[8:11]
	v_mfma_f32_16x16x32_bf16 v[12:15], v[150:153], v[230:233], v[12:15]
	v_mfma_f32_16x16x32_bf16 v[52:55], v[172:175], v[188:191], v[52:55]
	v_mfma_f32_16x16x32_bf16 v[48:51], v[180:183], v[188:191], v[48:51]
	v_mfma_f32_16x16x32_bf16 v[32:35], v[180:183], v[202:205], v[32:35]
	v_mfma_f32_16x16x32_bf16 v[36:39], v[172:175], v[202:205], v[36:39]
	v_mfma_f32_16x16x32_bf16 v[20:23], v[172:175], v[210:213], v[20:23]
	v_mfma_f32_16x16x32_bf16 v[16:19], v[180:183], v[210:213], v[16:19]
	v_mfma_f32_16x16x32_bf16 v[0:3], v[180:183], v[218:221], v[0:3]
	v_mfma_f32_16x16x32_bf16 v[4:7], v[172:175], v[218:221], v[4:7]
	v_mfma_f32_16x16x32_bf16 v[52:55], v[176:179], v[198:201], v[52:55]
	v_mfma_f32_16x16x32_bf16 v[48:51], v[184:187], v[198:201], v[48:51]
	v_mfma_f32_16x16x32_bf16 v[32:35], v[184:187], v[206:209], v[32:35]
	v_mfma_f32_16x16x32_bf16 v[36:39], v[176:179], v[206:209], v[36:39]
	v_mfma_f32_16x16x32_bf16 v[20:23], v[176:179], v[214:217], v[20:23]
	v_mfma_f32_16x16x32_bf16 v[16:19], v[184:187], v[214:217], v[16:19]
	v_mfma_f32_16x16x32_bf16 v[0:3], v[184:187], v[230:233], v[0:3]
	v_mfma_f32_16x16x32_bf16 v[4:7], v[176:179], v[230:233], v[4:7]
	s_barrier
; #define PG8_STAGE(bufoff, gbase, voff) do { _Pragma("unroll") for (int _i = 0; _i < 2; ++_i) \
;         __builtin_amdgcn_global_load_lds((const unsigned*)((const char*)(gbase) + (voff)[_i]), (LAS unsigned*)(lds + (bufoff) + ldsw + _i * 8192), 16, 0, 0); } while (0)
; #define PG8_LDA(dst, b, h) do { _Pragma("unroll") for (int m = 0; m < 4; ++m) _Pragma("unroll") for (int k = 0; k < 2; ++k) dst[m][k] = *(const LAS bf16x8*)(lds + PG8_SA(b, h) + aoff + m * 2048 + k * 1024); } while (0)
; #define PG8_LDB(dst, b, h) do { _Pragma("unroll") for (int n = 0; n < 2; ++n) _Pragma("unroll") for (int k = 0; k < 2; ++k) dst[n][k] = *(const LAS bf16x8*)(lds + PG8_SB(b, h) + boff + n * 2048 + k * 1024); } while (0)
; #define PG8_MMA(ai, bj, At, Bt) do { __builtin_amdgcn_s_setprio(1); _Pragma("unroll") for (int m = 0; m < 4; ++m) _Pragma("unroll") for (int n = 0; n < 2; ++n) _Pragma("unroll") for (int k = 0; k < 2; ++k) \
;         acc[ai][bj][m][n] = __builtin_amdgcn_mfma_f32_16x16x32_bf16(Bt[n][k], At[m][k], acc[ai][bj][m][n], 0, 0, 0); __builtin_amdgcn_s_setprio(0); } while (0)
; #define PG8_WAIT_V(n) asm volatile("s_waitcnt vmcnt(" #n ")" ::: "memory")
; #define PG8_WAIT_L(n) asm volatile("s_waitcnt lgkmcnt(" #n ")" ::: "memory")
; #define PG8_BAR __builtin_amdgcn_s_barrier()
; #define PG8_SCHED __builtin_amdgcn_sched_barrier(0)
; template <class Epi, class Sched>
; __device__ __forceinline__ void gemm_phase(LAS unsigned char* lds, const Gemm g, const Sched& S, const Epi& E, const int tid) {
;     ...
;             PG8_LDB(B0, 1, 0); PG8_LDB(B1, 1, 1); PG8_SCHED; PG8_LDA(At, 1, 0); PG8_STAGE(PG8_SA(0, 1), a2 + hstep, voffA);
;             PG8_WAIT_V(8); PG8_WAIT_L(0); PG8_BAR; PG8_MMA(0, 0, At, B0); PG8_MMA(0, 1, At, B1); PG8_BAR; PG8_SCHED;
;             PG8_LDA(At, 1, 1); PG8_STAGE(PG8_SB(1, 0), b3, voffB); PG8_STAGE(PG8_SB(1, 1), b3 + hstep, voffB); PG8_STAGE(PG8_SA(1, 0), a3, voffA);
;             PG8_WAIT_V(8); PG8_WAIT_L(0); PG8_BAR; PG8_MMA(1, 0, At, B0); PG8_MMA(1, 1, At, B1); PG8_BAR; PG8_SCHED;
;         }
	s_add_i32 s63, 0, 0x18000
	v_add_u32_e32 v145, s63, v166
	s_add_i32 s78, 0, 0x1c000
	ds_read_b128 v[146:149], v145
	ds_read_b128 v[150:153], v145 offset:1024
	ds_read_b128 v[154:157], v145 offset:2048
	ds_read_b128 v[158:161], v145 offset:3072
	v_add_u32_e32 v145, s78, v166
	ds_read_b128 v[172:175], v145
	ds_read_b128 v[176:179], v145 offset:1024
	ds_read_b128 v[180:183], v145 offset:2048
	ds_read_b128 v[184:187], v145 offset:3072
	s_add_u32 s70, s70, 0x40000
	s_addc_u32 s71, s71, 0
	s_mov_b32 m0, s82
	ds_read_b128 v[188:191], v171 offset:32768
	ds_read_b128 v[198:201], v171 offset:33792
	ds_read_b128 v[202:205], v171 offset:34816
	ds_read_b128 v[206:209], v171 offset:35840
	ds_read_b128 v[210:213], v171 offset:36864
	ds_read_b128 v[214:217], v171 offset:37888
	ds_read_b128 v[218:221], v171 offset:38912
	ds_read_b128 v[230:233], v171 offset:39936
	global_load_lds_dwordx4 v138, s[70:71]
	v_lshl_add_u64 v[240:241], s[70:71], 0, v[136:137]
	s_mov_b32 m0, s83
	s_nop 0
	global_load_lds_dwordx4 v136, s[70:71]
	s_waitcnt vmcnt(8)
	s_waitcnt lgkmcnt(0)
	s_barrier
	s_waitcnt lgkmcnt(0)
	v_mfma_f32_16x16x32_bf16 v[128:131], v[146:149], v[188:191], v[128:131]
	v_mfma_f32_16x16x32_bf16 v[124:127], v[154:157], v[188:191], v[124:127]
	v_mfma_f32_16x16x32_bf16 v[104:107], v[154:157], v[202:205], v[104:107]
	v_mfma_f32_16x16x32_bf16 v[108:111], v[146:149], v[202:205], v[108:111]
	v_mfma_f32_16x16x32_bf16 v[92:95], v[146:149], v[210:213], v[92:95]
	v_mfma_f32_16x16x32_bf16 v[88:91], v[154:157], v[210:213], v[88:91]
	v_mfma_f32_16x16x32_bf16 v[72:75], v[154:157], v[218:221], v[72:75]
	v_mfma_f32_16x16x32_bf16 v[76:79], v[146:149], v[218:221], v[76:79]
	v_mfma_f32_16x16x32_bf16 v[128:131], v[150:153], v[198:201], v[128:131]
	v_mfma_f32_16x16x32_bf16 v[124:127], v[158:161], v[198:201], v[124:127]
	v_mfma_f32_16x16x32_bf16 v[104:107], v[158:161], v[206:209], v[104:107]
	v_mfma_f32_16x16x32_bf16 v[108:111], v[150:153], v[206:209], v[108:111]
	v_mfma_f32_16x16x32_bf16 v[92:95], v[150:153], v[214:217], v[92:95]
	v_mfma_f32_16x16x32_bf16 v[88:91], v[158:161], v[214:217], v[88:91]
	v_mfma_f32_16x16x32_bf16 v[72:75], v[158:161], v[230:233], v[72:75]
	v_mfma_f32_16x16x32_bf16 v[76:79], v[150:153], v[230:233], v[76:79]
	v_mfma_f32_16x16x32_bf16 v[120:123], v[172:175], v[188:191], v[120:123]
	v_mfma_f32_16x16x32_bf16 v[116:119], v[180:183], v[188:191], v[116:119]
	v_mfma_f32_16x16x32_bf16 v[96:99], v[180:183], v[202:205], v[96:99]
	v_mfma_f32_16x16x32_bf16 v[100:103], v[172:175], v[202:205], v[100:103]
	v_mfma_f32_16x16x32_bf16 v[84:87], v[172:175], v[210:213], v[84:87]
	v_mfma_f32_16x16x32_bf16 v[80:83], v[180:183], v[210:213], v[80:83]
	v_mfma_f32_16x16x32_bf16 v[64:67], v[180:183], v[218:221], v[64:67]
	v_mfma_f32_16x16x32_bf16 v[68:71], v[172:175], v[218:221], v[68:71]
	v_mfma_f32_16x16x32_bf16 v[120:123], v[176:179], v[198:201], v[120:123]
	v_mfma_f32_16x16x32_bf16 v[116:119], v[184:187], v[198:201], v[116:119]
	v_mfma_f32_16x16x32_bf16 v[96:99], v[184:187], v[206:209], v[96:99]
	v_mfma_f32_16x16x32_bf16 v[100:103], v[176:179], v[206:209], v[100:103]
	v_mfma_f32_16x16x32_bf16 v[84:87], v[176:179], v[214:217], v[84:87]
	v_mfma_f32_16x16x32_bf16 v[80:83], v[184:187], v[214:217], v[80:83]
	v_mfma_f32_16x16x32_bf16 v[64:67], v[184:187], v[230:233], v[64:67]
	v_mfma_f32_16x16x32_bf16 v[68:71], v[176:179], v[230:233], v[68:71]
	s_barrier
	s_add_i32 s63, s63, s74
	v_lshl_add_u64 v[162:163], v[162:163], 0, s[68:69]
	s_mov_b32 m0, s63
	ds_read_b128 v[188:191], v171 offset:49152
	ds_read_b128 v[198:201], v171 offset:50176
	ds_read_b128 v[202:205], v171 offset:51200
	ds_read_b128 v[206:209], v171 offset:52224
	ds_read_b128 v[210:213], v171 offset:53248
	ds_read_b128 v[214:217], v171 offset:54272
	ds_read_b128 v[218:221], v171 offset:55296
	ds_read_b128 v[230:233], v171 offset:56320
	global_load_lds_dwordx4 v[162:163], off
	s_add_i32 m0, s63, 0x2000
	s_add_u32 s66, s66, 0x40080
	v_lshl_add_u64 v[162:163], v[234:235], 0, s[68:69]
	s_addc_u32 s67, s67, 0
	s_add_i32 s63, s78, s74
	global_load_lds_dwordx4 v[162:163], off
	s_mov_b32 m0, s63
	s_nop 0
	global_load_lds_dwordx4 v192, s[66:67]
	s_add_i32 m0, s63, 0x2000
	s_nop 0
	global_load_lds_dwordx4 v134, s[66:67]
	v_lshl_add_u64 v[162:163], v[236:237], 0, s[68:69]
	s_mov_b32 m0, s93
	s_nop 0
	global_load_lds_dwordx4 v[162:163], off
	v_lshl_add_u64 v[162:163], v[238:239], 0, s[68:69]
	s_mov_b32 m0, s94
	s_nop 0
	global_load_lds_dwordx4 v[162:163], off
	s_waitcnt vmcnt(8)
	s_waitcnt lgkmcnt(0)
	s_barrier
	s_waitcnt lgkmcnt(0)
	v_mfma_f32_16x16x32_bf16 v[60:63], v[146:149], v[188:191], v[60:63]
	v_mfma_f32_16x16x32_bf16 v[56:59], v[154:157], v[188:191], v[56:59]
	v_mfma_f32_16x16x32_bf16 v[40:43], v[154:157], v[202:205], v[40:43]
	v_mfma_f32_16x16x32_bf16 v[44:47], v[146:149], v[202:205], v[44:47]
	v_mfma_f32_16x16x32_bf16 v[28:31], v[146:149], v[210:213], v[28:31]
	v_mfma_f32_16x16x32_bf16 v[24:27], v[154:157], v[210:213], v[24:27]
	v_mfma_f32_16x16x32_bf16 v[8:11], v[154:157], v[218:221], v[8:11]
	v_mfma_f32_16x16x32_bf16 v[12:15], v[146:149], v[218:221], v[12:15]
	v_mfma_f32_16x16x32_bf16 v[60:63], v[150:153], v[198:201], v[60:63]
	v_mfma_f32_16x16x32_bf16 v[56:59], v[158:161], v[198:201], v[56:59]
	v_mfma_f32_16x16x32_bf16 v[40:43], v[158:161], v[206:209], v[40:43]
	v_mfma_f32_16x16x32_bf16 v[44:47], v[150:153], v[206:209], v[44:47]
	v_mfma_f32_16x16x32_bf16 v[28:31], v[150:153], v[214:217], v[28:31]
	v_mfma_f32_16x16x32_bf16 v[24:27], v[158:161], v[214:217], v[24:27]
	v_mfma_f32_16x16x32_bf16 v[8:11], v[158:161], v[230:233], v[8:11]
	v_mfma_f32_16x16x32_bf16 v[12:15], v[150:153], v[230:233], v[12:15]
	v_mfma_f32_16x16x32_bf16 v[52:55], v[172:175], v[188:191], v[52:55]
	v_mfma_f32_16x16x32_bf16 v[48:51], v[180:183], v[188:191], v[48:51]
	v_mfma_f32_16x16x32_bf16 v[32:35], v[180:183], v[202:205], v[32:35]
	v_mfma_f32_16x16x32_bf16 v[36:39], v[172:175], v[202:205], v[36:39]
	v_mfma_f32_16x16x32_bf16 v[20:23], v[172:175], v[210:213], v[20:23]
	v_mfma_f32_16x16x32_bf16 v[16:19], v[180:183], v[210:213], v[16:19]
	v_mfma_f32_16x16x32_bf16 v[0:3], v[180:183], v[218:221], v[0:3]
	v_mfma_f32_16x16x32_bf16 v[4:7], v[172:175], v[218:221], v[4:7]
	v_mfma_f32_16x16x32_bf16 v[52:55], v[176:179], v[198:201], v[52:55]
	v_mfma_f32_16x16x32_bf16 v[48:51], v[184:187], v[198:201], v[48:51]
	v_mfma_f32_16x16x32_bf16 v[32:35], v[184:187], v[206:209], v[32:35]
	v_mfma_f32_16x16x32_bf16 v[36:39], v[176:179], v[206:209], v[36:39]
	v_mfma_f32_16x16x32_bf16 v[20:23], v[176:179], v[214:217], v[20:23]
	v_mfma_f32_16x16x32_bf16 v[16:19], v[184:187], v[214:217], v[16:19]
	v_mfma_f32_16x16x32_bf16 v[0:3], v[184:187], v[230:233], v[0:3]
	v_mfma_f32_16x16x32_bf16 v[4:7], v[176:179], v[230:233], v[4:7]
	s_barrier
	s_add_i32 s61, s61, 2
	s_add_u32 s64, s64, 0x100
	s_addc_u32 s65, s65, 0
	s_add_u32 s59, s59, 0x100
	s_addc_u32 s60, s60, 0
	s_cmp_gt_u32 s61, 13
	s_cbranch_scc0 .LBB0_168
	s_and_b64 vcc, exec, s[50:51]
	s_cbranch_vccz .LBB0_171
	s_barrier

;     __device__ __forceinline__ Pre prefetch(const Unit& u, int tid) const { return prenorm_load(stats, u.pn * BM, sW + (size_t)(u.pn >> 4) * SW_ROWS + u.pm * BM, tid); }
;     __device__ __forceinline__ Pre prefetch(const Unit& u, int tid) const { return prenorm_load(stats, u.pm * BM, sW + (size_t)(u.pm >> 4) * SW_ROWS + u.pn * BM, tid); }
;     __device__ __forceinline__ Pre prefetch(const Unit& u, int tid) const { return prenorm_load(stats, u.pm * BM, sW + (size_t)(u.pm >> 4) * SW_ROWS + u.pn * BM, tid); }
; #define PG8_STAGE(bufoff, gbase, voff) do { _Pragma("unroll") for (int _i = 0; _i < 2; ++_i) \
;         __builtin_amdgcn_global_load_lds((const unsigned*)((const char*)(gbase) + (voff)[_i]), (LAS unsigned*)(lds + (bufoff) + ldsw + _i * 8192), 16, 0, 0); } while (0)
; #define PG8_LDA(dst, b, h) do { _Pragma("unroll") for (int m = 0; m < 4; ++m) _Pragma("unroll") for (int k = 0; k < 2; ++k) dst[m][k] = *(const LAS bf16x8*)(lds + PG8_SA(b, h) + aoff + m * 2048 + k * 1024); } while (0)
; #define PG8_WAIT_V(n) asm volatile("s_waitcnt vmcnt(" #n ")" ::: "memory")
; template <class Epi, class Sched>
; __device__ __forceinline__ void gemm_phase(LAS unsigned char* lds, const Gemm g, const Sched& S, const Epi& E, const int tid) {
;     ...
;         const bool has_next = S.next(ui + 1, nxt);
;         const char* nA = has_next ? (const char*)g.A + (size_t)nxt.pm * tstep : cA; const char* nB = has_next ? (const char*)g.Bt + (size_t)nxt.pn * tstep : cB;
;         const typename Epi::Pre pre = E.prefetch(cur, tid);
;         for (int t = 0; t < nt; t += 2) {
;             const bool last = (t == nt - 2);
;             const char* a1 = cA + (size_t)(t + 1) * kstep;
;             const char* a2 = last ? nA : cA + (size_t)(t + 2) * kstep; const char* b2 = last ? nB : cB + (size_t)(t + 2) * kstep;
;             const char* a3 = a2 + kstep; const char* b3 = b2 + kstep;
;             PG8_LDB(B0, 0, 0); PG8_LDB(B1, 0, 1); PG8_SCHED; PG8_LDA(At, 0, 0); PG8_STAGE(PG8_SA(1, 1), a1 + hstep, voffA);
;             PG8_WAIT_V(8); PG8_WAIT_L(0); PG8_BAR; PG8_MMA(0, 0, At, B0); PG8_MMA(0, 1, At, B1); PG8_BAR; PG8_SCHED;
;             PG8_LDA(At, 0, 1); PG8_STAGE(PG8_SB(0, 0), b2, voffB); PG8_STAGE(PG8_SB(0, 1), b2 + hstep, voffB); PG8_STAGE(PG8_SA(0, 0), a2, voffA);
;             PG8_WAIT_V(8); PG8_WAIT_L(0); PG8_BAR; PG8_MMA(1, 0, At, B0); PG8_MMA(1, 1, At, B1); PG8_BAR; PG8_SCHED;
.LBB0_265:
	s_or_b64 exec, exec, s[38:39]
	s_ashr_i32 s23, s22, 31
	s_lshl_b64 s[38:39], s[22:23], 19
	s_add_u32 s38, s46, s38
	s_addc_u32 s39, s47, s39
	s_and_b64 s[56:57], s[4:5], exec
	s_cselect_b32 s23, s39, s7
	s_cselect_b32 s56, s38, s6
	s_ashr_i32 s55, s54, 31
	s_lshl_b64 s[58:59], s[54:55], 19
	s_add_u32 s62, s35, s58
	s_addc_u32 s63, s84, s59
	s_and_b64 s[58:59], s[4:5], exec
	s_cselect_b32 s55, s63, s65
	s_cselect_b32 s57, s62, s64
	s_add_u32 s6, s6, 0x40080
	s_addc_u32 s7, s7, 0
	s_add_u32 s58, s64, 0x100
	s_addc_u32 s59, s65, 0
	s_mov_b32 s60, -2
	s_add_u32 s61, s6, 0xfffc0080
	s_addc_u32 s64, s7, -1
	s_add_i32 s70, 0, 0x10000
	s_cmp_eq_u32 s60, 12
	s_cselect_b32 s67, s23, s64
	s_cselect_b32 s66, s56, s61
	v_add_u32_e32 v81, s70, v216
	s_cselect_b32 s65, s55, s59
	s_cselect_b32 s64, s57, s58
	s_add_i32 s61, 0, 0x14000
	ds_read_b128 v[88:91], v81
	ds_read_b128 v[92:95], v81 offset:1024
	ds_read_b128 v[144:147], v81 offset:2048
	ds_read_b128 v[148:151], v81 offset:3072
	v_add_u32_e32 v81, s61, v216
	ds_read_b128 v[152:155], v81
	ds_read_b128 v[156:159], v81 offset:1024
	ds_read_b128 v[178:181], v81 offset:2048
	ds_read_b128 v[182:185], v81 offset:3072
	s_add_i32 m0, s73, 0xc000
	ds_read_b128 v[186:189], v230
	ds_read_b128 v[198:201], v230 offset:1024
	ds_read_b128 v[202:205], v230 offset:2048
	ds_read_b128 v[206:209], v230 offset:3072
	ds_read_b128 v[234:237], v230 offset:4096
	ds_read_b128 v[238:241], v230 offset:5120
	ds_read_b128 v[242:245], v230 offset:6144
	ds_read_b128 v[246:249], v230 offset:7168
	global_load_lds_dwordx4 v174, s[6:7]
	v_lshl_add_u64 v[82:83], s[6:7], 0, v[176:177]
	s_add_i32 m0, s73, 0xe000
	s_nop 0
	global_load_lds_dwordx4 v176, s[6:7]
	s_waitcnt vmcnt(8)
	s_waitcnt lgkmcnt(0)
	s_barrier
	s_waitcnt lgkmcnt(0)
	v_mfma_f32_16x16x32_bf16 v[140:143], v[88:91], v[186:189], 0
	v_mfma_f32_16x16x32_bf16 v[136:139], v[144:147], v[186:189], 0
	v_mfma_f32_16x16x32_bf16 v[120:123], v[144:147], v[202:205], 0
	v_mfma_f32_16x16x32_bf16 v[124:127], v[88:91], v[202:205], 0
	v_mfma_f32_16x16x32_bf16 v[108:111], v[88:91], v[234:237], 0
	v_mfma_f32_16x16x32_bf16 v[104:107], v[144:147], v[234:237], 0
	v_mfma_f32_16x16x32_bf16 v[76:79], v[144:147], v[242:245], 0
	v_mfma_f32_16x16x32_bf16 v[82:85], v[88:91], v[242:245], 0
	v_mfma_f32_16x16x32_bf16 v[140:143], v[92:95], v[198:201], v[140:143]
	v_mfma_f32_16x16x32_bf16 v[136:139], v[148:151], v[198:201], v[136:139]
	v_mfma_f32_16x16x32_bf16 v[120:123], v[148:151], v[206:209], v[120:123]
	v_mfma_f32_16x16x32_bf16 v[124:127], v[92:95], v[206:209], v[124:127]
	v_mfma_f32_16x16x32_bf16 v[108:111], v[92:95], v[238:241], v[108:111]
	v_mfma_f32_16x16x32_bf16 v[104:107], v[148:151], v[238:241], v[104:107]
	v_mfma_f32_16x16x32_bf16 v[76:79], v[148:151], v[246:249], v[76:79]
	v_mfma_f32_16x16x32_bf16 v[82:85], v[92:95], v[246:249], v[82:85]
	v_mfma_f32_16x16x32_bf16 v[132:135], v[152:155], v[186:189], 0
	v_mfma_f32_16x16x32_bf16 v[128:131], v[178:181], v[186:189], 0
	v_mfma_f32_16x16x32_bf16 v[112:115], v[178:181], v[202:205], 0
	v_mfma_f32_16x16x32_bf16 v[116:119], v[152:155], v[202:205], 0
	v_mfma_f32_16x16x32_bf16 v[100:103], v[152:155], v[234:237], 0
	v_mfma_f32_16x16x32_bf16 v[96:99], v[178:181], v[234:237], 0
	v_mfma_f32_16x16x32_bf16 v[64:67], v[178:181], v[242:245], 0
	v_mfma_f32_16x16x32_bf16 v[68:71], v[152:155], v[242:245], 0
	v_mfma_f32_16x16x32_bf16 v[132:135], v[156:159], v[198:201], v[132:135]
	v_mfma_f32_16x16x32_bf16 v[128:131], v[182:185], v[198:201], v[128:131]
	v_mfma_f32_16x16x32_bf16 v[112:115], v[182:185], v[206:209], v[112:115]
	v_mfma_f32_16x16x32_bf16 v[116:119], v[156:159], v[206:209], v[116:119]
	v_mfma_f32_16x16x32_bf16 v[100:103], v[156:159], v[238:241], v[100:103]
	v_mfma_f32_16x16x32_bf16 v[96:99], v[182:185], v[238:241], v[96:99]
	v_mfma_f32_16x16x32_bf16 v[64:67], v[182:185], v[246:249], v[64:67]
	v_mfma_f32_16x16x32_bf16 v[68:71], v[156:159], v[246:249], v[68:71]
	s_barrier
	s_add_i32 s70, s70, s12
	v_lshl_add_u64 v[190:191], s[64:65], 0, v[164:165]
	s_mov_b32 m0, s70
	ds_read_b128 v[186:189], v230 offset:16384
	ds_read_b128 v[198:201], v230 offset:17408
	ds_read_b128 v[202:205], v230 offset:18432
	ds_read_b128 v[206:209], v230 offset:19456
	ds_read_b128 v[234:237], v230 offset:20480
	ds_read_b128 v[238:241], v230 offset:21504
	ds_read_b128 v[242:245], v230 offset:22528
	ds_read_b128 v[246:249], v230 offset:23552
	global_load_lds_dwordx4 v164, s[64:65]
	s_add_i32 m0, s70, 0x2000
	s_add_u32 s70, s64, 0x40000
	v_lshl_add_u64 v[250:251], s[64:65], 0, v[168:169]
	s_addc_u32 s71, s65, 0
	s_add_i32 s61, s61, s12
	global_load_lds_dwordx4 v168, s[64:65]
	s_mov_b32 m0, s61
	v_lshl_add_u64 v[224:225], s[66:67], 0, v[162:163]
	global_load_lds_dwordx4 v164, s[70:71]
	s_add_i32 m0, s61, 0x2000
	v_lshl_add_u64 v[226:227], s[66:67], 0, v[166:167]
	global_load_lds_dwordx4 v168, s[70:71]
	s_mov_b32 m0, s73
	s_nop 0
	global_load_lds_dwordx4 v162, s[66:67]
	s_mov_b32 m0, s74
	s_nop 0
	global_load_lds_dwordx4 v166, s[66:67]
	s_waitcnt vmcnt(8)
	s_waitcnt lgkmcnt(0)
	s_barrier
; #define PG8_STAGE(bufoff, gbase, voff) do { _Pragma("unroll") for (int _i = 0; _i < 2; ++_i) \
;         __builtin_amdgcn_global_load_lds((const unsigned*)((const char*)(gbase) + (voff)[_i]), (LAS unsigned*)(lds + (bufoff) + ldsw + _i * 8192), 16, 0, 0); } while (0)
; #define PG8_LDA(dst, b, h) do { _Pragma("unroll") for (int m = 0; m < 4; ++m) _Pragma("unroll") for (int k = 0; k < 2; ++k) dst[m][k] = *(const LAS bf16x8*)(lds + PG8_SA(b, h) + aoff + m * 2048 + k * 1024); } while (0)
; #define PG8_LDB(dst, b, h) do { _Pragma("unroll") for (int n = 0; n < 2; ++n) _Pragma("unroll") for (int k = 0; k < 2; ++k) dst[n][k] = *(const LAS bf16x8*)(lds + PG8_SB(b, h) + boff + n * 2048 + k * 1024); } while (0)
; #define PG8_MMA(ai, bj, At, Bt) do { __builtin_amdgcn_s_setprio(1); _Pragma("unroll") for (int m = 0; m < 4; ++m) _Pragma("unroll") for (int n = 0; n < 2; ++n) _Pragma("unroll") for (int k = 0; k < 2; ++k) \
;         acc[ai][bj][m][n] = __builtin_amdgcn_mfma_f32_16x16x32_bf16(Bt[n][k], At[m][k], acc[ai][bj][m][n], 0, 0, 0); __builtin_amdgcn_s_setprio(0); } while (0)
; #define PG8_WAIT_V(n) asm volatile("s_waitcnt vmcnt(" #n ")" ::: "memory")
; #define PG8_WAIT_L(n) asm volatile("s_waitcnt lgkmcnt(" #n ")" ::: "memory")
; #define PG8_BAR __builtin_amdgcn_s_barrier()
; #define PG8_SCHED __builtin_amdgcn_sched_barrier(0)
; template <class Epi, class Sched>
; __device__ __forceinline__ void gemm_phase(LAS unsigned char* lds, const Gemm g, const Sched& S, const Epi& E, const int tid) {
;     ...
;             PG8_WAIT_V(8); PG8_WAIT_L(0); PG8_BAR; PG8_MMA(0, 0, At, B0); PG8_MMA(0, 1, At, B1); PG8_BAR; PG8_SCHED;
;             PG8_LDA(At, 0, 1); PG8_STAGE(PG8_SB(0, 0), b2, voffB); PG8_STAGE(PG8_SB(0, 1), b2 + hstep, voffB); PG8_STAGE(PG8_SA(0, 0), a2, voffA);
;             PG8_WAIT_V(8); PG8_WAIT_L(0); PG8_BAR; PG8_MMA(1, 0, At, B0); PG8_MMA(1, 1, At, B1); PG8_BAR; PG8_SCHED;
;             PG8_LDB(B0, 1, 0); PG8_LDB(B1, 1, 1); PG8_SCHED; PG8_LDA(At, 1, 0); PG8_STAGE(PG8_SA(0, 1), a2 + hstep, voffA);
;             PG8_WAIT_V(8); PG8_WAIT_L(0); PG8_BAR; PG8_MMA(0, 0, At, B0); PG8_MMA(0, 1, At, B1); PG8_BAR; PG8_SCHED;
	s_waitcnt lgkmcnt(0)
	v_mfma_f32_16x16x32_bf16 v[60:63], v[88:91], v[186:189], 0
	v_mfma_f32_16x16x32_bf16 v[56:59], v[144:147], v[186:189], 0
	v_mfma_f32_16x16x32_bf16 v[40:43], v[144:147], v[202:205], 0
	v_mfma_f32_16x16x32_bf16 v[44:47], v[88:91], v[202:205], 0
	v_mfma_f32_16x16x32_bf16 v[28:31], v[88:91], v[234:237], 0
	v_mfma_f32_16x16x32_bf16 v[24:27], v[144:147], v[234:237], 0
	v_mfma_f32_16x16x32_bf16 v[8:11], v[144:147], v[242:245], 0
	v_mfma_f32_16x16x32_bf16 v[12:15], v[88:91], v[242:245], 0
	v_mfma_f32_16x16x32_bf16 v[60:63], v[92:95], v[198:201], v[60:63]
	v_mfma_f32_16x16x32_bf16 v[56:59], v[148:151], v[198:201], v[56:59]
	v_mfma_f32_16x16x32_bf16 v[40:43], v[148:151], v[206:209], v[40:43]
	v_mfma_f32_16x16x32_bf16 v[44:47], v[92:95], v[206:209], v[44:47]
	v_mfma_f32_16x16x32_bf16 v[28:31], v[92:95], v[238:241], v[28:31]
	v_mfma_f32_16x16x32_bf16 v[24:27], v[148:151], v[238:241], v[24:27]
	v_mfma_f32_16x16x32_bf16 v[8:11], v[148:151], v[246:249], v[8:11]
	v_mfma_f32_16x16x32_bf16 v[12:15], v[92:95], v[246:249], v[12:15]
	v_mfma_f32_16x16x32_bf16 v[52:55], v[152:155], v[186:189], 0
	v_mfma_f32_16x16x32_bf16 v[48:51], v[178:181], v[186:189], 0
	v_mfma_f32_16x16x32_bf16 v[32:35], v[178:181], v[202:205], 0
	v_mfma_f32_16x16x32_bf16 v[36:39], v[152:155], v[202:205], 0
	v_mfma_f32_16x16x32_bf16 v[20:23], v[152:155], v[234:237], 0
	v_mfma_f32_16x16x32_bf16 v[16:19], v[178:181], v[234:237], 0
	v_mfma_f32_16x16x32_bf16 v[0:3], v[178:181], v[242:245], 0
	v_mfma_f32_16x16x32_bf16 v[4:7], v[152:155], v[242:245], 0
	v_mfma_f32_16x16x32_bf16 v[52:55], v[156:159], v[198:201], v[52:55]
	v_mfma_f32_16x16x32_bf16 v[48:51], v[182:185], v[198:201], v[48:51]
	v_mfma_f32_16x16x32_bf16 v[32:35], v[182:185], v[206:209], v[32:35]
	v_mfma_f32_16x16x32_bf16 v[36:39], v[156:159], v[206:209], v[36:39]
	v_mfma_f32_16x16x32_bf16 v[20:23], v[156:159], v[238:241], v[20:23]
	v_mfma_f32_16x16x32_bf16 v[16:19], v[182:185], v[238:241], v[16:19]
	v_mfma_f32_16x16x32_bf16 v[0:3], v[182:185], v[246:249], v[0:3]
	v_mfma_f32_16x16x32_bf16 v[4:7], v[156:159], v[246:249], v[4:7]
	s_barrier
	s_add_i32 s61, 0, 0x18000
	v_add_u32_e32 v81, s61, v216
	s_add_i32 s70, 0, 0x1c000
	ds_read_b128 v[88:91], v81
	ds_read_b128 v[92:95], v81 offset:1024
	ds_read_b128 v[144:147], v81 offset:2048
	ds_read_b128 v[148:151], v81 offset:3072
	v_add_u32_e32 v81, s70, v216
	ds_read_b128 v[152:155], v81
	ds_read_b128 v[156:159], v81 offset:1024
	ds_read_b128 v[178:181], v81 offset:2048
	ds_read_b128 v[182:185], v81 offset:3072
	s_add_u32 s66, s66, 0x40000
	s_addc_u32 s67, s67, 0
	s_mov_b32 m0, s75
	ds_read_b128 v[186:189], v230 offset:32768
	ds_read_b128 v[198:201], v230 offset:33792
	ds_read_b128 v[202:205], v230 offset:34816
	ds_read_b128 v[206:209], v230 offset:35840
	ds_read_b128 v[234:237], v230 offset:36864
	ds_read_b128 v[238:241], v230 offset:37888
	ds_read_b128 v[242:245], v230 offset:38912
	ds_read_b128 v[246:249], v230 offset:39936
	global_load_lds_dwordx4 v162, s[66:67]
	v_lshl_add_u64 v[86:87], s[66:67], 0, v[166:167]
	s_mov_b32 m0, s81
	s_nop 0
	global_load_lds_dwordx4 v166, s[66:67]
	s_waitcnt vmcnt(8)
	s_waitcnt lgkmcnt(0)
	s_barrier
	s_waitcnt lgkmcnt(0)
	v_mfma_f32_16x16x32_bf16 v[140:143], v[88:91], v[186:189], v[140:143]
	v_mfma_f32_16x16x32_bf16 v[136:139], v[144:147], v[186:189], v[136:139]
	v_mfma_f32_16x16x32_bf16 v[120:123], v[144:147], v[202:205], v[120:123]
	v_mfma_f32_16x16x32_bf16 v[124:127], v[88:91], v[202:205], v[124:127]
	v_mfma_f32_16x16x32_bf16 v[108:111], v[88:91], v[234:237], v[108:111]
	v_mfma_f32_16x16x32_bf16 v[104:107], v[144:147], v[234:237], v[104:107]
	v_mfma_f32_16x16x32_bf16 v[76:79], v[144:147], v[242:245], v[76:79]
	v_mfma_f32_16x16x32_bf16 v[82:85], v[88:91], v[242:245], v[82:85]
	v_mfma_f32_16x16x32_bf16 v[140:143], v[92:95], v[198:201], v[140:143]
	v_mfma_f32_16x16x32_bf16 v[136:139], v[148:151], v[198:201], v[136:139]
	v_mfma_f32_16x16x32_bf16 v[120:123], v[148:151], v[206:209], v[120:123]
	v_mfma_f32_16x16x32_bf16 v[124:127], v[92:95], v[206:209], v[124:127]
	v_mfma_f32_16x16x32_bf16 v[108:111], v[92:95], v[238:241], v[108:111]
	v_mfma_f32_16x16x32_bf16 v[104:107], v[148:151], v[238:241], v[104:107]
	v_mfma_f32_16x16x32_bf16 v[76:79], v[148:151], v[246:249], v[76:79]
	v_mfma_f32_16x16x32_bf16 v[84:87], v[92:95], v[246:249], v[82:85]
	v_mfma_f32_16x16x32_bf16 v[132:135], v[152:155], v[186:189], v[132:135]
	v_mfma_f32_16x16x32_bf16 v[128:131], v[178:181], v[186:189], v[128:131]
	v_mfma_f32_16x16x32_bf16 v[112:115], v[178:181], v[202:205], v[112:115]
	v_mfma_f32_16x16x32_bf16 v[116:119], v[152:155], v[202:205], v[116:119]
	v_mfma_f32_16x16x32_bf16 v[100:103], v[152:155], v[234:237], v[100:103]
	v_mfma_f32_16x16x32_bf16 v[96:99], v[178:181], v[234:237], v[96:99]
	v_mfma_f32_16x16x32_bf16 v[64:67], v[178:181], v[242:245], v[64:67]
	v_mfma_f32_16x16x32_bf16 v[68:71], v[152:155], v[242:245], v[68:71]
	v_mfma_f32_16x16x32_bf16 v[132:135], v[156:159], v[198:201], v[132:135]
	v_mfma_f32_16x16x32_bf16 v[128:131], v[182:185], v[198:201], v[128:131]
	v_mfma_f32_16x16x32_bf16 v[112:115], v[182:185], v[206:209], v[112:115]
	v_mfma_f32_16x16x32_bf16 v[116:119], v[156:159], v[206:209], v[116:119]
	v_mfma_f32_16x16x32_bf16 v[100:103], v[156:159], v[238:241], v[100:103]
	v_mfma_f32_16x16x32_bf16 v[96:99], v[182:185], v[238:241], v[96:99]
	v_mfma_f32_16x16x32_bf16 v[64:67], v[182:185], v[246:249], v[64:67]
	v_mfma_f32_16x16x32_bf16 v[68:71], v[156:159], v[246:249], v[68:71]
	s_barrier
; #define PG8_STAGE(bufoff, gbase, voff) do { _Pragma("unroll") for (int _i = 0; _i < 2; ++_i) \
;         __builtin_amdgcn_global_load_lds((const unsigned*)((const char*)(gbase) + (voff)[_i]), (LAS unsigned*)(lds + (bufoff) + ldsw + _i * 8192), 16, 0, 0); } while (0)
; #define PG8_LDA(dst, b, h) do { _Pragma("unroll") for (int m = 0; m < 4; ++m) _Pragma("unroll") for (int k = 0; k < 2; ++k) dst[m][k] = *(const LAS bf16x8*)(lds + PG8_SA(b, h) + aoff + m * 2048 + k * 1024); } while (0)
; #define PG8_LDB(dst, b, h) do { _Pragma("unroll") for (int n = 0; n < 2; ++n) _Pragma("unroll") for (int k = 0; k < 2; ++k) dst[n][k] = *(const LAS bf16x8*)(lds + PG8_SB(b, h) + boff + n * 2048 + k * 1024); } while (0)
; #define PG8_WAIT_V(n) asm volatile("s_waitcnt vmcnt(" #n ")" ::: "memory")
; #define PG8_BAR __builtin_amdgcn_s_barrier()
; template <class Epi, class Sched>
; __device__ __forceinline__ void gemm_phase(LAS unsigned char* lds, const Gemm g, const Sched& S, const Epi& E, const int tid) {
;     ...
;         for (int t = 0; t < nt; t += 2) {
;             const bool last = (t == nt - 2);
;             const char* a1 = cA + (size_t)(t + 1) * kstep;
;             const char* a2 = last ? nA : cA + (size_t)(t + 2) * kstep; const char* b2 = last ? nB : cB + (size_t)(t + 2) * kstep;
;             const char* a3 = a2 + kstep; const char* b3 = b2 + kstep;
;             PG8_LDB(B0, 0, 0); PG8_LDB(B1, 0, 1); PG8_SCHED; PG8_LDA(At, 0, 0); PG8_STAGE(PG8_SA(1, 1), a1 + hstep, voffA);
;             PG8_WAIT_V(8); PG8_WAIT_L(0); PG8_BAR; PG8_MMA(0, 0, At, B0); PG8_MMA(0, 1, At, B1); PG8_BAR; PG8_SCHED;
;             PG8_LDA(At, 0, 1); PG8_STAGE(PG8_SB(0, 0), b2, voffB); PG8_STAGE(PG8_SB(0, 1), b2 + hstep, voffB); PG8_STAGE(PG8_SA(0, 0), a2, voffA);
;             PG8_WAIT_V(8); PG8_WAIT_L(0); PG8_BAR; PG8_MMA(1, 0, At, B0); PG8_MMA(1, 1, At, B1); PG8_BAR; PG8_SCHED;
;             PG8_LDB(B0, 1, 0); PG8_LDB(B1, 1, 1); PG8_SCHED; PG8_LDA(At, 1, 0); PG8_STAGE(PG8_SA(0, 1), a2 + hstep, voffA);
;             PG8_WAIT_V(8); PG8_WAIT_L(0); PG8_BAR; PG8_MMA(0, 0, At, B0); PG8_MMA(0, 1, At, B1); PG8_BAR; PG8_SCHED;
;             PG8_LDA(At, 1, 1); PG8_STAGE(PG8_SB(1, 0), b3, voffB); PG8_STAGE(PG8_SB(1, 1), b3 + hstep, voffB); PG8_STAGE(PG8_SA(1, 0), a3, voffA);
;             PG8_WAIT_V(8); PG8_WAIT_L(0); PG8_BAR; PG8_MMA(1, 0, At, B0); PG8_MMA(1, 1, At, B1); PG8_BAR; PG8_SCHED;
	s_add_i32 s61, s61, s12
	v_lshl_add_u64 v[82:83], v[190:191], 0, s[68:69]
	s_mov_b32 m0, s61
	ds_read_b128 v[186:189], v230 offset:49152
	ds_read_b128 v[198:201], v230 offset:50176
	ds_read_b128 v[202:205], v230 offset:51200
	ds_read_b128 v[206:209], v230 offset:52224
	ds_read_b128 v[234:237], v230 offset:53248
	ds_read_b128 v[238:241], v230 offset:54272
	ds_read_b128 v[242:245], v230 offset:55296
	ds_read_b128 v[246:249], v230 offset:56320
	global_load_lds_dwordx4 v[82:83], off
	s_add_i32 m0, s61, 0x2000
	s_add_u32 s64, s64, 0x40080
	v_lshl_add_u64 v[82:83], v[250:251], 0, s[68:69]
	s_addc_u32 s65, s65, 0
	s_add_i32 s61, s70, s12
	global_load_lds_dwordx4 v[82:83], off
	s_mov_b32 m0, s61
	s_nop 0
	global_load_lds_dwordx4 v164, s[64:65]
	s_add_i32 m0, s61, 0x2000
	s_nop 0
	global_load_lds_dwordx4 v168, s[64:65]
	v_lshl_add_u64 v[82:83], v[224:225], 0, s[68:69]
	s_mov_b32 m0, s82
	s_nop 0
	global_load_lds_dwordx4 v[82:83], off
	v_lshl_add_u64 v[82:83], v[226:227], 0, s[68:69]
	s_mov_b32 m0, s83
	s_nop 0
	global_load_lds_dwordx4 v[82:83], off
	s_waitcnt vmcnt(8)
	s_waitcnt lgkmcnt(0)
	s_barrier
	s_waitcnt lgkmcnt(0)
	v_mfma_f32_16x16x32_bf16 v[60:63], v[88:91], v[186:189], v[60:63]
	v_mfma_f32_16x16x32_bf16 v[56:59], v[144:147], v[186:189], v[56:59]
	v_mfma_f32_16x16x32_bf16 v[40:43], v[144:147], v[202:205], v[40:43]
	v_mfma_f32_16x16x32_bf16 v[44:47], v[88:91], v[202:205], v[44:47]
	v_mfma_f32_16x16x32_bf16 v[28:31], v[88:91], v[234:237], v[28:31]
	v_mfma_f32_16x16x32_bf16 v[24:27], v[144:147], v[234:237], v[24:27]
	v_mfma_f32_16x16x32_bf16 v[8:11], v[144:147], v[242:245], v[8:11]
	v_mfma_f32_16x16x32_bf16 v[12:15], v[88:91], v[242:245], v[12:15]
	v_mfma_f32_16x16x32_bf16 v[60:63], v[92:95], v[198:201], v[60:63]
	v_mfma_f32_16x16x32_bf16 v[56:59], v[148:151], v[198:201], v[56:59]
	v_mfma_f32_16x16x32_bf16 v[40:43], v[148:151], v[206:209], v[40:43]
	v_mfma_f32_16x16x32_bf16 v[44:47], v[92:95], v[206:209], v[44:47]
	v_mfma_f32_16x16x32_bf16 v[28:31], v[92:95], v[238:241], v[28:31]
	v_mfma_f32_16x16x32_bf16 v[24:27], v[148:151], v[238:241], v[24:27]
	v_mfma_f32_16x16x32_bf16 v[8:11], v[148:151], v[246:249], v[8:11]
	v_mfma_f32_16x16x32_bf16 v[12:15], v[92:95], v[246:249], v[12:15]
	v_mfma_f32_16x16x32_bf16 v[52:55], v[152:155], v[186:189], v[52:55]
	v_mfma_f32_16x16x32_bf16 v[48:51], v[178:181], v[186:189], v[48:51]
	v_mfma_f32_16x16x32_bf16 v[32:35], v[178:181], v[202:205], v[32:35]
	v_mfma_f32_16x16x32_bf16 v[36:39], v[152:155], v[202:205], v[36:39]
	v_mfma_f32_16x16x32_bf16 v[20:23], v[152:155], v[234:237], v[20:23]
	v_mfma_f32_16x16x32_bf16 v[16:19], v[178:181], v[234:237], v[16:19]
	v_mfma_f32_16x16x32_bf16 v[0:3], v[178:181], v[242:245], v[0:3]
	v_mfma_f32_16x16x32_bf16 v[4:7], v[152:155], v[242:245], v[4:7]
	v_mfma_f32_16x16x32_bf16 v[52:55], v[156:159], v[198:201], v[52:55]
	v_mfma_f32_16x16x32_bf16 v[48:51], v[182:185], v[198:201], v[48:51]
	v_mfma_f32_16x16x32_bf16 v[32:35], v[182:185], v[206:209], v[32:35]
	v_mfma_f32_16x16x32_bf16 v[36:39], v[156:159], v[206:209], v[36:39]
	v_mfma_f32_16x16x32_bf16 v[20:23], v[156:159], v[238:241], v[20:23]
	v_mfma_f32_16x16x32_bf16 v[16:19], v[182:185], v[238:241], v[16:19]
	v_mfma_f32_16x16x32_bf16 v[0:3], v[182:185], v[246:249], v[0:3]
	v_mfma_f32_16x16x32_bf16 v[4:7], v[156:159], v[246:249], v[4:7]
	s_barrier
	s_add_i32 s60, s60, 2
	s_add_u32 s6, s6, 0x100
	s_addc_u32 s7, s7, 0
	s_add_u32 s58, s58, 0x100
	s_addc_u32 s59, s59, 0
	s_cmp_gt_u32 s60, 13
.LBB0_266:
	s_add_u32 s61, s6, 0xfffc0080
	s_addc_u32 s64, s7, -1
	s_add_i32 s70, 0, 0x10000
	s_cmp_eq_u32 s60, 12
	s_cselect_b32 s67, s23, s64
	s_cselect_b32 s66, s56, s61
	v_add_u32_e32 v81, s70, v216
	s_cselect_b32 s65, s55, s59
	s_cselect_b32 s64, s57, s58
	s_add_i32 s61, 0, 0x14000
	ds_read_b128 v[88:91], v81
	ds_read_b128 v[92:95], v81 offset:1024
	ds_read_b128 v[144:147], v81 offset:2048
	ds_read_b128 v[148:151], v81 offset:3072
	v_add_u32_e32 v81, s61, v216
	ds_read_b128 v[152:155], v81
	ds_read_b128 v[156:159], v81 offset:1024
	ds_read_b128 v[178:181], v81 offset:2048
	ds_read_b128 v[182:185], v81 offset:3072
	s_add_i32 m0, s73, 0xc000
	ds_read_b128 v[186:189], v230
	ds_read_b128 v[198:201], v230 offset:1024
	ds_read_b128 v[202:205], v230 offset:2048
	ds_read_b128 v[206:209], v230 offset:3072
	ds_read_b128 v[234:237], v230 offset:4096
	ds_read_b128 v[238:241], v230 offset:5120
	ds_read_b128 v[242:245], v230 offset:6144
	ds_read_b128 v[246:249], v230 offset:7168
	global_load_lds_dwordx4 v174, s[6:7]
	v_lshl_add_u64 v[82:83], s[6:7], 0, v[176:177]
	s_add_i32 m0, s73, 0xe000
	s_nop 0
	global_load_lds_dwordx4 v176, s[6:7]
	s_waitcnt vmcnt(8)
	s_waitcnt lgkmcnt(0)
	s_barrier
; #define PG8_STAGE(bufoff, gbase, voff) do { _Pragma("unroll") for (int _i = 0; _i < 2; ++_i) \
;         __builtin_amdgcn_global_load_lds((const unsigned*)((const char*)(gbase) + (voff)[_i]), (LAS unsigned*)(lds + (bufoff) + ldsw + _i * 8192), 16, 0, 0); } while (0)
; #define PG8_LDA(dst, b, h) do { _Pragma("unroll") for (int m = 0; m < 4; ++m) _Pragma("unroll") for (int k = 0; k < 2; ++k) dst[m][k] = *(const LAS bf16x8*)(lds + PG8_SA(b, h) + aoff + m * 2048 + k * 1024); } while (0)
; #define PG8_MMA(ai, bj, At, Bt) do { __builtin_amdgcn_s_setprio(1); _Pragma("unroll") for (int m = 0; m < 4; ++m) _Pragma("unroll") for (int n = 0; n < 2; ++n) _Pragma("unroll") for (int k = 0; k < 2; ++k) \
;         acc[ai][bj][m][n] = __builtin_amdgcn_mfma_f32_16x16x32_bf16(Bt[n][k], At[m][k], acc[ai][bj][m][n], 0, 0, 0); __builtin_amdgcn_s_setprio(0); } while (0)
; #define PG8_WAIT_V(n) asm volatile("s_waitcnt vmcnt(" #n ")" ::: "memory")
; #define PG8_WAIT_L(n) asm volatile("s_waitcnt lgkmcnt(" #n ")" ::: "memory")
; #define PG8_BAR __builtin_amdgcn_s_barrier()
; #define PG8_SCHED __builtin_amdgcn_sched_barrier(0)
; template <class Epi, class Sched>
; __device__ __forceinline__ void gemm_phase(LAS unsigned char* lds, const Gemm g, const Sched& S, const Epi& E, const int tid) {
;     ...
;             PG8_WAIT_V(8); PG8_WAIT_L(0); PG8_BAR; PG8_MMA(0, 0, At, B0); PG8_MMA(0, 1, At, B1); PG8_BAR; PG8_SCHED;
;             PG8_LDA(At, 0, 1); PG8_STAGE(PG8_SB(0, 0), b2, voffB); PG8_STAGE(PG8_SB(0, 1), b2 + hstep, voffB); PG8_STAGE(PG8_SA(0, 0), a2, voffA);
;             PG8_WAIT_V(8); PG8_WAIT_L(0); PG8_BAR; PG8_MMA(1, 0, At, B0); PG8_MMA(1, 1, At, B1); PG8_BAR; PG8_SCHED;
	s_waitcnt lgkmcnt(0)
	v_mfma_f32_16x16x32_bf16 v[140:143], v[88:91], v[186:189], v[140:143]
	v_mfma_f32_16x16x32_bf16 v[136:139], v[144:147], v[186:189], v[136:139]
	v_mfma_f32_16x16x32_bf16 v[120:123], v[144:147], v[202:205], v[120:123]
	v_mfma_f32_16x16x32_bf16 v[124:127], v[88:91], v[202:205], v[124:127]
	v_mfma_f32_16x16x32_bf16 v[108:111], v[88:91], v[234:237], v[108:111]
	v_mfma_f32_16x16x32_bf16 v[104:107], v[144:147], v[234:237], v[104:107]
	v_mfma_f32_16x16x32_bf16 v[76:79], v[144:147], v[242:245], v[76:79]
	v_mfma_f32_16x16x32_bf16 v[82:85], v[88:91], v[242:245], v[84:87]
	v_mfma_f32_16x16x32_bf16 v[140:143], v[92:95], v[198:201], v[140:143]
	v_mfma_f32_16x16x32_bf16 v[136:139], v[148:151], v[198:201], v[136:139]
	v_mfma_f32_16x16x32_bf16 v[120:123], v[148:151], v[206:209], v[120:123]
	v_mfma_f32_16x16x32_bf16 v[124:127], v[92:95], v[206:209], v[124:127]
	v_mfma_f32_16x16x32_bf16 v[108:111], v[92:95], v[238:241], v[108:111]
	v_mfma_f32_16x16x32_bf16 v[104:107], v[148:151], v[238:241], v[104:107]
	v_mfma_f32_16x16x32_bf16 v[76:79], v[148:151], v[246:249], v[76:79]
	v_mfma_f32_16x16x32_bf16 v[82:85], v[92:95], v[246:249], v[82:85]
	v_mfma_f32_16x16x32_bf16 v[132:135], v[152:155], v[186:189], v[132:135]
	v_mfma_f32_16x16x32_bf16 v[128:131], v[178:181], v[186:189], v[128:131]
	v_mfma_f32_16x16x32_bf16 v[112:115], v[178:181], v[202:205], v[112:115]
	v_mfma_f32_16x16x32_bf16 v[116:119], v[152:155], v[202:205], v[116:119]
	v_mfma_f32_16x16x32_bf16 v[100:103], v[152:155], v[234:237], v[100:103]
	v_mfma_f32_16x16x32_bf16 v[96:99], v[178:181], v[234:237], v[96:99]
	v_mfma_f32_16x16x32_bf16 v[64:67], v[178:181], v[242:245], v[64:67]
	v_mfma_f32_16x16x32_bf16 v[68:71], v[152:155], v[242:245], v[68:71]
	v_mfma_f32_16x16x32_bf16 v[132:135], v[156:159], v[198:201], v[132:135]
	v_mfma_f32_16x16x32_bf16 v[128:131], v[182:185], v[198:201], v[128:131]
	v_mfma_f32_16x16x32_bf16 v[112:115], v[182:185], v[206:209], v[112:115]
	v_mfma_f32_16x16x32_bf16 v[116:119], v[156:159], v[206:209], v[116:119]
	v_mfma_f32_16x16x32_bf16 v[100:103], v[156:159], v[238:241], v[100:103]
	v_mfma_f32_16x16x32_bf16 v[96:99], v[182:185], v[238:241], v[96:99]
	v_mfma_f32_16x16x32_bf16 v[64:67], v[182:185], v[246:249], v[64:67]
	v_mfma_f32_16x16x32_bf16 v[68:71], v[156:159], v[246:249], v[68:71]
	s_barrier
	s_add_i32 s70, s70, s12
	v_lshl_add_u64 v[190:191], s[64:65], 0, v[164:165]
	s_mov_b32 m0, s70
	ds_read_b128 v[186:189], v230 offset:16384
	ds_read_b128 v[198:201], v230 offset:17408
	ds_read_b128 v[202:205], v230 offset:18432
	ds_read_b128 v[206:209], v230 offset:19456
	ds_read_b128 v[234:237], v230 offset:20480
	ds_read_b128 v[238:241], v230 offset:21504
	ds_read_b128 v[242:245], v230 offset:22528
	ds_read_b128 v[246:249], v230 offset:23552
	global_load_lds_dwordx4 v164, s[64:65]
	s_add_i32 m0, s70, 0x2000
	s_add_u32 s70, s64, 0x40000
	v_lshl_add_u64 v[250:251], s[64:65], 0, v[168:169]
	s_addc_u32 s71, s65, 0
	s_add_i32 s61, s61, s12
	global_load_lds_dwordx4 v168, s[64:65]
	s_mov_b32 m0, s61
	v_lshl_add_u64 v[224:225], s[66:67], 0, v[162:163]
	global_load_lds_dwordx4 v164, s[70:71]
	s_add_i32 m0, s61, 0x2000
	v_lshl_add_u64 v[226:227], s[66:67], 0, v[166:167]
	global_load_lds_dwordx4 v168, s[70:71]
	s_mov_b32 m0, s73
	s_nop 0
	global_load_lds_dwordx4 v162, s[66:67]
	s_mov_b32 m0, s74
	s_nop 0
	global_load_lds_dwordx4 v166, s[66:67]
	s_waitcnt vmcnt(8)
	s_waitcnt lgkmcnt(0)
	s_barrier
	s_waitcnt lgkmcnt(0)
	v_mfma_f32_16x16x32_bf16 v[60:63], v[88:91], v[186:189], v[60:63]
	v_mfma_f32_16x16x32_bf16 v[56:59], v[144:147], v[186:189], v[56:59]
	v_mfma_f32_16x16x32_bf16 v[40:43], v[144:147], v[202:205], v[40:43]
	v_mfma_f32_16x16x32_bf16 v[44:47], v[88:91], v[202:205], v[44:47]
	v_mfma_f32_16x16x32_bf16 v[28:31], v[88:91], v[234:237], v[28:31]
	v_mfma_f32_16x16x32_bf16 v[24:27], v[144:147], v[234:237], v[24:27]
	v_mfma_f32_16x16x32_bf16 v[8:11], v[144:147], v[242:245], v[8:11]
	v_mfma_f32_16x16x32_bf16 v[12:15], v[88:91], v[242:245], v[12:15]
	v_mfma_f32_16x16x32_bf16 v[60:63], v[92:95], v[198:201], v[60:63]
	v_mfma_f32_16x16x32_bf16 v[56:59], v[148:151], v[198:201], v[56:59]
	v_mfma_f32_16x16x32_bf16 v[40:43], v[148:151], v[206:209], v[40:43]
	v_mfma_f32_16x16x32_bf16 v[44:47], v[92:95], v[206:209], v[44:47]
	v_mfma_f32_16x16x32_bf16 v[28:31], v[92:95], v[238:241], v[28:31]
	v_mfma_f32_16x16x32_bf16 v[24:27], v[148:151], v[238:241], v[24:27]
	v_mfma_f32_16x16x32_bf16 v[8:11], v[148:151], v[246:249], v[8:11]
	v_mfma_f32_16x16x32_bf16 v[12:15], v[92:95], v[246:249], v[12:15]
	v_mfma_f32_16x16x32_bf16 v[52:55], v[152:155], v[186:189], v[52:55]
	v_mfma_f32_16x16x32_bf16 v[48:51], v[178:181], v[186:189], v[48:51]
	v_mfma_f32_16x16x32_bf16 v[32:35], v[178:181], v[202:205], v[32:35]
	v_mfma_f32_16x16x32_bf16 v[36:39], v[152:155], v[202:205], v[36:39]
	v_mfma_f32_16x16x32_bf16 v[20:23], v[152:155], v[234:237], v[20:23]
	v_mfma_f32_16x16x32_bf16 v[16:19], v[178:181], v[234:237], v[16:19]
	v_mfma_f32_16x16x32_bf16 v[0:3], v[178:181], v[242:245], v[0:3]
	v_mfma_f32_16x16x32_bf16 v[4:7], v[152:155], v[242:245], v[4:7]
	v_mfma_f32_16x16x32_bf16 v[52:55], v[156:159], v[198:201], v[52:55]
	v_mfma_f32_16x16x32_bf16 v[48:51], v[182:185], v[198:201], v[48:51]
	v_mfma_f32_16x16x32_bf16 v[32:35], v[182:185], v[206:209], v[32:35]
	v_mfma_f32_16x16x32_bf16 v[36:39], v[156:159], v[206:209], v[36:39]
	v_mfma_f32_16x16x32_bf16 v[20:23], v[156:159], v[238:241], v[20:23]
	v_mfma_f32_16x16x32_bf16 v[16:19], v[182:185], v[238:241], v[16:19]
	v_mfma_f32_16x16x32_bf16 v[0:3], v[182:185], v[246:249], v[0:3]
	v_mfma_f32_16x16x32_bf16 v[4:7], v[156:159], v[246:249], v[4:7]
	s_barrier
; #define PG8_STAGE(bufoff, gbase, voff) do { _Pragma("unroll") for (int _i = 0; _i < 2; ++_i) \
;         __builtin_amdgcn_global_load_lds((const unsigned*)((const char*)(gbase) + (voff)[_i]), (LAS unsigned*)(lds + (bufoff) + ldsw + _i * 8192), 16, 0, 0); } while (0)
; #define PG8_LDA(dst, b, h) do { _Pragma("unroll") for (int m = 0; m < 4; ++m) _Pragma("unroll") for (int k = 0; k < 2; ++k) dst[m][k] = *(const LAS bf16x8*)(lds + PG8_SA(b, h) + aoff + m * 2048 + k * 1024); } while (0)
; #define PG8_LDB(dst, b, h) do { _Pragma("unroll") for (int n = 0; n < 2; ++n) _Pragma("unroll") for (int k = 0; k < 2; ++k) dst[n][k] = *(const LAS bf16x8*)(lds + PG8_SB(b, h) + boff + n * 2048 + k * 1024); } while (0)
; #define PG8_MMA(ai, bj, At, Bt) do { __builtin_amdgcn_s_setprio(1); _Pragma("unroll") for (int m = 0; m < 4; ++m) _Pragma("unroll") for (int n = 0; n < 2; ++n) _Pragma("unroll") for (int k = 0; k < 2; ++k) \
;         acc[ai][bj][m][n] = __builtin_amdgcn_mfma_f32_16x16x32_bf16(Bt[n][k], At[m][k], acc[ai][bj][m][n], 0, 0, 0); __builtin_amdgcn_s_setprio(0); } while (0)
; #define PG8_WAIT_V(n) asm volatile("s_waitcnt vmcnt(" #n ")" ::: "memory")
; #define PG8_WAIT_L(n) asm volatile("s_waitcnt lgkmcnt(" #n ")" ::: "memory")
; #define PG8_BAR __builtin_amdgcn_s_barrier()
; #define PG8_SCHED __builtin_amdgcn_sched_barrier(0)
; template <class Epi, class Sched>
; __device__ __forceinline__ void gemm_phase(LAS unsigned char* lds, const Gemm g, const Sched& S, const Epi& E, const int tid) {
;     ...
;             PG8_LDB(B0, 1, 0); PG8_LDB(B1, 1, 1); PG8_SCHED; PG8_LDA(At, 1, 0); PG8_STAGE(PG8_SA(0, 1), a2 + hstep, voffA);
;             PG8_WAIT_V(8); PG8_WAIT_L(0); PG8_BAR; PG8_MMA(0, 0, At, B0); PG8_MMA(0, 1, At, B1); PG8_BAR; PG8_SCHED;
;             PG8_LDA(At, 1, 1); PG8_STAGE(PG8_SB(1, 0), b3, voffB); PG8_STAGE(PG8_SB(1, 1), b3 + hstep, voffB); PG8_STAGE(PG8_SA(1, 0), a3, voffA);
;             PG8_WAIT_V(8); PG8_WAIT_L(0); PG8_BAR; PG8_MMA(1, 0, At, B0); PG8_MMA(1, 1, At, B1); PG8_BAR; PG8_SCHED;
;         }
	s_add_i32 s61, 0, 0x18000
	v_add_u32_e32 v81, s61, v216
	s_add_i32 s70, 0, 0x1c000
	ds_read_b128 v[88:91], v81
	ds_read_b128 v[92:95], v81 offset:1024
	ds_read_b128 v[144:147], v81 offset:2048
	ds_read_b128 v[148:151], v81 offset:3072
	v_add_u32_e32 v81, s70, v216
	ds_read_b128 v[152:155], v81
	ds_read_b128 v[156:159], v81 offset:1024
	ds_read_b128 v[178:181], v81 offset:2048
	ds_read_b128 v[182:185], v81 offset:3072
	s_add_u32 s66, s66, 0x40000
	s_addc_u32 s67, s67, 0
	s_mov_b32 m0, s75
	ds_read_b128 v[186:189], v230 offset:32768
	ds_read_b128 v[198:201], v230 offset:33792
	ds_read_b128 v[202:205], v230 offset:34816
	ds_read_b128 v[206:209], v230 offset:35840
	ds_read_b128 v[234:237], v230 offset:36864
	ds_read_b128 v[238:241], v230 offset:37888
	ds_read_b128 v[242:245], v230 offset:38912
	ds_read_b128 v[246:249], v230 offset:39936
	global_load_lds_dwordx4 v162, s[66:67]
	v_lshl_add_u64 v[86:87], s[66:67], 0, v[166:167]
	s_mov_b32 m0, s81
	s_nop 0
	global_load_lds_dwordx4 v166, s[66:67]
	s_waitcnt vmcnt(8)
	s_waitcnt lgkmcnt(0)
	s_barrier
	s_waitcnt lgkmcnt(0)
	v_mfma_f32_16x16x32_bf16 v[140:143], v[88:91], v[186:189], v[140:143]
	v_mfma_f32_16x16x32_bf16 v[136:139], v[144:147], v[186:189], v[136:139]
	v_mfma_f32_16x16x32_bf16 v[120:123], v[144:147], v[202:205], v[120:123]
	v_mfma_f32_16x16x32_bf16 v[124:127], v[88:91], v[202:205], v[124:127]
	v_mfma_f32_16x16x32_bf16 v[108:111], v[88:91], v[234:237], v[108:111]
	v_mfma_f32_16x16x32_bf16 v[104:107], v[144:147], v[234:237], v[104:107]
	v_mfma_f32_16x16x32_bf16 v[76:79], v[144:147], v[242:245], v[76:79]
	v_mfma_f32_16x16x32_bf16 v[82:85], v[88:91], v[242:245], v[82:85]
	v_mfma_f32_16x16x32_bf16 v[140:143], v[92:95], v[198:201], v[140:143]
	v_mfma_f32_16x16x32_bf16 v[136:139], v[148:151], v[198:201], v[136:139]
	v_mfma_f32_16x16x32_bf16 v[120:123], v[148:151], v[206:209], v[120:123]
	v_mfma_f32_16x16x32_bf16 v[124:127], v[92:95], v[206:209], v[124:127]
	v_mfma_f32_16x16x32_bf16 v[108:111], v[92:95], v[238:241], v[108:111]
	v_mfma_f32_16x16x32_bf16 v[104:107], v[148:151], v[238:241], v[104:107]
	v_mfma_f32_16x16x32_bf16 v[76:79], v[148:151], v[246:249], v[76:79]
	v_mfma_f32_16x16x32_bf16 v[84:87], v[92:95], v[246:249], v[82:85]
	v_mfma_f32_16x16x32_bf16 v[132:135], v[152:155], v[186:189], v[132:135]
	v_mfma_f32_16x16x32_bf16 v[128:131], v[178:181], v[186:189], v[128:131]
	v_mfma_f32_16x16x32_bf16 v[112:115], v[178:181], v[202:205], v[112:115]
	v_mfma_f32_16x16x32_bf16 v[116:119], v[152:155], v[202:205], v[116:119]
	v_mfma_f32_16x16x32_bf16 v[100:103], v[152:155], v[234:237], v[100:103]
	v_mfma_f32_16x16x32_bf16 v[96:99], v[178:181], v[234:237], v[96:99]
	v_mfma_f32_16x16x32_bf16 v[64:67], v[178:181], v[242:245], v[64:67]
	v_mfma_f32_16x16x32_bf16 v[68:71], v[152:155], v[242:245], v[68:71]
	v_mfma_f32_16x16x32_bf16 v[132:135], v[156:159], v[198:201], v[132:135]
	v_mfma_f32_16x16x32_bf16 v[128:131], v[182:185], v[198:201], v[128:131]
	v_mfma_f32_16x16x32_bf16 v[112:115], v[182:185], v[206:209], v[112:115]
	v_mfma_f32_16x16x32_bf16 v[116:119], v[156:159], v[206:209], v[116:119]
	v_mfma_f32_16x16x32_bf16 v[100:103], v[156:159], v[238:241], v[100:103]
	v_mfma_f32_16x16x32_bf16 v[96:99], v[182:185], v[238:241], v[96:99]
	v_mfma_f32_16x16x32_bf16 v[64:67], v[182:185], v[246:249], v[64:67]
	v_mfma_f32_16x16x32_bf16 v[68:71], v[156:159], v[246:249], v[68:71]
	s_barrier
	s_add_i32 s61, s61, s12
	v_lshl_add_u64 v[82:83], v[190:191], 0, s[68:69]
	s_mov_b32 m0, s61
	ds_read_b128 v[186:189], v230 offset:49152
	ds_read_b128 v[198:201], v230 offset:50176
	ds_read_b128 v[202:205], v230 offset:51200
	ds_read_b128 v[206:209], v230 offset:52224
	ds_read_b128 v[234:237], v230 offset:53248
	ds_read_b128 v[238:241], v230 offset:54272
	ds_read_b128 v[242:245], v230 offset:55296
	ds_read_b128 v[246:249], v230 offset:56320
	global_load_lds_dwordx4 v[82:83], off
	s_add_i32 m0, s61, 0x2000
	s_add_u32 s64, s64, 0x40080
	v_lshl_add_u64 v[82:83], v[250:251], 0, s[68:69]
	s_addc_u32 s65, s65, 0
	s_add_i32 s61, s70, s12
	global_load_lds_dwordx4 v[82:83], off
	s_mov_b32 m0, s61
	s_nop 0
	global_load_lds_dwordx4 v164, s[64:65]
	s_add_i32 m0, s61, 0x2000
	s_nop 0
	global_load_lds_dwordx4 v168, s[64:65]
	v_lshl_add_u64 v[82:83], v[224:225], 0, s[68:69]
	s_mov_b32 m0, s82
	s_nop 0
	global_load_lds_dwordx4 v[82:83], off
	v_lshl_add_u64 v[82:83], v[226:227], 0, s[68:69]
	s_mov_b32 m0, s83
	s_nop 0
	global_load_lds_dwordx4 v[82:83], off
	s_waitcnt vmcnt(8)
	s_waitcnt lgkmcnt(0)
	s_barrier
	s_waitcnt lgkmcnt(0)
	v_mfma_f32_16x16x32_bf16 v[60:63], v[88:91], v[186:189], v[60:63]
	v_mfma_f32_16x16x32_bf16 v[56:59], v[144:147], v[186:189], v[56:59]
	v_mfma_f32_16x16x32_bf16 v[40:43], v[144:147], v[202:205], v[40:43]
	v_mfma_f32_16x16x32_bf16 v[44:47], v[88:91], v[202:205], v[44:47]
	v_mfma_f32_16x16x32_bf16 v[28:31], v[88:91], v[234:237], v[28:31]
	v_mfma_f32_16x16x32_bf16 v[24:27], v[144:147], v[234:237], v[24:27]
	v_mfma_f32_16x16x32_bf16 v[8:11], v[144:147], v[242:245], v[8:11]
	v_mfma_f32_16x16x32_bf16 v[12:15], v[88:91], v[242:245], v[12:15]
	v_mfma_f32_16x16x32_bf16 v[60:63], v[92:95], v[198:201], v[60:63]
	v_mfma_f32_16x16x32_bf16 v[56:59], v[148:151], v[198:201], v[56:59]
	v_mfma_f32_16x16x32_bf16 v[40:43], v[148:151], v[206:209], v[40:43]
	v_mfma_f32_16x16x32_bf16 v[44:47], v[92:95], v[206:209], v[44:47]
	v_mfma_f32_16x16x32_bf16 v[28:31], v[92:95], v[238:241], v[28:31]
	v_mfma_f32_16x16x32_bf16 v[24:27], v[148:151], v[238:241], v[24:27]
	v_mfma_f32_16x16x32_bf16 v[8:11], v[148:151], v[246:249], v[8:11]
	v_mfma_f32_16x16x32_bf16 v[12:15], v[92:95], v[246:249], v[12:15]
	v_mfma_f32_16x16x32_bf16 v[52:55], v[152:155], v[186:189], v[52:55]
	v_mfma_f32_16x16x32_bf16 v[48:51], v[178:181], v[186:189], v[48:51]
	v_mfma_f32_16x16x32_bf16 v[32:35], v[178:181], v[202:205], v[32:35]
	v_mfma_f32_16x16x32_bf16 v[36:39], v[152:155], v[202:205], v[36:39]
	v_mfma_f32_16x16x32_bf16 v[20:23], v[152:155], v[234:237], v[20:23]
	v_mfma_f32_16x16x32_bf16 v[16:19], v[178:181], v[234:237], v[16:19]
	v_mfma_f32_16x16x32_bf16 v[0:3], v[178:181], v[242:245], v[0:3]
	v_mfma_f32_16x16x32_bf16 v[4:7], v[152:155], v[242:245], v[4:7]
	v_mfma_f32_16x16x32_bf16 v[52:55], v[156:159], v[198:201], v[52:55]
	v_mfma_f32_16x16x32_bf16 v[48:51], v[182:185], v[198:201], v[48:51]
	v_mfma_f32_16x16x32_bf16 v[32:35], v[182:185], v[206:209], v[32:35]
	v_mfma_f32_16x16x32_bf16 v[36:39], v[156:159], v[206:209], v[36:39]
	v_mfma_f32_16x16x32_bf16 v[20:23], v[156:159], v[238:241], v[20:23]
	v_mfma_f32_16x16x32_bf16 v[16:19], v[182:185], v[238:241], v[16:19]
	v_mfma_f32_16x16x32_bf16 v[0:3], v[182:185], v[246:249], v[0:3]
	v_mfma_f32_16x16x32_bf16 v[4:7], v[156:159], v[246:249], v[4:7]
	s_barrier
	s_add_i32 s60, s60, 2
	s_add_u32 s6, s6, 0x100
	s_addc_u32 s7, s7, 0
	s_add_u32 s58, s58, 0x100
	s_addc_u32 s59, s59, 0
	s_cmp_gt_u32 s60, 13
	s_cbranch_scc0 .LBB0_266
	s_and_b64 vcc, exec, s[50:51]
	s_cbranch_vccz .LBB0_269
	s_barrier

;     __device__ __forceinline__ Pre prefetch(const Unit& u, int tid) const { return prenorm_load(stats, u.pn * BM, sW + (size_t)(u.pn >> 4) * SW_ROWS + u.pm * BM, tid); }
;     __device__ __forceinline__ Pre prefetch(const Unit& u, int tid) const { return prenorm_load(stats, u.pm * BM, sW + (size_t)(u.pm >> 4) * SW_ROWS + u.pn * BM, tid); }
;     __device__ __forceinline__ Pre prefetch(const Unit& u, int tid) const { return prenorm_load(stats, u.pm * BM, sW + (size_t)(u.pm >> 4) * SW_ROWS + u.pn * BM, tid); }
; #define PG8_STAGE(bufoff, gbase, voff) do { _Pragma("unroll") for (int _i = 0; _i < 2; ++_i) \
;         __builtin_amdgcn_global_load_lds((const unsigned*)((const char*)(gbase) + (voff)[_i]), (LAS unsigned*)(lds + (bufoff) + ldsw + _i * 8192), 16, 0, 0); } while (0)
; #define PG8_LDA(dst, b, h) do { _Pragma("unroll") for (int m = 0; m < 4; ++m) _Pragma("unroll") for (int k = 0; k < 2; ++k) dst[m][k] = *(const LAS bf16x8*)(lds + PG8_SA(b, h) + aoff + m * 2048 + k * 1024); } while (0)
; #define PG8_WAIT_V(n) asm volatile("s_waitcnt vmcnt(" #n ")" ::: "memory")
; template <class Epi, class Sched>
; __device__ __forceinline__ void gemm_phase(LAS unsigned char* lds, const Gemm g, const Sched& S, const Epi& E, const int tid) {
;     ...
;         const bool has_next = S.next(ui + 1, nxt);
;         const char* nA = has_next ? (const char*)g.A + (size_t)nxt.pm * tstep : cA; const char* nB = has_next ? (const char*)g.Bt + (size_t)nxt.pn * tstep : cB;
;         const typename Epi::Pre pre = E.prefetch(cur, tid);
;         for (int t = 0; t < nt; t += 2) {
;             const bool last = (t == nt - 2);
;             const char* a1 = cA + (size_t)(t + 1) * kstep;
;             const char* a2 = last ? nA : cA + (size_t)(t + 2) * kstep; const char* b2 = last ? nB : cB + (size_t)(t + 2) * kstep;
;             const char* a3 = a2 + kstep; const char* b3 = b2 + kstep;
;             PG8_LDB(B0, 0, 0); PG8_LDB(B1, 0, 1); PG8_SCHED; PG8_LDA(At, 0, 0); PG8_STAGE(PG8_SA(1, 1), a1 + hstep, voffA);
;             PG8_WAIT_V(8); PG8_WAIT_L(0); PG8_BAR; PG8_MMA(0, 0, At, B0); PG8_MMA(0, 1, At, B1); PG8_BAR; PG8_SCHED;
;             PG8_LDA(At, 0, 1); PG8_STAGE(PG8_SB(0, 0), b2, voffB); PG8_STAGE(PG8_SB(0, 1), b2 + hstep, voffB); PG8_STAGE(PG8_SA(0, 0), a2, voffA);
;             PG8_WAIT_V(8); PG8_WAIT_L(0); PG8_BAR; PG8_MMA(1, 0, At, B0); PG8_MMA(1, 1, At, B1); PG8_BAR; PG8_SCHED;
.LBB0_325:
	s_or_b64 exec, exec, s[50:51]
	s_ashr_i32 s39, s38, 31
	s_lshl_b64 s[50:51], s[38:39], 19
	s_add_u32 s50, s85, s50
	s_addc_u32 s51, s86, s51
	s_and_b64 s[54:55], s[4:5], exec
	s_cselect_b32 s39, s51, s63
	s_cselect_b32 s74, s50, s62
	s_ashr_i32 s23, s22, 31
	s_lshl_b64 s[54:55], s[22:23], 19
	s_add_u32 s54, s46, s54
	s_addc_u32 s55, s47, s55
	s_and_b64 s[66:67], s[4:5], exec
	s_cselect_b32 s23, s55, s65
	s_cselect_b32 s75, s54, s64
	s_add_u32 s62, s62, 0x40080
	s_addc_u32 s63, s63, 0
	s_add_u32 s78, s64, 0x100
	s_addc_u32 s79, s65, 0
	s_mov_b32 s81, -2
	s_waitcnt lgkmcnt(0)
	s_add_u32 s64, s62, 0xfffc0080
	s_addc_u32 s65, s63, -1
	s_add_i32 s82, 0, 0x10000
	s_cmp_eq_u32 s81, 12
	s_cselect_b32 s67, s39, s65
	s_cselect_b32 s66, s74, s64
	v_add_u32_e32 v69, s82, v154
	s_cselect_b32 s65, s23, s79
	s_cselect_b32 s64, s75, s78
	s_add_i32 s90, 0, 0x14000
	ds_read_b128 v[70:73], v69
	ds_read_b128 v[74:77], v69 offset:1024
	ds_read_b128 v[172:175], v69 offset:2048
	ds_read_b128 v[176:179], v69 offset:3072
	v_add_u32_e32 v69, s90, v154
	ds_read_b128 v[180:183], v69
	ds_read_b128 v[184:187], v69 offset:1024
	ds_read_b128 v[188:191], v69 offset:2048
	ds_read_b128 v[198:201], v69 offset:3072
	s_add_i32 m0, s53, 0xc000
	ds_read_b128 v[202:205], v171
	ds_read_b128 v[206:209], v171 offset:1024
	ds_read_b128 v[210:213], v171 offset:2048
	ds_read_b128 v[214:217], v171 offset:3072
	ds_read_b128 v[218:221], v171 offset:4096
	ds_read_b128 v[230:233], v171 offset:5120
	ds_read_b128 v[234:237], v171 offset:6144
	ds_read_b128 v[238:241], v171 offset:7168
	global_load_lds_dwordx4 v144, s[62:63]
	v_lshl_add_u64 v[78:79], s[62:63], 0, v[146:147]
	s_add_i32 m0, s53, 0xe000
	s_nop 0
	global_load_lds_dwordx4 v146, s[62:63]
	s_waitcnt vmcnt(8)
	s_waitcnt lgkmcnt(0)
	s_barrier
	s_waitcnt lgkmcnt(0)
	v_mfma_f32_16x16x32_bf16 v[140:143], v[70:73], v[202:205], 0
	v_mfma_f32_16x16x32_bf16 v[136:139], v[172:175], v[202:205], 0
	v_mfma_f32_16x16x32_bf16 v[128:131], v[172:175], v[210:213], 0
	v_mfma_f32_16x16x32_bf16 v[132:135], v[70:73], v[210:213], 0
	v_mfma_f32_16x16x32_bf16 v[116:119], v[70:73], v[218:221], 0
	v_mfma_f32_16x16x32_bf16 v[112:115], v[172:175], v[218:221], 0
	v_mfma_f32_16x16x32_bf16 v[96:99], v[172:175], v[234:237], 0
	v_mfma_f32_16x16x32_bf16 v[100:103], v[70:73], v[234:237], 0
	v_mfma_f32_16x16x32_bf16 v[140:143], v[74:77], v[206:209], v[140:143]
	v_mfma_f32_16x16x32_bf16 v[136:139], v[176:179], v[206:209], v[136:139]
	v_mfma_f32_16x16x32_bf16 v[128:131], v[176:179], v[214:217], v[128:131]
	v_mfma_f32_16x16x32_bf16 v[132:135], v[74:77], v[214:217], v[132:135]
	v_mfma_f32_16x16x32_bf16 v[116:119], v[74:77], v[230:233], v[116:119]
	v_mfma_f32_16x16x32_bf16 v[112:115], v[176:179], v[230:233], v[112:115]
	v_mfma_f32_16x16x32_bf16 v[96:99], v[176:179], v[238:241], v[96:99]
	v_mfma_f32_16x16x32_bf16 v[100:103], v[74:77], v[238:241], v[100:103]
	v_mfma_f32_16x16x32_bf16 v[124:127], v[180:183], v[202:205], 0
	v_mfma_f32_16x16x32_bf16 v[120:123], v[188:191], v[202:205], 0
	v_mfma_f32_16x16x32_bf16 v[104:107], v[188:191], v[210:213], 0
	v_mfma_f32_16x16x32_bf16 v[108:111], v[180:183], v[210:213], 0
	v_mfma_f32_16x16x32_bf16 v[92:95], v[180:183], v[218:221], 0
	v_mfma_f32_16x16x32_bf16 v[88:91], v[188:191], v[218:221], 0
	v_mfma_f32_16x16x32_bf16 v[78:81], v[188:191], v[234:237], 0
	v_mfma_f32_16x16x32_bf16 v[84:87], v[180:183], v[234:237], 0
	v_mfma_f32_16x16x32_bf16 v[124:127], v[184:187], v[206:209], v[124:127]
	v_mfma_f32_16x16x32_bf16 v[120:123], v[198:201], v[206:209], v[120:123]
	v_mfma_f32_16x16x32_bf16 v[104:107], v[198:201], v[214:217], v[104:107]
	v_mfma_f32_16x16x32_bf16 v[108:111], v[184:187], v[214:217], v[108:111]
	v_mfma_f32_16x16x32_bf16 v[92:95], v[184:187], v[230:233], v[92:95]
	v_mfma_f32_16x16x32_bf16 v[88:91], v[198:201], v[230:233], v[88:91]
	v_mfma_f32_16x16x32_bf16 v[78:81], v[198:201], v[238:241], v[78:81]
	v_mfma_f32_16x16x32_bf16 v[84:87], v[184:187], v[238:241], v[84:87]
	s_barrier
	s_add_i32 s82, s82, s52
	v_lshl_add_u64 v[224:225], s[64:65], 0, v[164:165]
	s_mov_b32 m0, s82
	ds_read_b128 v[202:205], v171 offset:16384
	ds_read_b128 v[206:209], v171 offset:17408
	ds_read_b128 v[210:213], v171 offset:18432
	ds_read_b128 v[214:217], v171 offset:19456
	ds_read_b128 v[218:221], v171 offset:20480
	ds_read_b128 v[230:233], v171 offset:21504
	ds_read_b128 v[234:237], v171 offset:22528
	ds_read_b128 v[238:241], v171 offset:23552
	global_load_lds_dwordx4 v164, s[64:65]
	s_add_i32 m0, s82, 0x2000
	s_add_u32 s82, s64, 0x40000
	v_lshl_add_u64 v[226:227], s[64:65], 0, v[168:169]
	s_addc_u32 s83, s65, 0
	s_add_i32 s90, s90, s52
	global_load_lds_dwordx4 v168, s[64:65]
	s_mov_b32 m0, s90
	v_lshl_add_u64 v[242:243], s[66:67], 0, v[162:163]
	global_load_lds_dwordx4 v164, s[82:83]
	s_add_i32 m0, s90, 0x2000
	v_lshl_add_u64 v[244:245], s[66:67], 0, v[166:167]
	global_load_lds_dwordx4 v168, s[82:83]
	s_mov_b32 m0, s53
	s_nop 0
	global_load_lds_dwordx4 v162, s[66:67]
	s_mov_b32 m0, s56
	s_nop 0
	global_load_lds_dwordx4 v166, s[66:67]
	s_waitcnt vmcnt(8)
	s_waitcnt lgkmcnt(0)
	s_barrier
; #define PG8_STAGE(bufoff, gbase, voff) do { _Pragma("unroll") for (int _i = 0; _i < 2; ++_i) \
;         __builtin_amdgcn_global_load_lds((const unsigned*)((const char*)(gbase) + (voff)[_i]), (LAS unsigned*)(lds + (bufoff) + ldsw + _i * 8192), 16, 0, 0); } while (0)
; #define PG8_LDA(dst, b, h) do { _Pragma("unroll") for (int m = 0; m < 4; ++m) _Pragma("unroll") for (int k = 0; k < 2; ++k) dst[m][k] = *(const LAS bf16x8*)(lds + PG8_SA(b, h) + aoff + m * 2048 + k * 1024); } while (0)
; #define PG8_LDB(dst, b, h) do { _Pragma("unroll") for (int n = 0; n < 2; ++n) _Pragma("unroll") for (int k = 0; k < 2; ++k) dst[n][k] = *(const LAS bf16x8*)(lds + PG8_SB(b, h) + boff + n * 2048 + k * 1024); } while (0)
; #define PG8_MMA(ai, bj, At, Bt) do { __builtin_amdgcn_s_setprio(1); _Pragma("unroll") for (int m = 0; m < 4; ++m) _Pragma("unroll") for (int n = 0; n < 2; ++n) _Pragma("unroll") for (int k = 0; k < 2; ++k) \
;         acc[ai][bj][m][n] = __builtin_amdgcn_mfma_f32_16x16x32_bf16(Bt[n][k], At[m][k], acc[ai][bj][m][n], 0, 0, 0); __builtin_amdgcn_s_setprio(0); } while (0)
; #define PG8_WAIT_V(n) asm volatile("s_waitcnt vmcnt(" #n ")" ::: "memory")
; #define PG8_WAIT_L(n) asm volatile("s_waitcnt lgkmcnt(" #n ")" ::: "memory")
; #define PG8_BAR __builtin_amdgcn_s_barrier()
; #define PG8_SCHED __builtin_amdgcn_sched_barrier(0)
; template <class Epi, class Sched>
; __device__ __forceinline__ void gemm_phase(LAS unsigned char* lds, const Gemm g, const Sched& S, const Epi& E, const int tid) {
;     ...
;             PG8_WAIT_V(8); PG8_WAIT_L(0); PG8_BAR; PG8_MMA(0, 0, At, B0); PG8_MMA(0, 1, At, B1); PG8_BAR; PG8_SCHED;
;             PG8_LDA(At, 0, 1); PG8_STAGE(PG8_SB(0, 0), b2, voffB); PG8_STAGE(PG8_SB(0, 1), b2 + hstep, voffB); PG8_STAGE(PG8_SA(0, 0), a2, voffA);
;             PG8_WAIT_V(8); PG8_WAIT_L(0); PG8_BAR; PG8_MMA(1, 0, At, B0); PG8_MMA(1, 1, At, B1); PG8_BAR; PG8_SCHED;
;             PG8_LDB(B0, 1, 0); PG8_LDB(B1, 1, 1); PG8_SCHED; PG8_LDA(At, 1, 0); PG8_STAGE(PG8_SA(0, 1), a2 + hstep, voffA);
;             PG8_WAIT_V(8); PG8_WAIT_L(0); PG8_BAR; PG8_MMA(0, 0, At, B0); PG8_MMA(0, 1, At, B1); PG8_BAR; PG8_SCHED;
	s_waitcnt lgkmcnt(0)
	v_mfma_f32_16x16x32_bf16 v[60:63], v[70:73], v[202:205], 0
	v_mfma_f32_16x16x32_bf16 v[56:59], v[172:175], v[202:205], 0
	v_mfma_f32_16x16x32_bf16 v[44:47], v[172:175], v[210:213], 0
	v_mfma_f32_16x16x32_bf16 v[52:55], v[70:73], v[210:213], 0
	v_mfma_f32_16x16x32_bf16 v[28:31], v[70:73], v[218:221], 0
	v_mfma_f32_16x16x32_bf16 v[24:27], v[172:175], v[218:221], 0
	v_mfma_f32_16x16x32_bf16 v[8:11], v[172:175], v[234:237], 0
	v_mfma_f32_16x16x32_bf16 v[16:19], v[70:73], v[234:237], 0
	v_mfma_f32_16x16x32_bf16 v[60:63], v[74:77], v[206:209], v[60:63]
	v_mfma_f32_16x16x32_bf16 v[56:59], v[176:179], v[206:209], v[56:59]
	v_mfma_f32_16x16x32_bf16 v[44:47], v[176:179], v[214:217], v[44:47]
	v_mfma_f32_16x16x32_bf16 v[52:55], v[74:77], v[214:217], v[52:55]
	v_mfma_f32_16x16x32_bf16 v[28:31], v[74:77], v[230:233], v[28:31]
	v_mfma_f32_16x16x32_bf16 v[24:27], v[176:179], v[230:233], v[24:27]
	v_mfma_f32_16x16x32_bf16 v[8:11], v[176:179], v[238:241], v[8:11]
	v_mfma_f32_16x16x32_bf16 v[16:19], v[74:77], v[238:241], v[16:19]
	v_mfma_f32_16x16x32_bf16 v[48:51], v[180:183], v[202:205], 0
	v_mfma_f32_16x16x32_bf16 v[40:43], v[188:191], v[202:205], 0
	v_mfma_f32_16x16x32_bf16 v[32:35], v[188:191], v[210:213], 0
	v_mfma_f32_16x16x32_bf16 v[36:39], v[180:183], v[210:213], 0
	v_mfma_f32_16x16x32_bf16 v[20:23], v[180:183], v[218:221], 0
	v_mfma_f32_16x16x32_bf16 v[12:15], v[188:191], v[218:221], 0
	v_mfma_f32_16x16x32_bf16 v[0:3], v[188:191], v[234:237], 0
	v_mfma_f32_16x16x32_bf16 v[4:7], v[180:183], v[234:237], 0
	v_mfma_f32_16x16x32_bf16 v[48:51], v[184:187], v[206:209], v[48:51]
	v_mfma_f32_16x16x32_bf16 v[40:43], v[198:201], v[206:209], v[40:43]
	v_mfma_f32_16x16x32_bf16 v[32:35], v[198:201], v[214:217], v[32:35]
	v_mfma_f32_16x16x32_bf16 v[36:39], v[184:187], v[214:217], v[36:39]
	v_mfma_f32_16x16x32_bf16 v[20:23], v[184:187], v[230:233], v[20:23]
	v_mfma_f32_16x16x32_bf16 v[12:15], v[198:201], v[230:233], v[12:15]
	v_mfma_f32_16x16x32_bf16 v[0:3], v[198:201], v[238:241], v[0:3]
	v_mfma_f32_16x16x32_bf16 v[4:7], v[184:187], v[238:241], v[4:7]
	s_barrier
	s_add_i32 s82, 0, 0x18000
	v_add_u32_e32 v69, s82, v154
	s_add_i32 s83, 0, 0x1c000
	ds_read_b128 v[70:73], v69
	ds_read_b128 v[74:77], v69 offset:1024
	ds_read_b128 v[172:175], v69 offset:2048
	ds_read_b128 v[176:179], v69 offset:3072
	v_add_u32_e32 v69, s83, v154
	ds_read_b128 v[180:183], v69
	ds_read_b128 v[184:187], v69 offset:1024
	ds_read_b128 v[188:191], v69 offset:2048
	ds_read_b128 v[198:201], v69 offset:3072
	s_add_u32 s66, s66, 0x40000
	s_addc_u32 s67, s67, 0
	s_mov_b32 m0, s57
	ds_read_b128 v[202:205], v171 offset:32768
	ds_read_b128 v[206:209], v171 offset:33792
	ds_read_b128 v[210:213], v171 offset:34816
	ds_read_b128 v[214:217], v171 offset:35840
	ds_read_b128 v[218:221], v171 offset:36864
	ds_read_b128 v[230:233], v171 offset:37888
	ds_read_b128 v[234:237], v171 offset:38912
	ds_read_b128 v[238:241], v171 offset:39936
	global_load_lds_dwordx4 v162, s[66:67]
	v_lshl_add_u64 v[82:83], s[66:67], 0, v[166:167]
	s_mov_b32 m0, s58
	s_nop 0
	global_load_lds_dwordx4 v166, s[66:67]
	s_waitcnt vmcnt(8)
	s_waitcnt lgkmcnt(0)
	s_barrier
	s_waitcnt lgkmcnt(0)
	v_mfma_f32_16x16x32_bf16 v[140:143], v[70:73], v[202:205], v[140:143]
	v_mfma_f32_16x16x32_bf16 v[136:139], v[172:175], v[202:205], v[136:139]
	v_mfma_f32_16x16x32_bf16 v[128:131], v[172:175], v[210:213], v[128:131]
	v_mfma_f32_16x16x32_bf16 v[132:135], v[70:73], v[210:213], v[132:135]
	v_mfma_f32_16x16x32_bf16 v[116:119], v[70:73], v[218:221], v[116:119]
	v_mfma_f32_16x16x32_bf16 v[112:115], v[172:175], v[218:221], v[112:115]
	v_mfma_f32_16x16x32_bf16 v[96:99], v[172:175], v[234:237], v[96:99]
	v_mfma_f32_16x16x32_bf16 v[100:103], v[70:73], v[234:237], v[100:103]
	v_mfma_f32_16x16x32_bf16 v[140:143], v[74:77], v[206:209], v[140:143]
	v_mfma_f32_16x16x32_bf16 v[136:139], v[176:179], v[206:209], v[136:139]
	v_mfma_f32_16x16x32_bf16 v[128:131], v[176:179], v[214:217], v[128:131]
	v_mfma_f32_16x16x32_bf16 v[132:135], v[74:77], v[214:217], v[132:135]
	v_mfma_f32_16x16x32_bf16 v[116:119], v[74:77], v[230:233], v[116:119]
	v_mfma_f32_16x16x32_bf16 v[112:115], v[176:179], v[230:233], v[112:115]
	v_mfma_f32_16x16x32_bf16 v[96:99], v[176:179], v[238:241], v[96:99]
	v_mfma_f32_16x16x32_bf16 v[100:103], v[74:77], v[238:241], v[100:103]
	v_mfma_f32_16x16x32_bf16 v[124:127], v[180:183], v[202:205], v[124:127]
	v_mfma_f32_16x16x32_bf16 v[120:123], v[188:191], v[202:205], v[120:123]
	v_mfma_f32_16x16x32_bf16 v[104:107], v[188:191], v[210:213], v[104:107]
	v_mfma_f32_16x16x32_bf16 v[108:111], v[180:183], v[210:213], v[108:111]
	v_mfma_f32_16x16x32_bf16 v[92:95], v[180:183], v[218:221], v[92:95]
	v_mfma_f32_16x16x32_bf16 v[88:91], v[188:191], v[218:221], v[88:91]
	v_mfma_f32_16x16x32_bf16 v[78:81], v[188:191], v[234:237], v[78:81]
	v_mfma_f32_16x16x32_bf16 v[82:85], v[180:183], v[234:237], v[84:87]
	v_mfma_f32_16x16x32_bf16 v[124:127], v[184:187], v[206:209], v[124:127]
	v_mfma_f32_16x16x32_bf16 v[120:123], v[198:201], v[206:209], v[120:123]
	v_mfma_f32_16x16x32_bf16 v[104:107], v[198:201], v[214:217], v[104:107]
	v_mfma_f32_16x16x32_bf16 v[108:111], v[184:187], v[214:217], v[108:111]
	v_mfma_f32_16x16x32_bf16 v[92:95], v[184:187], v[230:233], v[92:95]
	v_mfma_f32_16x16x32_bf16 v[88:91], v[198:201], v[230:233], v[88:91]
	v_mfma_f32_16x16x32_bf16 v[80:83], v[198:201], v[238:241], v[78:81]
	v_mfma_f32_16x16x32_bf16 v[84:87], v[184:187], v[238:241], v[82:85]
	s_barrier
; #define PG8_STAGE(bufoff, gbase, voff) do { _Pragma("unroll") for (int _i = 0; _i < 2; ++_i) \
;         __builtin_amdgcn_global_load_lds((const unsigned*)((const char*)(gbase) + (voff)[_i]), (LAS unsigned*)(lds + (bufoff) + ldsw + _i * 8192), 16, 0, 0); } while (0)
; #define PG8_LDA(dst, b, h) do { _Pragma("unroll") for (int m = 0; m < 4; ++m) _Pragma("unroll") for (int k = 0; k < 2; ++k) dst[m][k] = *(const LAS bf16x8*)(lds + PG8_SA(b, h) + aoff + m * 2048 + k * 1024); } while (0)
; #define PG8_LDB(dst, b, h) do { _Pragma("unroll") for (int n = 0; n < 2; ++n) _Pragma("unroll") for (int k = 0; k < 2; ++k) dst[n][k] = *(const LAS bf16x8*)(lds + PG8_SB(b, h) + boff + n * 2048 + k * 1024); } while (0)
; #define PG8_WAIT_V(n) asm volatile("s_waitcnt vmcnt(" #n ")" ::: "memory")
; #define PG8_BAR __builtin_amdgcn_s_barrier()
; template <class Epi, class Sched>
; __device__ __forceinline__ void gemm_phase(LAS unsigned char* lds, const Gemm g, const Sched& S, const Epi& E, const int tid) {
;     ...
;         for (int t = 0; t < nt; t += 2) {
;             const bool last = (t == nt - 2);
;             const char* a1 = cA + (size_t)(t + 1) * kstep;
;             const char* a2 = last ? nA : cA + (size_t)(t + 2) * kstep; const char* b2 = last ? nB : cB + (size_t)(t + 2) * kstep;
;             const char* a3 = a2 + kstep; const char* b3 = b2 + kstep;
;             PG8_LDB(B0, 0, 0); PG8_LDB(B1, 0, 1); PG8_SCHED; PG8_LDA(At, 0, 0); PG8_STAGE(PG8_SA(1, 1), a1 + hstep, voffA);
;             PG8_WAIT_V(8); PG8_WAIT_L(0); PG8_BAR; PG8_MMA(0, 0, At, B0); PG8_MMA(0, 1, At, B1); PG8_BAR; PG8_SCHED;
;             PG8_LDA(At, 0, 1); PG8_STAGE(PG8_SB(0, 0), b2, voffB); PG8_STAGE(PG8_SB(0, 1), b2 + hstep, voffB); PG8_STAGE(PG8_SA(0, 0), a2, voffA);
;             PG8_WAIT_V(8); PG8_WAIT_L(0); PG8_BAR; PG8_MMA(1, 0, At, B0); PG8_MMA(1, 1, At, B1); PG8_BAR; PG8_SCHED;
;             PG8_LDB(B0, 1, 0); PG8_LDB(B1, 1, 1); PG8_SCHED; PG8_LDA(At, 1, 0); PG8_STAGE(PG8_SA(0, 1), a2 + hstep, voffA);
;             PG8_WAIT_V(8); PG8_WAIT_L(0); PG8_BAR; PG8_MMA(0, 0, At, B0); PG8_MMA(0, 1, At, B1); PG8_BAR; PG8_SCHED;
;             PG8_LDA(At, 1, 1); PG8_STAGE(PG8_SB(1, 0), b3, voffB); PG8_STAGE(PG8_SB(1, 1), b3 + hstep, voffB); PG8_STAGE(PG8_SA(1, 0), a3, voffA);
;             PG8_WAIT_V(8); PG8_WAIT_L(0); PG8_BAR; PG8_MMA(1, 0, At, B0); PG8_MMA(1, 1, At, B1); PG8_BAR; PG8_SCHED;
	s_add_i32 s66, s82, s52
	v_lshl_add_u64 v[78:79], v[224:225], 0, s[68:69]
	s_mov_b32 m0, s66
	ds_read_b128 v[202:205], v171 offset:49152
	ds_read_b128 v[206:209], v171 offset:50176
	ds_read_b128 v[210:213], v171 offset:51200
	ds_read_b128 v[214:217], v171 offset:52224
	ds_read_b128 v[218:221], v171 offset:53248
	ds_read_b128 v[230:233], v171 offset:54272
	ds_read_b128 v[234:237], v171 offset:55296
	ds_read_b128 v[238:241], v171 offset:56320
	global_load_lds_dwordx4 v[78:79], off
	s_add_i32 m0, s66, 0x2000
	s_add_u32 s64, s64, 0x40080
	v_lshl_add_u64 v[78:79], v[226:227], 0, s[68:69]
	s_addc_u32 s65, s65, 0
	s_add_i32 s66, s83, s52
	global_load_lds_dwordx4 v[78:79], off
	s_mov_b32 m0, s66
	s_nop 0
	global_load_lds_dwordx4 v164, s[64:65]
	s_add_i32 m0, s66, 0x2000
	s_nop 0
	global_load_lds_dwordx4 v168, s[64:65]
	v_lshl_add_u64 v[78:79], v[242:243], 0, s[68:69]
	s_mov_b32 m0, s61
	s_nop 0
	global_load_lds_dwordx4 v[78:79], off
	v_lshl_add_u64 v[78:79], v[244:245], 0, s[68:69]
	s_mov_b32 m0, s70
	s_nop 0
	global_load_lds_dwordx4 v[78:79], off
	s_waitcnt vmcnt(8)
	s_waitcnt lgkmcnt(0)
	s_barrier
	s_waitcnt lgkmcnt(0)
	v_mfma_f32_16x16x32_bf16 v[60:63], v[70:73], v[202:205], v[60:63]
	v_mfma_f32_16x16x32_bf16 v[56:59], v[172:175], v[202:205], v[56:59]
	v_mfma_f32_16x16x32_bf16 v[44:47], v[172:175], v[210:213], v[44:47]
	v_mfma_f32_16x16x32_bf16 v[52:55], v[70:73], v[210:213], v[52:55]
	v_mfma_f32_16x16x32_bf16 v[28:31], v[70:73], v[218:221], v[28:31]
	v_mfma_f32_16x16x32_bf16 v[24:27], v[172:175], v[218:221], v[24:27]
	v_mfma_f32_16x16x32_bf16 v[8:11], v[172:175], v[234:237], v[8:11]
	v_mfma_f32_16x16x32_bf16 v[16:19], v[70:73], v[234:237], v[16:19]
	v_mfma_f32_16x16x32_bf16 v[60:63], v[74:77], v[206:209], v[60:63]
	v_mfma_f32_16x16x32_bf16 v[56:59], v[176:179], v[206:209], v[56:59]
	v_mfma_f32_16x16x32_bf16 v[44:47], v[176:179], v[214:217], v[44:47]
	v_mfma_f32_16x16x32_bf16 v[52:55], v[74:77], v[214:217], v[52:55]
	v_mfma_f32_16x16x32_bf16 v[28:31], v[74:77], v[230:233], v[28:31]
	v_mfma_f32_16x16x32_bf16 v[24:27], v[176:179], v[230:233], v[24:27]
	v_mfma_f32_16x16x32_bf16 v[8:11], v[176:179], v[238:241], v[8:11]
	v_mfma_f32_16x16x32_bf16 v[16:19], v[74:77], v[238:241], v[16:19]
	v_mfma_f32_16x16x32_bf16 v[48:51], v[180:183], v[202:205], v[48:51]
	v_mfma_f32_16x16x32_bf16 v[40:43], v[188:191], v[202:205], v[40:43]
	v_mfma_f32_16x16x32_bf16 v[32:35], v[188:191], v[210:213], v[32:35]
	v_mfma_f32_16x16x32_bf16 v[36:39], v[180:183], v[210:213], v[36:39]
	v_mfma_f32_16x16x32_bf16 v[20:23], v[180:183], v[218:221], v[20:23]
	v_mfma_f32_16x16x32_bf16 v[12:15], v[188:191], v[218:221], v[12:15]
	v_mfma_f32_16x16x32_bf16 v[0:3], v[188:191], v[234:237], v[0:3]
	v_mfma_f32_16x16x32_bf16 v[4:7], v[180:183], v[234:237], v[4:7]
	v_mfma_f32_16x16x32_bf16 v[48:51], v[184:187], v[206:209], v[48:51]
	v_mfma_f32_16x16x32_bf16 v[40:43], v[198:201], v[206:209], v[40:43]
	v_mfma_f32_16x16x32_bf16 v[32:35], v[198:201], v[214:217], v[32:35]
	v_mfma_f32_16x16x32_bf16 v[36:39], v[184:187], v[214:217], v[36:39]
	v_mfma_f32_16x16x32_bf16 v[20:23], v[184:187], v[230:233], v[20:23]
	v_mfma_f32_16x16x32_bf16 v[12:15], v[198:201], v[230:233], v[12:15]
	v_mfma_f32_16x16x32_bf16 v[0:3], v[198:201], v[238:241], v[0:3]
	v_mfma_f32_16x16x32_bf16 v[4:7], v[184:187], v[238:241], v[4:7]
	s_barrier
	s_add_i32 s81, s81, 2
	s_add_u32 s62, s62, 0x100
	s_addc_u32 s63, s63, 0
	s_add_u32 s78, s78, 0x100
	s_addc_u32 s79, s79, 0
	s_cmp_gt_u32 s81, 13
.LBB0_326:
	s_add_u32 s64, s62, 0xfffc0080
	s_addc_u32 s65, s63, -1
	s_add_i32 s82, 0, 0x10000
	s_cmp_eq_u32 s81, 12
	s_cselect_b32 s67, s39, s65
	s_cselect_b32 s66, s74, s64
	v_add_u32_e32 v69, s82, v154
	s_cselect_b32 s65, s23, s79
	s_cselect_b32 s64, s75, s78
	s_add_i32 s90, 0, 0x14000
	ds_read_b128 v[70:73], v69
	ds_read_b128 v[74:77], v69 offset:1024
	ds_read_b128 v[172:175], v69 offset:2048
	ds_read_b128 v[176:179], v69 offset:3072
	v_add_u32_e32 v69, s90, v154
	ds_read_b128 v[180:183], v69
	ds_read_b128 v[184:187], v69 offset:1024
	ds_read_b128 v[188:191], v69 offset:2048
	ds_read_b128 v[198:201], v69 offset:3072
	s_add_i32 m0, s53, 0xc000
	ds_read_b128 v[202:205], v171
	ds_read_b128 v[206:209], v171 offset:1024
	ds_read_b128 v[210:213], v171 offset:2048
	ds_read_b128 v[214:217], v171 offset:3072
	ds_read_b128 v[218:221], v171 offset:4096
	ds_read_b128 v[230:233], v171 offset:5120
	ds_read_b128 v[234:237], v171 offset:6144
	ds_read_b128 v[238:241], v171 offset:7168
	global_load_lds_dwordx4 v144, s[62:63]
	v_lshl_add_u64 v[78:79], s[62:63], 0, v[146:147]
	s_add_i32 m0, s53, 0xe000
	s_nop 0
	global_load_lds_dwordx4 v146, s[62:63]
	s_waitcnt vmcnt(8)
	s_waitcnt lgkmcnt(0)
	s_barrier
; #define PG8_STAGE(bufoff, gbase, voff) do { _Pragma("unroll") for (int _i = 0; _i < 2; ++_i) \
;         __builtin_amdgcn_global_load_lds((const unsigned*)((const char*)(gbase) + (voff)[_i]), (LAS unsigned*)(lds + (bufoff) + ldsw + _i * 8192), 16, 0, 0); } while (0)
; #define PG8_LDA(dst, b, h) do { _Pragma("unroll") for (int m = 0; m < 4; ++m) _Pragma("unroll") for (int k = 0; k < 2; ++k) dst[m][k] = *(const LAS bf16x8*)(lds + PG8_SA(b, h) + aoff + m * 2048 + k * 1024); } while (0)
; #define PG8_MMA(ai, bj, At, Bt) do { __builtin_amdgcn_s_setprio(1); _Pragma("unroll") for (int m = 0; m < 4; ++m) _Pragma("unroll") for (int n = 0; n < 2; ++n) _Pragma("unroll") for (int k = 0; k < 2; ++k) \
;         acc[ai][bj][m][n] = __builtin_amdgcn_mfma_f32_16x16x32_bf16(Bt[n][k], At[m][k], acc[ai][bj][m][n], 0, 0, 0); __builtin_amdgcn_s_setprio(0); } while (0)
; #define PG8_WAIT_V(n) asm volatile("s_waitcnt vmcnt(" #n ")" ::: "memory")
; #define PG8_WAIT_L(n) asm volatile("s_waitcnt lgkmcnt(" #n ")" ::: "memory")
; #define PG8_BAR __builtin_amdgcn_s_barrier()
; #define PG8_SCHED __builtin_amdgcn_sched_barrier(0)
; template <class Epi, class Sched>
; __device__ __forceinline__ void gemm_phase(LAS unsigned char* lds, const Gemm g, const Sched& S, const Epi& E, const int tid) {
;     ...
;             PG8_WAIT_V(8); PG8_WAIT_L(0); PG8_BAR; PG8_MMA(0, 0, At, B0); PG8_MMA(0, 1, At, B1); PG8_BAR; PG8_SCHED;
;             PG8_LDA(At, 0, 1); PG8_STAGE(PG8_SB(0, 0), b2, voffB); PG8_STAGE(PG8_SB(0, 1), b2 + hstep, voffB); PG8_STAGE(PG8_SA(0, 0), a2, voffA);
;             PG8_WAIT_V(8); PG8_WAIT_L(0); PG8_BAR; PG8_MMA(1, 0, At, B0); PG8_MMA(1, 1, At, B1); PG8_BAR; PG8_SCHED;
	s_waitcnt lgkmcnt(0)
	v_mfma_f32_16x16x32_bf16 v[140:143], v[70:73], v[202:205], v[140:143]
	v_mfma_f32_16x16x32_bf16 v[136:139], v[172:175], v[202:205], v[136:139]
	v_mfma_f32_16x16x32_bf16 v[128:131], v[172:175], v[210:213], v[128:131]
	v_mfma_f32_16x16x32_bf16 v[132:135], v[70:73], v[210:213], v[132:135]
	v_mfma_f32_16x16x32_bf16 v[116:119], v[70:73], v[218:221], v[116:119]
	v_mfma_f32_16x16x32_bf16 v[112:115], v[172:175], v[218:221], v[112:115]
	v_mfma_f32_16x16x32_bf16 v[96:99], v[172:175], v[234:237], v[96:99]
	v_mfma_f32_16x16x32_bf16 v[100:103], v[70:73], v[234:237], v[100:103]
	v_mfma_f32_16x16x32_bf16 v[140:143], v[74:77], v[206:209], v[140:143]
	v_mfma_f32_16x16x32_bf16 v[136:139], v[176:179], v[206:209], v[136:139]
	v_mfma_f32_16x16x32_bf16 v[128:131], v[176:179], v[214:217], v[128:131]
	v_mfma_f32_16x16x32_bf16 v[132:135], v[74:77], v[214:217], v[132:135]
	v_mfma_f32_16x16x32_bf16 v[116:119], v[74:77], v[230:233], v[116:119]
	v_mfma_f32_16x16x32_bf16 v[112:115], v[176:179], v[230:233], v[112:115]
	v_mfma_f32_16x16x32_bf16 v[96:99], v[176:179], v[238:241], v[96:99]
	v_mfma_f32_16x16x32_bf16 v[100:103], v[74:77], v[238:241], v[100:103]
	v_mfma_f32_16x16x32_bf16 v[124:127], v[180:183], v[202:205], v[124:127]
	v_mfma_f32_16x16x32_bf16 v[120:123], v[188:191], v[202:205], v[120:123]
	v_mfma_f32_16x16x32_bf16 v[104:107], v[188:191], v[210:213], v[104:107]
	v_mfma_f32_16x16x32_bf16 v[108:111], v[180:183], v[210:213], v[108:111]
	v_mfma_f32_16x16x32_bf16 v[92:95], v[180:183], v[218:221], v[92:95]
	v_mfma_f32_16x16x32_bf16 v[88:91], v[188:191], v[218:221], v[88:91]
	v_mfma_f32_16x16x32_bf16 v[78:81], v[188:191], v[234:237], v[80:83]
	v_mfma_f32_16x16x32_bf16 v[84:87], v[180:183], v[234:237], v[84:87]
	v_mfma_f32_16x16x32_bf16 v[124:127], v[184:187], v[206:209], v[124:127]
	v_mfma_f32_16x16x32_bf16 v[120:123], v[198:201], v[206:209], v[120:123]
	v_mfma_f32_16x16x32_bf16 v[104:107], v[198:201], v[214:217], v[104:107]
	v_mfma_f32_16x16x32_bf16 v[108:111], v[184:187], v[214:217], v[108:111]
	v_mfma_f32_16x16x32_bf16 v[92:95], v[184:187], v[230:233], v[92:95]
	v_mfma_f32_16x16x32_bf16 v[88:91], v[198:201], v[230:233], v[88:91]
	v_mfma_f32_16x16x32_bf16 v[78:81], v[198:201], v[238:241], v[78:81]
	v_mfma_f32_16x16x32_bf16 v[84:87], v[184:187], v[238:241], v[84:87]
	s_barrier
	s_add_i32 s82, s82, s52
	v_lshl_add_u64 v[224:225], s[64:65], 0, v[164:165]
	s_mov_b32 m0, s82
	ds_read_b128 v[202:205], v171 offset:16384
	ds_read_b128 v[206:209], v171 offset:17408
	ds_read_b128 v[210:213], v171 offset:18432
	ds_read_b128 v[214:217], v171 offset:19456
	ds_read_b128 v[218:221], v171 offset:20480
	ds_read_b128 v[230:233], v171 offset:21504
	ds_read_b128 v[234:237], v171 offset:22528
	ds_read_b128 v[238:241], v171 offset:23552
	global_load_lds_dwordx4 v164, s[64:65]
	s_add_i32 m0, s82, 0x2000
	s_add_u32 s82, s64, 0x40000
	v_lshl_add_u64 v[226:227], s[64:65], 0, v[168:169]
	s_addc_u32 s83, s65, 0
	s_add_i32 s90, s90, s52
	global_load_lds_dwordx4 v168, s[64:65]
	s_mov_b32 m0, s90
	v_lshl_add_u64 v[242:243], s[66:67], 0, v[162:163]
	global_load_lds_dwordx4 v164, s[82:83]
	s_add_i32 m0, s90, 0x2000
	v_lshl_add_u64 v[244:245], s[66:67], 0, v[166:167]
	global_load_lds_dwordx4 v168, s[82:83]
	s_mov_b32 m0, s53
	s_nop 0
	global_load_lds_dwordx4 v162, s[66:67]
	s_mov_b32 m0, s56
	s_nop 0
	global_load_lds_dwordx4 v166, s[66:67]
	s_waitcnt vmcnt(8)
	s_waitcnt lgkmcnt(0)
	s_barrier
	s_waitcnt lgkmcnt(0)
	v_mfma_f32_16x16x32_bf16 v[60:63], v[70:73], v[202:205], v[60:63]
	v_mfma_f32_16x16x32_bf16 v[56:59], v[172:175], v[202:205], v[56:59]
	v_mfma_f32_16x16x32_bf16 v[44:47], v[172:175], v[210:213], v[44:47]
	v_mfma_f32_16x16x32_bf16 v[52:55], v[70:73], v[210:213], v[52:55]
	v_mfma_f32_16x16x32_bf16 v[28:31], v[70:73], v[218:221], v[28:31]
	v_mfma_f32_16x16x32_bf16 v[24:27], v[172:175], v[218:221], v[24:27]
	v_mfma_f32_16x16x32_bf16 v[8:11], v[172:175], v[234:237], v[8:11]
	v_mfma_f32_16x16x32_bf16 v[16:19], v[70:73], v[234:237], v[16:19]
	v_mfma_f32_16x16x32_bf16 v[60:63], v[74:77], v[206:209], v[60:63]
	v_mfma_f32_16x16x32_bf16 v[56:59], v[176:179], v[206:209], v[56:59]
	v_mfma_f32_16x16x32_bf16 v[44:47], v[176:179], v[214:217], v[44:47]
	v_mfma_f32_16x16x32_bf16 v[52:55], v[74:77], v[214:217], v[52:55]
	v_mfma_f32_16x16x32_bf16 v[28:31], v[74:77], v[230:233], v[28:31]
	v_mfma_f32_16x16x32_bf16 v[24:27], v[176:179], v[230:233], v[24:27]
	v_mfma_f32_16x16x32_bf16 v[8:11], v[176:179], v[238:241], v[8:11]
	v_mfma_f32_16x16x32_bf16 v[16:19], v[74:77], v[238:241], v[16:19]
	v_mfma_f32_16x16x32_bf16 v[48:51], v[180:183], v[202:205], v[48:51]
	v_mfma_f32_16x16x32_bf16 v[40:43], v[188:191], v[202:205], v[40:43]
	v_mfma_f32_16x16x32_bf16 v[32:35], v[188:191], v[210:213], v[32:35]
	v_mfma_f32_16x16x32_bf16 v[36:39], v[180:183], v[210:213], v[36:39]
	v_mfma_f32_16x16x32_bf16 v[20:23], v[180:183], v[218:221], v[20:23]
	v_mfma_f32_16x16x32_bf16 v[12:15], v[188:191], v[218:221], v[12:15]
	v_mfma_f32_16x16x32_bf16 v[0:3], v[188:191], v[234:237], v[0:3]
	v_mfma_f32_16x16x32_bf16 v[4:7], v[180:183], v[234:237], v[4:7]
	v_mfma_f32_16x16x32_bf16 v[48:51], v[184:187], v[206:209], v[48:51]
	v_mfma_f32_16x16x32_bf16 v[40:43], v[198:201], v[206:209], v[40:43]
	v_mfma_f32_16x16x32_bf16 v[32:35], v[198:201], v[214:217], v[32:35]
	v_mfma_f32_16x16x32_bf16 v[36:39], v[184:187], v[214:217], v[36:39]
	v_mfma_f32_16x16x32_bf16 v[20:23], v[184:187], v[230:233], v[20:23]
	v_mfma_f32_16x16x32_bf16 v[12:15], v[198:201], v[230:233], v[12:15]
	v_mfma_f32_16x16x32_bf16 v[0:3], v[198:201], v[238:241], v[0:3]
	v_mfma_f32_16x16x32_bf16 v[4:7], v[184:187], v[238:241], v[4:7]
	s_barrier
; #define PG8_STAGE(bufoff, gbase, voff) do { _Pragma("unroll") for (int _i = 0; _i < 2; ++_i) \
;         __builtin_amdgcn_global_load_lds((const unsigned*)((const char*)(gbase) + (voff)[_i]), (LAS unsigned*)(lds + (bufoff) + ldsw + _i * 8192), 16, 0, 0); } while (0)
; #define PG8_LDA(dst, b, h) do { _Pragma("unroll") for (int m = 0; m < 4; ++m) _Pragma("unroll") for (int k = 0; k < 2; ++k) dst[m][k] = *(const LAS bf16x8*)(lds + PG8_SA(b, h) + aoff + m * 2048 + k * 1024); } while (0)
; #define PG8_LDB(dst, b, h) do { _Pragma("unroll") for (int n = 0; n < 2; ++n) _Pragma("unroll") for (int k = 0; k < 2; ++k) dst[n][k] = *(const LAS bf16x8*)(lds + PG8_SB(b, h) + boff + n * 2048 + k * 1024); } while (0)
; #define PG8_MMA(ai, bj, At, Bt) do { __builtin_amdgcn_s_setprio(1); _Pragma("unroll") for (int m = 0; m < 4; ++m) _Pragma("unroll") for (int n = 0; n < 2; ++n) _Pragma("unroll") for (int k = 0; k < 2; ++k) \
;         acc[ai][bj][m][n] = __builtin_amdgcn_mfma_f32_16x16x32_bf16(Bt[n][k], At[m][k], acc[ai][bj][m][n], 0, 0, 0); __builtin_amdgcn_s_setprio(0); } while (0)
; #define PG8_WAIT_V(n) asm volatile("s_waitcnt vmcnt(" #n ")" ::: "memory")
; #define PG8_WAIT_L(n) asm volatile("s_waitcnt lgkmcnt(" #n ")" ::: "memory")
; #define PG8_BAR __builtin_amdgcn_s_barrier()
; #define PG8_SCHED __builtin_amdgcn_sched_barrier(0)
; template <class Epi, class Sched>
; __device__ __forceinline__ void gemm_phase(LAS unsigned char* lds, const Gemm g, const Sched& S, const Epi& E, const int tid) {
;     ...
;             PG8_LDB(B0, 1, 0); PG8_LDB(B1, 1, 1); PG8_SCHED; PG8_LDA(At, 1, 0); PG8_STAGE(PG8_SA(0, 1), a2 + hstep, voffA);
;             PG8_WAIT_V(8); PG8_WAIT_L(0); PG8_BAR; PG8_MMA(0, 0, At, B0); PG8_MMA(0, 1, At, B1); PG8_BAR; PG8_SCHED;
;             PG8_LDA(At, 1, 1); PG8_STAGE(PG8_SB(1, 0), b3, voffB); PG8_STAGE(PG8_SB(1, 1), b3 + hstep, voffB); PG8_STAGE(PG8_SA(1, 0), a3, voffA);
;             PG8_WAIT_V(8); PG8_WAIT_L(0); PG8_BAR; PG8_MMA(1, 0, At, B0); PG8_MMA(1, 1, At, B1); PG8_BAR; PG8_SCHED;
;         }
	s_add_i32 s82, 0, 0x18000
	v_add_u32_e32 v69, s82, v154
	s_add_i32 s83, 0, 0x1c000
	ds_read_b128 v[70:73], v69
	ds_read_b128 v[74:77], v69 offset:1024
	ds_read_b128 v[172:175], v69 offset:2048
	ds_read_b128 v[176:179], v69 offset:3072
	v_add_u32_e32 v69, s83, v154
	ds_read_b128 v[180:183], v69
	ds_read_b128 v[184:187], v69 offset:1024
	ds_read_b128 v[188:191], v69 offset:2048
	ds_read_b128 v[198:201], v69 offset:3072
	s_add_u32 s66, s66, 0x40000
	s_addc_u32 s67, s67, 0
	s_mov_b32 m0, s57
	ds_read_b128 v[202:205], v171 offset:32768
	ds_read_b128 v[206:209], v171 offset:33792
	ds_read_b128 v[210:213], v171 offset:34816
	ds_read_b128 v[214:217], v171 offset:35840
	ds_read_b128 v[218:221], v171 offset:36864
	ds_read_b128 v[230:233], v171 offset:37888
	ds_read_b128 v[234:237], v171 offset:38912
	ds_read_b128 v[238:241], v171 offset:39936
	global_load_lds_dwordx4 v162, s[66:67]
	v_lshl_add_u64 v[82:83], s[66:67], 0, v[166:167]
	s_mov_b32 m0, s58
	s_nop 0
	global_load_lds_dwordx4 v166, s[66:67]
	s_waitcnt vmcnt(8)
	s_waitcnt lgkmcnt(0)
	s_barrier
	s_waitcnt lgkmcnt(0)
	v_mfma_f32_16x16x32_bf16 v[140:143], v[70:73], v[202:205], v[140:143]
	v_mfma_f32_16x16x32_bf16 v[136:139], v[172:175], v[202:205], v[136:139]
	v_mfma_f32_16x16x32_bf16 v[128:131], v[172:175], v[210:213], v[128:131]
	v_mfma_f32_16x16x32_bf16 v[132:135], v[70:73], v[210:213], v[132:135]
	v_mfma_f32_16x16x32_bf16 v[116:119], v[70:73], v[218:221], v[116:119]
	v_mfma_f32_16x16x32_bf16 v[112:115], v[172:175], v[218:221], v[112:115]
	v_mfma_f32_16x16x32_bf16 v[96:99], v[172:175], v[234:237], v[96:99]
	v_mfma_f32_16x16x32_bf16 v[100:103], v[70:73], v[234:237], v[100:103]
	v_mfma_f32_16x16x32_bf16 v[140:143], v[74:77], v[206:209], v[140:143]
	v_mfma_f32_16x16x32_bf16 v[136:139], v[176:179], v[206:209], v[136:139]
	v_mfma_f32_16x16x32_bf16 v[128:131], v[176:179], v[214:217], v[128:131]
	v_mfma_f32_16x16x32_bf16 v[132:135], v[74:77], v[214:217], v[132:135]
	v_mfma_f32_16x16x32_bf16 v[116:119], v[74:77], v[230:233], v[116:119]
	v_mfma_f32_16x16x32_bf16 v[112:115], v[176:179], v[230:233], v[112:115]
	v_mfma_f32_16x16x32_bf16 v[96:99], v[176:179], v[238:241], v[96:99]
	v_mfma_f32_16x16x32_bf16 v[100:103], v[74:77], v[238:241], v[100:103]
	v_mfma_f32_16x16x32_bf16 v[124:127], v[180:183], v[202:205], v[124:127]
	v_mfma_f32_16x16x32_bf16 v[120:123], v[188:191], v[202:205], v[120:123]
	v_mfma_f32_16x16x32_bf16 v[104:107], v[188:191], v[210:213], v[104:107]
	v_mfma_f32_16x16x32_bf16 v[108:111], v[180:183], v[210:213], v[108:111]
	v_mfma_f32_16x16x32_bf16 v[92:95], v[180:183], v[218:221], v[92:95]
	v_mfma_f32_16x16x32_bf16 v[88:91], v[188:191], v[218:221], v[88:91]
	v_mfma_f32_16x16x32_bf16 v[78:81], v[188:191], v[234:237], v[78:81]
	v_mfma_f32_16x16x32_bf16 v[82:85], v[180:183], v[234:237], v[84:87]
	v_mfma_f32_16x16x32_bf16 v[124:127], v[184:187], v[206:209], v[124:127]
	v_mfma_f32_16x16x32_bf16 v[120:123], v[198:201], v[206:209], v[120:123]
	v_mfma_f32_16x16x32_bf16 v[104:107], v[198:201], v[214:217], v[104:107]
	v_mfma_f32_16x16x32_bf16 v[108:111], v[184:187], v[214:217], v[108:111]
	v_mfma_f32_16x16x32_bf16 v[92:95], v[184:187], v[230:233], v[92:95]
	v_mfma_f32_16x16x32_bf16 v[88:91], v[198:201], v[230:233], v[88:91]
	v_mfma_f32_16x16x32_bf16 v[80:83], v[198:201], v[238:241], v[78:81]
	v_mfma_f32_16x16x32_bf16 v[84:87], v[184:187], v[238:241], v[82:85]
	s_barrier
	s_add_i32 s66, s82, s52
	v_lshl_add_u64 v[78:79], v[224:225], 0, s[68:69]
	s_mov_b32 m0, s66
	ds_read_b128 v[202:205], v171 offset:49152
	ds_read_b128 v[206:209], v171 offset:50176
	ds_read_b128 v[210:213], v171 offset:51200
	ds_read_b128 v[214:217], v171 offset:52224
	ds_read_b128 v[218:221], v171 offset:53248
	ds_read_b128 v[230:233], v171 offset:54272
	ds_read_b128 v[234:237], v171 offset:55296
	ds_read_b128 v[238:241], v171 offset:56320
	global_load_lds_dwordx4 v[78:79], off
	s_add_i32 m0, s66, 0x2000
	s_add_u32 s64, s64, 0x40080
	v_lshl_add_u64 v[78:79], v[226:227], 0, s[68:69]
	s_addc_u32 s65, s65, 0
	s_add_i32 s66, s83, s52
	global_load_lds_dwordx4 v[78:79], off
	s_mov_b32 m0, s66
	s_nop 0
	global_load_lds_dwordx4 v164, s[64:65]
	s_add_i32 m0, s66, 0x2000
	s_nop 0
	global_load_lds_dwordx4 v168, s[64:65]
	v_lshl_add_u64 v[78:79], v[242:243], 0, s[68:69]
	s_mov_b32 m0, s61
	s_nop 0
	global_load_lds_dwordx4 v[78:79], off
	v_lshl_add_u64 v[78:79], v[244:245], 0, s[68:69]
	s_mov_b32 m0, s70
	s_nop 0
	global_load_lds_dwordx4 v[78:79], off
	s_waitcnt vmcnt(8)
	s_waitcnt lgkmcnt(0)
	s_barrier
	s_waitcnt lgkmcnt(0)
	v_mfma_f32_16x16x32_bf16 v[60:63], v[70:73], v[202:205], v[60:63]
	v_mfma_f32_16x16x32_bf16 v[56:59], v[172:175], v[202:205], v[56:59]
	v_mfma_f32_16x16x32_bf16 v[44:47], v[172:175], v[210:213], v[44:47]
	v_mfma_f32_16x16x32_bf16 v[52:55], v[70:73], v[210:213], v[52:55]
	v_mfma_f32_16x16x32_bf16 v[28:31], v[70:73], v[218:221], v[28:31]
	v_mfma_f32_16x16x32_bf16 v[24:27], v[172:175], v[218:221], v[24:27]
	v_mfma_f32_16x16x32_bf16 v[8:11], v[172:175], v[234:237], v[8:11]
	v_mfma_f32_16x16x32_bf16 v[16:19], v[70:73], v[234:237], v[16:19]
	v_mfma_f32_16x16x32_bf16 v[60:63], v[74:77], v[206:209], v[60:63]
	v_mfma_f32_16x16x32_bf16 v[56:59], v[176:179], v[206:209], v[56:59]
	v_mfma_f32_16x16x32_bf16 v[44:47], v[176:179], v[214:217], v[44:47]
	v_mfma_f32_16x16x32_bf16 v[52:55], v[74:77], v[214:217], v[52:55]
	v_mfma_f32_16x16x32_bf16 v[28:31], v[74:77], v[230:233], v[28:31]
	v_mfma_f32_16x16x32_bf16 v[24:27], v[176:179], v[230:233], v[24:27]
	v_mfma_f32_16x16x32_bf16 v[8:11], v[176:179], v[238:241], v[8:11]
	v_mfma_f32_16x16x32_bf16 v[16:19], v[74:77], v[238:241], v[16:19]
	v_mfma_f32_16x16x32_bf16 v[48:51], v[180:183], v[202:205], v[48:51]
	v_mfma_f32_16x16x32_bf16 v[40:43], v[188:191], v[202:205], v[40:43]
	v_mfma_f32_16x16x32_bf16 v[32:35], v[188:191], v[210:213], v[32:35]
	v_mfma_f32_16x16x32_bf16 v[36:39], v[180:183], v[210:213], v[36:39]
	v_mfma_f32_16x16x32_bf16 v[20:23], v[180:183], v[218:221], v[20:23]
	v_mfma_f32_16x16x32_bf16 v[12:15], v[188:191], v[218:221], v[12:15]
	v_mfma_f32_16x16x32_bf16 v[0:3], v[188:191], v[234:237], v[0:3]
	v_mfma_f32_16x16x32_bf16 v[4:7], v[180:183], v[234:237], v[4:7]
	v_mfma_f32_16x16x32_bf16 v[48:51], v[184:187], v[206:209], v[48:51]
	v_mfma_f32_16x16x32_bf16 v[40:43], v[198:201], v[206:209], v[40:43]
	v_mfma_f32_16x16x32_bf16 v[32:35], v[198:201], v[214:217], v[32:35]
	v_mfma_f32_16x16x32_bf16 v[36:39], v[184:187], v[214:217], v[36:39]
	v_mfma_f32_16x16x32_bf16 v[20:23], v[184:187], v[230:233], v[20:23]
	v_mfma_f32_16x16x32_bf16 v[12:15], v[198:201], v[230:233], v[12:15]
	v_mfma_f32_16x16x32_bf16 v[0:3], v[198:201], v[238:241], v[0:3]
	v_mfma_f32_16x16x32_bf16 v[4:7], v[184:187], v[238:241], v[4:7]
	s_barrier
	s_add_i32 s81, s81, 2
	s_add_u32 s62, s62, 0x100
	s_addc_u32 s63, s63, 0
	s_add_u32 s78, s78, 0x100
	s_addc_u32 s79, s79, 0
	s_cmp_gt_u32 s81, 13
	s_cbranch_scc0 .LBB0_326
	s_and_b64 vcc, exec, s[8:9]
	s_cbranch_vccz .LBB0_329
	s_barrier

; #define PG8_STAGE(bufoff, gbase, voff) do { _Pragma("unroll") for (int _i = 0; _i < 2; ++_i) \
;         __builtin_amdgcn_global_load_lds((const unsigned*)((const char*)(gbase) + (voff)[_i]), (LAS unsigned*)(lds + (bufoff) + ldsw + _i * 8192), 16, 0, 0); } while (0)
; #define PG8_LDA(dst, b, h) do { _Pragma("unroll") for (int m = 0; m < 4; ++m) _Pragma("unroll") for (int k = 0; k < 2; ++k) dst[m][k] = *(const LAS bf16x8*)(lds + PG8_SA(b, h) + aoff + m * 2048 + k * 1024); } while (0)
; #define PG8_LDB(dst, b, h) do { _Pragma("unroll") for (int n = 0; n < 2; ++n) _Pragma("unroll") for (int k = 0; k < 2; ++k) dst[n][k] = *(const LAS bf16x8*)(lds + PG8_SB(b, h) + boff + n * 2048 + k * 1024); } while (0)
; #define PG8_MMA(ai, bj, At, Bt) do { __builtin_amdgcn_s_setprio(1); _Pragma("unroll") for (int m = 0; m < 4; ++m) _Pragma("unroll") for (int n = 0; n < 2; ++n) _Pragma("unroll") for (int k = 0; k < 2; ++k) \
;         acc[ai][bj][m][n] = __builtin_amdgcn_mfma_f32_16x16x32_bf16(Bt[n][k], At[m][k], acc[ai][bj][m][n], 0, 0, 0); __builtin_amdgcn_s_setprio(0); } while (0)
; #define PG8_WAIT_V(n) asm volatile("s_waitcnt vmcnt(" #n ")" ::: "memory")
; #define PG8_WAIT_L(n) asm volatile("s_waitcnt lgkmcnt(" #n ")" ::: "memory")
; #define PG8_BAR __builtin_amdgcn_s_barrier()
; #define PG8_SCHED __builtin_amdgcn_sched_barrier(0)
; template <class Epi, class Sched>
; __device__ __forceinline__ void gemm_phase(LAS unsigned char* lds, const Gemm g, const Sched& S, const Epi& E, const int tid) {
;     ...
;         for (int t = 0; t < nt; t += 2) {
;             const bool last = (t == nt - 2);
;             const char* a1 = cA + (size_t)(t + 1) * kstep;
;             const char* a2 = last ? nA : cA + (size_t)(t + 2) * kstep; const char* b2 = last ? nB : cB + (size_t)(t + 2) * kstep;
;             const char* a3 = a2 + kstep; const char* b3 = b2 + kstep;
;             PG8_LDB(B0, 0, 0); PG8_LDB(B1, 0, 1); PG8_SCHED; PG8_LDA(At, 0, 0); PG8_STAGE(PG8_SA(1, 1), a1 + hstep, voffA);
;             PG8_WAIT_V(8); PG8_WAIT_L(0); PG8_BAR; PG8_MMA(0, 0, At, B0); PG8_MMA(0, 1, At, B1); PG8_BAR; PG8_SCHED;
;             PG8_LDA(At, 0, 1); PG8_STAGE(PG8_SB(0, 0), b2, voffB); PG8_STAGE(PG8_SB(0, 1), b2 + hstep, voffB); PG8_STAGE(PG8_SA(0, 0), a2, voffA);
;             PG8_WAIT_V(8); PG8_WAIT_L(0); PG8_BAR; PG8_MMA(1, 0, At, B0); PG8_MMA(1, 1, At, B1); PG8_BAR; PG8_SCHED;
.LBB0_565:
.LBB0_566:
	s_or_b64 exec, exec, s[82:83]
	s_add_u32 vcc_lo, s80, 0x80
	s_addc_u32 vcc_hi, s81, 0
	s_add_u32 s61, s74, 0x100
	s_addc_u32 s67, s75, 0
	s_mov_b32 s74, 0
	s_add_i32 s80, s74, 2
	s_add_u32 s81, vcc_lo, 0x80
	s_addc_u32 s75, vcc_hi, 0
	s_add_i32 s3, 0, 0x10000
	s_cmp_eq_u32 s57, s74
	s_cselect_b32 s75, s71, s75
	s_cselect_b32 s74, s70, s81
	v_add_u32_e32 v70, s3, v232
	s_cselect_b32 s83, s73, s67
	s_cselect_b32 s82, s72, s61
	s_add_i32 s81, 0, 0x14000
	ds_read_b128 v[58:61], v70
	ds_read_b128 v[62:65], v70 offset:1024
	ds_read_b128 v[66:69], v70 offset:2048
	ds_read_b128 v[80:83], v70 offset:3072
	v_add_u32_e32 v70, s81, v232
	ds_read_b128 v[84:87], v70
	ds_read_b128 v[88:91], v70 offset:1024
	ds_read_b128 v[92:95], v70 offset:2048
	ds_read_b128 v[152:155], v70 offset:3072
	v_lshl_add_u64 v[70:71], vcc, 0, v[204:205]
	s_add_i32 m0, s97, 0xc000
	ds_read_b128 v[164:167], v240
	ds_read_b128 v[168:171], v240 offset:1024
	ds_read_b128 v[172:175], v240 offset:2048
	ds_read_b128 v[176:179], v240 offset:3072
	ds_read_b128 v[180:183], v240 offset:4096
	ds_read_b128 v[184:187], v240 offset:5120
	ds_read_b128 v[188:191], v240 offset:6144
	ds_read_b128 v[208:211], v240 offset:7168
	global_load_lds_dwordx4 v[70:71], off
	v_lshl_add_u64 v[70:71], vcc, 0, v[206:207]
	s_add_i32 m0, s97, 0xe000
	s_nop 0
	global_load_lds_dwordx4 v[70:71], off
	s_waitcnt vmcnt(8)
	s_waitcnt lgkmcnt(0)
	s_barrier
	s_waitcnt lgkmcnt(0)
	v_mfma_f32_16x16x32_bf16 v[160:163], v[58:61], v[164:167], 0
	v_mfma_f32_16x16x32_bf16 v[156:159], v[66:69], v[164:167], 0
	v_mfma_f32_16x16x32_bf16 v[136:139], v[66:69], v[172:175], 0
	v_mfma_f32_16x16x32_bf16 v[140:143], v[58:61], v[172:175], 0
	v_mfma_f32_16x16x32_bf16 v[124:127], v[58:61], v[180:183], 0
	v_mfma_f32_16x16x32_bf16 v[120:123], v[66:69], v[180:183], 0
	v_mfma_f32_16x16x32_bf16 v[104:107], v[66:69], v[188:191], 0
	v_mfma_f32_16x16x32_bf16 v[108:111], v[58:61], v[188:191], 0
	v_mfma_f32_16x16x32_bf16 v[160:163], v[62:65], v[168:171], v[160:163]
	v_mfma_f32_16x16x32_bf16 v[156:159], v[80:83], v[168:171], v[156:159]
	v_mfma_f32_16x16x32_bf16 v[136:139], v[80:83], v[176:179], v[136:139]
	v_mfma_f32_16x16x32_bf16 v[140:143], v[62:65], v[176:179], v[140:143]
	v_mfma_f32_16x16x32_bf16 v[124:127], v[62:65], v[184:187], v[124:127]
	v_mfma_f32_16x16x32_bf16 v[120:123], v[80:83], v[184:187], v[120:123]
	v_mfma_f32_16x16x32_bf16 v[104:107], v[80:83], v[208:211], v[104:107]
	v_mfma_f32_16x16x32_bf16 v[108:111], v[62:65], v[208:211], v[108:111]
	v_mfma_f32_16x16x32_bf16 v[148:151], v[84:87], v[164:167], 0
	v_mfma_f32_16x16x32_bf16 v[144:147], v[92:95], v[164:167], 0
	v_mfma_f32_16x16x32_bf16 v[128:131], v[92:95], v[172:175], 0
	v_mfma_f32_16x16x32_bf16 v[132:135], v[84:87], v[172:175], 0
	v_mfma_f32_16x16x32_bf16 v[116:119], v[84:87], v[180:183], 0
	v_mfma_f32_16x16x32_bf16 v[112:115], v[92:95], v[180:183], 0
	v_mfma_f32_16x16x32_bf16 v[96:99], v[92:95], v[188:191], 0
	v_mfma_f32_16x16x32_bf16 v[100:103], v[84:87], v[188:191], 0
	v_mfma_f32_16x16x32_bf16 v[148:151], v[88:91], v[168:171], v[148:151]
	v_mfma_f32_16x16x32_bf16 v[144:147], v[152:155], v[168:171], v[144:147]
	v_mfma_f32_16x16x32_bf16 v[128:131], v[152:155], v[176:179], v[128:131]
	v_mfma_f32_16x16x32_bf16 v[132:135], v[88:91], v[176:179], v[132:135]
	v_mfma_f32_16x16x32_bf16 v[116:119], v[88:91], v[184:187], v[116:119]
	v_mfma_f32_16x16x32_bf16 v[112:115], v[152:155], v[184:187], v[112:115]
	v_mfma_f32_16x16x32_bf16 v[96:99], v[152:155], v[208:211], v[96:99]
	v_mfma_f32_16x16x32_bf16 v[100:103], v[88:91], v[208:211], v[100:103]
	s_barrier
	s_add_i32 s3, s3, s94
	v_lshl_add_u64 v[212:213], s[82:83], 0, v[192:193]
	s_mov_b32 m0, s3
	ds_read_b128 v[164:167], v240 offset:16384
	ds_read_b128 v[168:171], v240 offset:17408
	ds_read_b128 v[172:175], v240 offset:18432
	ds_read_b128 v[176:179], v240 offset:19456
	ds_read_b128 v[180:183], v240 offset:20480
	ds_read_b128 v[184:187], v240 offset:21504
	ds_read_b128 v[188:191], v240 offset:22528
	ds_read_b128 v[208:211], v240 offset:23552
	global_load_lds_dwordx4 v192, s[82:83]
	s_add_i32 m0, s3, 0x2000
	v_lshl_add_u64 v[214:215], s[82:83], 0, v[198:199]
	s_add_u32 s82, s82, s12
	s_addc_u32 s83, s83, 0
	s_add_i32 s3, s81, s94
	global_load_lds_dwordx4 v[214:215], off
	v_lshl_add_u64 v[216:217], s[82:83], 0, v[192:193]
	s_mov_b32 m0, s3
	v_lshl_add_u64 v[218:219], s[82:83], 0, v[198:199]
	global_load_lds_dwordx4 v192, s[82:83]
	s_add_i32 m0, s3, 0x2000
	v_lshl_add_u64 v[220:221], s[74:75], 0, v[202:203]
	global_load_lds_dwordx4 v198, s[82:83]
	s_mov_b32 m0, s97
	v_lshl_add_u64 v[224:225], s[74:75], 0, v[200:201]
	global_load_lds_dwordx4 v202, s[74:75]
	s_mov_b32 m0, s98
	s_nop 0
	global_load_lds_dwordx4 v200, s[74:75]
	s_waitcnt vmcnt(8)
	s_waitcnt lgkmcnt(0)
	s_barrier
; #define PG8_STAGE(bufoff, gbase, voff) do { _Pragma("unroll") for (int _i = 0; _i < 2; ++_i) \
;         __builtin_amdgcn_global_load_lds((const unsigned*)((const char*)(gbase) + (voff)[_i]), (LAS unsigned*)(lds + (bufoff) + ldsw + _i * 8192), 16, 0, 0); } while (0)
; #define PG8_LDA(dst, b, h) do { _Pragma("unroll") for (int m = 0; m < 4; ++m) _Pragma("unroll") for (int k = 0; k < 2; ++k) dst[m][k] = *(const LAS bf16x8*)(lds + PG8_SA(b, h) + aoff + m * 2048 + k * 1024); } while (0)
; #define PG8_LDB(dst, b, h) do { _Pragma("unroll") for (int n = 0; n < 2; ++n) _Pragma("unroll") for (int k = 0; k < 2; ++k) dst[n][k] = *(const LAS bf16x8*)(lds + PG8_SB(b, h) + boff + n * 2048 + k * 1024); } while (0)
; #define PG8_MMA(ai, bj, At, Bt) do { __builtin_amdgcn_s_setprio(1); _Pragma("unroll") for (int m = 0; m < 4; ++m) _Pragma("unroll") for (int n = 0; n < 2; ++n) _Pragma("unroll") for (int k = 0; k < 2; ++k) \
;         acc[ai][bj][m][n] = __builtin_amdgcn_mfma_f32_16x16x32_bf16(Bt[n][k], At[m][k], acc[ai][bj][m][n], 0, 0, 0); __builtin_amdgcn_s_setprio(0); } while (0)
; #define PG8_WAIT_V(n) asm volatile("s_waitcnt vmcnt(" #n ")" ::: "memory")
; #define PG8_WAIT_L(n) asm volatile("s_waitcnt lgkmcnt(" #n ")" ::: "memory")
; #define PG8_BAR __builtin_amdgcn_s_barrier()
; #define PG8_SCHED __builtin_amdgcn_sched_barrier(0)
; template <class Epi, class Sched>
; __device__ __forceinline__ void gemm_phase(LAS unsigned char* lds, const Gemm g, const Sched& S, const Epi& E, const int tid) {
;     ...
;             PG8_WAIT_V(8); PG8_WAIT_L(0); PG8_BAR; PG8_MMA(0, 0, At, B0); PG8_MMA(0, 1, At, B1); PG8_BAR; PG8_SCHED;
;             PG8_LDA(At, 0, 1); PG8_STAGE(PG8_SB(0, 0), b2, voffB); PG8_STAGE(PG8_SB(0, 1), b2 + hstep, voffB); PG8_STAGE(PG8_SA(0, 0), a2, voffA);
;             PG8_WAIT_V(8); PG8_WAIT_L(0); PG8_BAR; PG8_MMA(1, 0, At, B0); PG8_MMA(1, 1, At, B1); PG8_BAR; PG8_SCHED;
;             PG8_LDB(B0, 1, 0); PG8_LDB(B1, 1, 1); PG8_SCHED; PG8_LDA(At, 1, 0); PG8_STAGE(PG8_SA(0, 1), a2 + hstep, voffA);
;             PG8_WAIT_V(8); PG8_WAIT_L(0); PG8_BAR; PG8_MMA(0, 0, At, B0); PG8_MMA(0, 1, At, B1); PG8_BAR; PG8_SCHED;
	s_waitcnt lgkmcnt(0)
	v_mfma_f32_16x16x32_bf16 v[76:79], v[58:61], v[164:167], 0
	v_mfma_f32_16x16x32_bf16 v[70:73], v[66:69], v[164:167], 0
	v_mfma_f32_16x16x32_bf16 v[40:43], v[66:69], v[172:175], 0
	v_mfma_f32_16x16x32_bf16 v[44:47], v[58:61], v[172:175], 0
	v_mfma_f32_16x16x32_bf16 v[28:31], v[58:61], v[180:183], 0
	v_mfma_f32_16x16x32_bf16 v[24:27], v[66:69], v[180:183], 0
	v_mfma_f32_16x16x32_bf16 v[8:11], v[66:69], v[188:191], 0
	v_mfma_f32_16x16x32_bf16 v[12:15], v[58:61], v[188:191], 0
	v_mfma_f32_16x16x32_bf16 v[76:79], v[62:65], v[168:171], v[76:79]
	v_mfma_f32_16x16x32_bf16 v[70:73], v[80:83], v[168:171], v[70:73]
	v_mfma_f32_16x16x32_bf16 v[40:43], v[80:83], v[176:179], v[40:43]
	v_mfma_f32_16x16x32_bf16 v[44:47], v[62:65], v[176:179], v[44:47]
	v_mfma_f32_16x16x32_bf16 v[28:31], v[62:65], v[184:187], v[28:31]
	v_mfma_f32_16x16x32_bf16 v[24:27], v[80:83], v[184:187], v[24:27]
	v_mfma_f32_16x16x32_bf16 v[8:11], v[80:83], v[208:211], v[8:11]
	v_mfma_f32_16x16x32_bf16 v[12:15], v[62:65], v[208:211], v[12:15]
	v_mfma_f32_16x16x32_bf16 v[52:55], v[84:87], v[164:167], 0
	v_mfma_f32_16x16x32_bf16 v[48:51], v[92:95], v[164:167], 0
	v_mfma_f32_16x16x32_bf16 v[32:35], v[92:95], v[172:175], 0
	v_mfma_f32_16x16x32_bf16 v[36:39], v[84:87], v[172:175], 0
	v_mfma_f32_16x16x32_bf16 v[20:23], v[84:87], v[180:183], 0
	v_mfma_f32_16x16x32_bf16 v[16:19], v[92:95], v[180:183], 0
	v_mfma_f32_16x16x32_bf16 v[0:3], v[92:95], v[188:191], 0
	v_mfma_f32_16x16x32_bf16 v[4:7], v[84:87], v[188:191], 0
	v_mfma_f32_16x16x32_bf16 v[52:55], v[88:91], v[168:171], v[52:55]
	v_mfma_f32_16x16x32_bf16 v[48:51], v[152:155], v[168:171], v[48:51]
	v_mfma_f32_16x16x32_bf16 v[32:35], v[152:155], v[176:179], v[32:35]
	v_mfma_f32_16x16x32_bf16 v[36:39], v[88:91], v[176:179], v[36:39]
	v_mfma_f32_16x16x32_bf16 v[20:23], v[88:91], v[184:187], v[20:23]
	v_mfma_f32_16x16x32_bf16 v[16:19], v[152:155], v[184:187], v[16:19]
	v_mfma_f32_16x16x32_bf16 v[0:3], v[152:155], v[208:211], v[0:3]
	v_mfma_f32_16x16x32_bf16 v[4:7], v[88:91], v[208:211], v[4:7]
	s_barrier
	s_add_i32 s3, 0, 0x18000
	v_add_u32_e32 v74, s3, v232
	s_add_i32 s81, 0, 0x1c000
	ds_read_b128 v[58:61], v74
	ds_read_b128 v[62:65], v74 offset:1024
	ds_read_b128 v[66:69], v74 offset:2048
	ds_read_b128 v[80:83], v74 offset:3072
	v_add_u32_e32 v74, s81, v232
	ds_read_b128 v[84:87], v74
	ds_read_b128 v[88:91], v74 offset:1024
	ds_read_b128 v[92:95], v74 offset:2048
	ds_read_b128 v[152:155], v74 offset:3072
	s_add_u32 s74, s74, s12
	s_addc_u32 s75, s75, 0
	s_mov_b32 m0, s99
	ds_read_b128 v[164:167], v240 offset:32768
	ds_read_b128 v[168:171], v240 offset:33792
	ds_read_b128 v[172:175], v240 offset:34816
	ds_read_b128 v[176:179], v240 offset:35840
	ds_read_b128 v[180:183], v240 offset:36864
	ds_read_b128 v[184:187], v240 offset:37888
	ds_read_b128 v[188:191], v240 offset:38912
	ds_read_b128 v[208:211], v240 offset:39936
	global_load_lds_dwordx4 v202, s[74:75]
	s_mov_b32 m0, s78
	s_nop 0
	global_load_lds_dwordx4 v200, s[74:75]
	s_waitcnt vmcnt(8)
	s_waitcnt lgkmcnt(0)
	s_barrier
	s_waitcnt lgkmcnt(0)
	v_mfma_f32_16x16x32_bf16 v[160:163], v[58:61], v[164:167], v[160:163]
	v_mfma_f32_16x16x32_bf16 v[156:159], v[66:69], v[164:167], v[156:159]
	v_mfma_f32_16x16x32_bf16 v[136:139], v[66:69], v[172:175], v[136:139]
	v_mfma_f32_16x16x32_bf16 v[140:143], v[58:61], v[172:175], v[140:143]
	v_mfma_f32_16x16x32_bf16 v[124:127], v[58:61], v[180:183], v[124:127]
	v_mfma_f32_16x16x32_bf16 v[120:123], v[66:69], v[180:183], v[120:123]
	v_mfma_f32_16x16x32_bf16 v[104:107], v[66:69], v[188:191], v[104:107]
	v_mfma_f32_16x16x32_bf16 v[108:111], v[58:61], v[188:191], v[108:111]
	v_mfma_f32_16x16x32_bf16 v[160:163], v[62:65], v[168:171], v[160:163]
	v_mfma_f32_16x16x32_bf16 v[156:159], v[80:83], v[168:171], v[156:159]
	v_mfma_f32_16x16x32_bf16 v[136:139], v[80:83], v[176:179], v[136:139]
	v_mfma_f32_16x16x32_bf16 v[140:143], v[62:65], v[176:179], v[140:143]
	v_mfma_f32_16x16x32_bf16 v[124:127], v[62:65], v[184:187], v[124:127]
	v_mfma_f32_16x16x32_bf16 v[120:123], v[80:83], v[184:187], v[120:123]
	v_mfma_f32_16x16x32_bf16 v[104:107], v[80:83], v[208:211], v[104:107]
	v_mfma_f32_16x16x32_bf16 v[108:111], v[62:65], v[208:211], v[108:111]
	v_mfma_f32_16x16x32_bf16 v[148:151], v[84:87], v[164:167], v[148:151]
	v_mfma_f32_16x16x32_bf16 v[144:147], v[92:95], v[164:167], v[144:147]
	v_mfma_f32_16x16x32_bf16 v[128:131], v[92:95], v[172:175], v[128:131]
	v_mfma_f32_16x16x32_bf16 v[132:135], v[84:87], v[172:175], v[132:135]
	v_mfma_f32_16x16x32_bf16 v[116:119], v[84:87], v[180:183], v[116:119]
	v_mfma_f32_16x16x32_bf16 v[112:115], v[92:95], v[180:183], v[112:115]
	v_mfma_f32_16x16x32_bf16 v[96:99], v[92:95], v[188:191], v[96:99]
	v_mfma_f32_16x16x32_bf16 v[100:103], v[84:87], v[188:191], v[100:103]
	v_mfma_f32_16x16x32_bf16 v[148:151], v[88:91], v[168:171], v[148:151]
	v_mfma_f32_16x16x32_bf16 v[144:147], v[152:155], v[168:171], v[144:147]
	v_mfma_f32_16x16x32_bf16 v[128:131], v[152:155], v[176:179], v[128:131]
	v_mfma_f32_16x16x32_bf16 v[132:135], v[88:91], v[176:179], v[132:135]
	v_mfma_f32_16x16x32_bf16 v[116:119], v[88:91], v[184:187], v[116:119]
	v_mfma_f32_16x16x32_bf16 v[112:115], v[152:155], v[184:187], v[112:115]
	v_mfma_f32_16x16x32_bf16 v[96:99], v[152:155], v[208:211], v[96:99]
	v_mfma_f32_16x16x32_bf16 v[100:103], v[88:91], v[208:211], v[100:103]
	s_barrier
; #define PG8_STAGE(bufoff, gbase, voff) do { _Pragma("unroll") for (int _i = 0; _i < 2; ++_i) \
;         __builtin_amdgcn_global_load_lds((const unsigned*)((const char*)(gbase) + (voff)[_i]), (LAS unsigned*)(lds + (bufoff) + ldsw + _i * 8192), 16, 0, 0); } while (0)
; #define PG8_LDA(dst, b, h) do { _Pragma("unroll") for (int m = 0; m < 4; ++m) _Pragma("unroll") for (int k = 0; k < 2; ++k) dst[m][k] = *(const LAS bf16x8*)(lds + PG8_SA(b, h) + aoff + m * 2048 + k * 1024); } while (0)
; #define PG8_LDB(dst, b, h) do { _Pragma("unroll") for (int n = 0; n < 2; ++n) _Pragma("unroll") for (int k = 0; k < 2; ++k) dst[n][k] = *(const LAS bf16x8*)(lds + PG8_SB(b, h) + boff + n * 2048 + k * 1024); } while (0)
; #define PG8_WAIT_V(n) asm volatile("s_waitcnt vmcnt(" #n ")" ::: "memory")
; #define PG8_BAR __builtin_amdgcn_s_barrier()
; template <class Epi, class Sched>
; __device__ __forceinline__ void gemm_phase(LAS unsigned char* lds, const Gemm g, const Sched& S, const Epi& E, const int tid) {
;     ...
;         for (int t = 0; t < nt; t += 2) {
;             const bool last = (t == nt - 2);
;             const char* a1 = cA + (size_t)(t + 1) * kstep;
;             const char* a2 = last ? nA : cA + (size_t)(t + 2) * kstep; const char* b2 = last ? nB : cB + (size_t)(t + 2) * kstep;
;             const char* a3 = a2 + kstep; const char* b3 = b2 + kstep;
;             PG8_LDB(B0, 0, 0); PG8_LDB(B1, 0, 1); PG8_SCHED; PG8_LDA(At, 0, 0); PG8_STAGE(PG8_SA(1, 1), a1 + hstep, voffA);
;             PG8_WAIT_V(8); PG8_WAIT_L(0); PG8_BAR; PG8_MMA(0, 0, At, B0); PG8_MMA(0, 1, At, B1); PG8_BAR; PG8_SCHED;
;             PG8_LDA(At, 0, 1); PG8_STAGE(PG8_SB(0, 0), b2, voffB); PG8_STAGE(PG8_SB(0, 1), b2 + hstep, voffB); PG8_STAGE(PG8_SA(0, 0), a2, voffA);
;             PG8_WAIT_V(8); PG8_WAIT_L(0); PG8_BAR; PG8_MMA(1, 0, At, B0); PG8_MMA(1, 1, At, B1); PG8_BAR; PG8_SCHED;
;             PG8_LDB(B0, 1, 0); PG8_LDB(B1, 1, 1); PG8_SCHED; PG8_LDA(At, 1, 0); PG8_STAGE(PG8_SA(0, 1), a2 + hstep, voffA);
;             PG8_WAIT_V(8); PG8_WAIT_L(0); PG8_BAR; PG8_MMA(0, 0, At, B0); PG8_MMA(0, 1, At, B1); PG8_BAR; PG8_SCHED;
;             PG8_LDA(At, 1, 1); PG8_STAGE(PG8_SB(1, 0), b3, voffB); PG8_STAGE(PG8_SB(1, 1), b3 + hstep, voffB); PG8_STAGE(PG8_SA(1, 0), a3, voffA);
;             PG8_WAIT_V(8); PG8_WAIT_L(0); PG8_BAR; PG8_MMA(1, 0, At, B0); PG8_MMA(1, 1, At, B1); PG8_BAR; PG8_SCHED;
	s_add_i32 s3, s3, s94
	v_lshl_add_u64 v[74:75], v[212:213], 0, s[68:69]
	s_mov_b32 m0, s3
	ds_read_b128 v[164:167], v240 offset:49152
	ds_read_b128 v[168:171], v240 offset:50176
	ds_read_b128 v[172:175], v240 offset:51200
	ds_read_b128 v[176:179], v240 offset:52224
	ds_read_b128 v[180:183], v240 offset:53248
	ds_read_b128 v[184:187], v240 offset:54272
	ds_read_b128 v[188:191], v240 offset:55296
	ds_read_b128 v[208:211], v240 offset:56320
	global_load_lds_dwordx4 v[74:75], off
	v_lshl_add_u64 v[74:75], v[214:215], 0, s[68:69]
	s_add_i32 m0, s3, 0x2000
	s_add_i32 s3, s81, s94
	global_load_lds_dwordx4 v[74:75], off
	v_lshl_add_u64 v[74:75], v[216:217], 0, s[68:69]
	s_mov_b32 m0, s3
	s_nop 0
	global_load_lds_dwordx4 v[74:75], off
	v_lshl_add_u64 v[74:75], v[218:219], 0, s[68:69]
	s_add_i32 m0, s3, 0x2000
	s_nop 0
	global_load_lds_dwordx4 v[74:75], off
	v_lshl_add_u64 v[74:75], v[220:221], 0, s[68:69]
	s_mov_b32 m0, s53
	s_nop 0
	global_load_lds_dwordx4 v[74:75], off
	v_lshl_add_u64 v[74:75], v[224:225], 0, s[68:69]
	s_mov_b32 m0, s56
	s_nop 0
	global_load_lds_dwordx4 v[74:75], off
	s_waitcnt vmcnt(8)
	s_waitcnt lgkmcnt(0)
	s_barrier
	s_waitcnt lgkmcnt(0)
	v_mfma_f32_16x16x32_bf16 v[74:77], v[58:61], v[164:167], v[76:79]
	v_mfma_f32_16x16x32_bf16 v[70:73], v[66:69], v[164:167], v[70:73]
	v_mfma_f32_16x16x32_bf16 v[40:43], v[66:69], v[172:175], v[40:43]
	v_mfma_f32_16x16x32_bf16 v[44:47], v[58:61], v[172:175], v[44:47]
	v_mfma_f32_16x16x32_bf16 v[28:31], v[58:61], v[180:183], v[28:31]
	v_mfma_f32_16x16x32_bf16 v[24:27], v[66:69], v[180:183], v[24:27]
	v_mfma_f32_16x16x32_bf16 v[8:11], v[66:69], v[188:191], v[8:11]
	v_mfma_f32_16x16x32_bf16 v[12:15], v[58:61], v[188:191], v[12:15]
	v_mfma_f32_16x16x32_bf16 v[76:79], v[62:65], v[168:171], v[74:77]
	v_mfma_f32_16x16x32_bf16 v[72:75], v[80:83], v[168:171], v[70:73]
	v_mfma_f32_16x16x32_bf16 v[40:43], v[80:83], v[176:179], v[40:43]
	v_mfma_f32_16x16x32_bf16 v[44:47], v[62:65], v[176:179], v[44:47]
	v_mfma_f32_16x16x32_bf16 v[28:31], v[62:65], v[184:187], v[28:31]
	v_mfma_f32_16x16x32_bf16 v[24:27], v[80:83], v[184:187], v[24:27]
	v_mfma_f32_16x16x32_bf16 v[8:11], v[80:83], v[208:211], v[8:11]
	v_mfma_f32_16x16x32_bf16 v[12:15], v[62:65], v[208:211], v[12:15]
	v_mfma_f32_16x16x32_bf16 v[52:55], v[84:87], v[164:167], v[52:55]
	v_mfma_f32_16x16x32_bf16 v[48:51], v[92:95], v[164:167], v[48:51]
	v_mfma_f32_16x16x32_bf16 v[32:35], v[92:95], v[172:175], v[32:35]
	v_mfma_f32_16x16x32_bf16 v[36:39], v[84:87], v[172:175], v[36:39]
	v_mfma_f32_16x16x32_bf16 v[20:23], v[84:87], v[180:183], v[20:23]
	v_mfma_f32_16x16x32_bf16 v[16:19], v[92:95], v[180:183], v[16:19]
	v_mfma_f32_16x16x32_bf16 v[0:3], v[92:95], v[188:191], v[0:3]
	v_mfma_f32_16x16x32_bf16 v[4:7], v[84:87], v[188:191], v[4:7]
	v_mfma_f32_16x16x32_bf16 v[52:55], v[88:91], v[168:171], v[52:55]
	v_mfma_f32_16x16x32_bf16 v[48:51], v[152:155], v[168:171], v[48:51]
	v_mfma_f32_16x16x32_bf16 v[32:35], v[152:155], v[176:179], v[32:35]
	v_mfma_f32_16x16x32_bf16 v[36:39], v[88:91], v[176:179], v[36:39]
	v_mfma_f32_16x16x32_bf16 v[20:23], v[88:91], v[184:187], v[20:23]
	v_mfma_f32_16x16x32_bf16 v[16:19], v[152:155], v[184:187], v[16:19]
	v_mfma_f32_16x16x32_bf16 v[0:3], v[152:155], v[208:211], v[0:3]
	v_mfma_f32_16x16x32_bf16 v[4:7], v[88:91], v[208:211], v[4:7]
	s_barrier
	s_add_u32 vcc_lo, vcc_lo, 0x100
	s_addc_u32 vcc_hi, vcc_hi, 0
	s_add_u32 s61, s61, 0x100
	s_addc_u32 s67, s67, 0
	s_cmp_ge_u32 s80, s52
	s_mov_b32 s74, s80
.LBB0_567:
	s_add_i32 s80, s74, 2
	s_add_u32 s81, vcc_lo, 0x80
	s_addc_u32 s75, vcc_hi, 0
	s_add_i32 s3, 0, 0x10000
	s_cmp_eq_u32 s57, s74
	s_cselect_b32 s75, s71, s75
	s_cselect_b32 s74, s70, s81
	v_add_u32_e32 v70, s3, v232
	s_cselect_b32 s83, s73, s67
	s_cselect_b32 s82, s72, s61
	s_add_i32 s81, 0, 0x14000
	ds_read_b128 v[58:61], v70
	ds_read_b128 v[62:65], v70 offset:1024
	ds_read_b128 v[66:69], v70 offset:2048
	ds_read_b128 v[80:83], v70 offset:3072
	v_add_u32_e32 v70, s81, v232
	ds_read_b128 v[84:87], v70
	ds_read_b128 v[88:91], v70 offset:1024
	ds_read_b128 v[92:95], v70 offset:2048
	ds_read_b128 v[152:155], v70 offset:3072
	v_lshl_add_u64 v[70:71], vcc, 0, v[204:205]
	s_add_i32 m0, s97, 0xc000
	ds_read_b128 v[164:167], v240
	ds_read_b128 v[168:171], v240 offset:1024
	ds_read_b128 v[172:175], v240 offset:2048
	ds_read_b128 v[176:179], v240 offset:3072
	ds_read_b128 v[180:183], v240 offset:4096
	ds_read_b128 v[184:187], v240 offset:5120
	ds_read_b128 v[188:191], v240 offset:6144
	ds_read_b128 v[208:211], v240 offset:7168
	global_load_lds_dwordx4 v[70:71], off
	v_lshl_add_u64 v[70:71], vcc, 0, v[206:207]
	s_add_i32 m0, s97, 0xe000
	s_nop 0
	global_load_lds_dwordx4 v[70:71], off
	s_waitcnt vmcnt(8)
	s_waitcnt lgkmcnt(0)
	s_barrier
; #define PG8_STAGE(bufoff, gbase, voff) do { _Pragma("unroll") for (int _i = 0; _i < 2; ++_i) \
;         __builtin_amdgcn_global_load_lds((const unsigned*)((const char*)(gbase) + (voff)[_i]), (LAS unsigned*)(lds + (bufoff) + ldsw + _i * 8192), 16, 0, 0); } while (0)
; #define PG8_LDA(dst, b, h) do { _Pragma("unroll") for (int m = 0; m < 4; ++m) _Pragma("unroll") for (int k = 0; k < 2; ++k) dst[m][k] = *(const LAS bf16x8*)(lds + PG8_SA(b, h) + aoff + m * 2048 + k * 1024); } while (0)
; #define PG8_MMA(ai, bj, At, Bt) do { __builtin_amdgcn_s_setprio(1); _Pragma("unroll") for (int m = 0; m < 4; ++m) _Pragma("unroll") for (int n = 0; n < 2; ++n) _Pragma("unroll") for (int k = 0; k < 2; ++k) \
;         acc[ai][bj][m][n] = __builtin_amdgcn_mfma_f32_16x16x32_bf16(Bt[n][k], At[m][k], acc[ai][bj][m][n], 0, 0, 0); __builtin_amdgcn_s_setprio(0); } while (0)
; #define PG8_WAIT_V(n) asm volatile("s_waitcnt vmcnt(" #n ")" ::: "memory")
; #define PG8_WAIT_L(n) asm volatile("s_waitcnt lgkmcnt(" #n ")" ::: "memory")
; #define PG8_BAR __builtin_amdgcn_s_barrier()
; #define PG8_SCHED __builtin_amdgcn_sched_barrier(0)
; template <class Epi, class Sched>
; __device__ __forceinline__ void gemm_phase(LAS unsigned char* lds, const Gemm g, const Sched& S, const Epi& E, const int tid) {
;     ...
;             PG8_WAIT_V(8); PG8_WAIT_L(0); PG8_BAR; PG8_MMA(0, 0, At, B0); PG8_MMA(0, 1, At, B1); PG8_BAR; PG8_SCHED;
;             PG8_LDA(At, 0, 1); PG8_STAGE(PG8_SB(0, 0), b2, voffB); PG8_STAGE(PG8_SB(0, 1), b2 + hstep, voffB); PG8_STAGE(PG8_SA(0, 0), a2, voffA);
;             PG8_WAIT_V(8); PG8_WAIT_L(0); PG8_BAR; PG8_MMA(1, 0, At, B0); PG8_MMA(1, 1, At, B1); PG8_BAR; PG8_SCHED;
	s_waitcnt lgkmcnt(0)
	v_mfma_f32_16x16x32_bf16 v[160:163], v[58:61], v[164:167], v[160:163]
	v_mfma_f32_16x16x32_bf16 v[156:159], v[66:69], v[164:167], v[156:159]
	v_mfma_f32_16x16x32_bf16 v[136:139], v[66:69], v[172:175], v[136:139]
	v_mfma_f32_16x16x32_bf16 v[140:143], v[58:61], v[172:175], v[140:143]
	v_mfma_f32_16x16x32_bf16 v[124:127], v[58:61], v[180:183], v[124:127]
	v_mfma_f32_16x16x32_bf16 v[120:123], v[66:69], v[180:183], v[120:123]
	v_mfma_f32_16x16x32_bf16 v[104:107], v[66:69], v[188:191], v[104:107]
	v_mfma_f32_16x16x32_bf16 v[108:111], v[58:61], v[188:191], v[108:111]
	v_mfma_f32_16x16x32_bf16 v[160:163], v[62:65], v[168:171], v[160:163]
	v_mfma_f32_16x16x32_bf16 v[156:159], v[80:83], v[168:171], v[156:159]
	v_mfma_f32_16x16x32_bf16 v[136:139], v[80:83], v[176:179], v[136:139]
	v_mfma_f32_16x16x32_bf16 v[140:143], v[62:65], v[176:179], v[140:143]
	v_mfma_f32_16x16x32_bf16 v[124:127], v[62:65], v[184:187], v[124:127]
	v_mfma_f32_16x16x32_bf16 v[120:123], v[80:83], v[184:187], v[120:123]
	v_mfma_f32_16x16x32_bf16 v[104:107], v[80:83], v[208:211], v[104:107]
	v_mfma_f32_16x16x32_bf16 v[108:111], v[62:65], v[208:211], v[108:111]
	v_mfma_f32_16x16x32_bf16 v[148:151], v[84:87], v[164:167], v[148:151]
	v_mfma_f32_16x16x32_bf16 v[144:147], v[92:95], v[164:167], v[144:147]
	v_mfma_f32_16x16x32_bf16 v[128:131], v[92:95], v[172:175], v[128:131]
	v_mfma_f32_16x16x32_bf16 v[132:135], v[84:87], v[172:175], v[132:135]
	v_mfma_f32_16x16x32_bf16 v[116:119], v[84:87], v[180:183], v[116:119]
	v_mfma_f32_16x16x32_bf16 v[112:115], v[92:95], v[180:183], v[112:115]
	v_mfma_f32_16x16x32_bf16 v[96:99], v[92:95], v[188:191], v[96:99]
	v_mfma_f32_16x16x32_bf16 v[100:103], v[84:87], v[188:191], v[100:103]
	v_mfma_f32_16x16x32_bf16 v[148:151], v[88:91], v[168:171], v[148:151]
	v_mfma_f32_16x16x32_bf16 v[144:147], v[152:155], v[168:171], v[144:147]
	v_mfma_f32_16x16x32_bf16 v[128:131], v[152:155], v[176:179], v[128:131]
	v_mfma_f32_16x16x32_bf16 v[132:135], v[88:91], v[176:179], v[132:135]
	v_mfma_f32_16x16x32_bf16 v[116:119], v[88:91], v[184:187], v[116:119]
	v_mfma_f32_16x16x32_bf16 v[112:115], v[152:155], v[184:187], v[112:115]
	v_mfma_f32_16x16x32_bf16 v[96:99], v[152:155], v[208:211], v[96:99]
	v_mfma_f32_16x16x32_bf16 v[100:103], v[88:91], v[208:211], v[100:103]
	s_barrier
	s_add_i32 s3, s3, s94
	v_lshl_add_u64 v[212:213], s[82:83], 0, v[192:193]
	s_mov_b32 m0, s3
	ds_read_b128 v[164:167], v240 offset:16384
	ds_read_b128 v[168:171], v240 offset:17408
	ds_read_b128 v[172:175], v240 offset:18432
	ds_read_b128 v[176:179], v240 offset:19456
	ds_read_b128 v[180:183], v240 offset:20480
	ds_read_b128 v[184:187], v240 offset:21504
	ds_read_b128 v[188:191], v240 offset:22528
	ds_read_b128 v[208:211], v240 offset:23552
	global_load_lds_dwordx4 v192, s[82:83]
	s_add_i32 m0, s3, 0x2000
	v_lshl_add_u64 v[214:215], s[82:83], 0, v[198:199]
	s_add_u32 s82, s82, s12
	s_addc_u32 s83, s83, 0
	s_add_i32 s3, s81, s94
	global_load_lds_dwordx4 v[214:215], off
	v_lshl_add_u64 v[216:217], s[82:83], 0, v[192:193]
	s_mov_b32 m0, s3
	v_lshl_add_u64 v[218:219], s[82:83], 0, v[198:199]
	global_load_lds_dwordx4 v192, s[82:83]
	s_add_i32 m0, s3, 0x2000
	v_lshl_add_u64 v[220:221], s[74:75], 0, v[202:203]
	global_load_lds_dwordx4 v198, s[82:83]
	s_mov_b32 m0, s97
	v_lshl_add_u64 v[224:225], s[74:75], 0, v[200:201]
	global_load_lds_dwordx4 v202, s[74:75]
	s_mov_b32 m0, s98
	s_nop 0
	global_load_lds_dwordx4 v200, s[74:75]
	s_waitcnt vmcnt(8)
	s_waitcnt lgkmcnt(0)
	s_barrier
	s_waitcnt lgkmcnt(0)
	v_mfma_f32_16x16x32_bf16 v[76:79], v[58:61], v[164:167], v[76:79]
	v_mfma_f32_16x16x32_bf16 v[70:73], v[66:69], v[164:167], v[72:75]
	v_mfma_f32_16x16x32_bf16 v[40:43], v[66:69], v[172:175], v[40:43]
	v_mfma_f32_16x16x32_bf16 v[44:47], v[58:61], v[172:175], v[44:47]
	v_mfma_f32_16x16x32_bf16 v[28:31], v[58:61], v[180:183], v[28:31]
	v_mfma_f32_16x16x32_bf16 v[24:27], v[66:69], v[180:183], v[24:27]
	v_mfma_f32_16x16x32_bf16 v[8:11], v[66:69], v[188:191], v[8:11]
	v_mfma_f32_16x16x32_bf16 v[12:15], v[58:61], v[188:191], v[12:15]
	v_mfma_f32_16x16x32_bf16 v[76:79], v[62:65], v[168:171], v[76:79]
	v_mfma_f32_16x16x32_bf16 v[70:73], v[80:83], v[168:171], v[70:73]
	v_mfma_f32_16x16x32_bf16 v[40:43], v[80:83], v[176:179], v[40:43]
	v_mfma_f32_16x16x32_bf16 v[44:47], v[62:65], v[176:179], v[44:47]
	v_mfma_f32_16x16x32_bf16 v[28:31], v[62:65], v[184:187], v[28:31]
	v_mfma_f32_16x16x32_bf16 v[24:27], v[80:83], v[184:187], v[24:27]
	v_mfma_f32_16x16x32_bf16 v[8:11], v[80:83], v[208:211], v[8:11]
	v_mfma_f32_16x16x32_bf16 v[12:15], v[62:65], v[208:211], v[12:15]
	v_mfma_f32_16x16x32_bf16 v[52:55], v[84:87], v[164:167], v[52:55]
	v_mfma_f32_16x16x32_bf16 v[48:51], v[92:95], v[164:167], v[48:51]
	v_mfma_f32_16x16x32_bf16 v[32:35], v[92:95], v[172:175], v[32:35]
	v_mfma_f32_16x16x32_bf16 v[36:39], v[84:87], v[172:175], v[36:39]
	v_mfma_f32_16x16x32_bf16 v[20:23], v[84:87], v[180:183], v[20:23]
	v_mfma_f32_16x16x32_bf16 v[16:19], v[92:95], v[180:183], v[16:19]
	v_mfma_f32_16x16x32_bf16 v[0:3], v[92:95], v[188:191], v[0:3]
	v_mfma_f32_16x16x32_bf16 v[4:7], v[84:87], v[188:191], v[4:7]
	v_mfma_f32_16x16x32_bf16 v[52:55], v[88:91], v[168:171], v[52:55]
	v_mfma_f32_16x16x32_bf16 v[48:51], v[152:155], v[168:171], v[48:51]
	v_mfma_f32_16x16x32_bf16 v[32:35], v[152:155], v[176:179], v[32:35]
	v_mfma_f32_16x16x32_bf16 v[36:39], v[88:91], v[176:179], v[36:39]
	v_mfma_f32_16x16x32_bf16 v[20:23], v[88:91], v[184:187], v[20:23]
	v_mfma_f32_16x16x32_bf16 v[16:19], v[152:155], v[184:187], v[16:19]
	v_mfma_f32_16x16x32_bf16 v[0:3], v[152:155], v[208:211], v[0:3]
	v_mfma_f32_16x16x32_bf16 v[4:7], v[88:91], v[208:211], v[4:7]
	s_barrier
; #define PG8_STAGE(bufoff, gbase, voff) do { _Pragma("unroll") for (int _i = 0; _i < 2; ++_i) \
;         __builtin_amdgcn_global_load_lds((const unsigned*)((const char*)(gbase) + (voff)[_i]), (LAS unsigned*)(lds + (bufoff) + ldsw + _i * 8192), 16, 0, 0); } while (0)
; #define PG8_LDA(dst, b, h) do { _Pragma("unroll") for (int m = 0; m < 4; ++m) _Pragma("unroll") for (int k = 0; k < 2; ++k) dst[m][k] = *(const LAS bf16x8*)(lds + PG8_SA(b, h) + aoff + m * 2048 + k * 1024); } while (0)
; #define PG8_LDB(dst, b, h) do { _Pragma("unroll") for (int n = 0; n < 2; ++n) _Pragma("unroll") for (int k = 0; k < 2; ++k) dst[n][k] = *(const LAS bf16x8*)(lds + PG8_SB(b, h) + boff + n * 2048 + k * 1024); } while (0)
; #define PG8_MMA(ai, bj, At, Bt) do { __builtin_amdgcn_s_setprio(1); _Pragma("unroll") for (int m = 0; m < 4; ++m) _Pragma("unroll") for (int n = 0; n < 2; ++n) _Pragma("unroll") for (int k = 0; k < 2; ++k) \
;         acc[ai][bj][m][n] = __builtin_amdgcn_mfma_f32_16x16x32_bf16(Bt[n][k], At[m][k], acc[ai][bj][m][n], 0, 0, 0); __builtin_amdgcn_s_setprio(0); } while (0)
; #define PG8_WAIT_V(n) asm volatile("s_waitcnt vmcnt(" #n ")" ::: "memory")
; #define PG8_WAIT_L(n) asm volatile("s_waitcnt lgkmcnt(" #n ")" ::: "memory")
; #define PG8_BAR __builtin_amdgcn_s_barrier()
; #define PG8_SCHED __builtin_amdgcn_sched_barrier(0)
; template <class Epi, class Sched>
; __device__ __forceinline__ void gemm_phase(LAS unsigned char* lds, const Gemm g, const Sched& S, const Epi& E, const int tid) {
;     ...
;             PG8_LDB(B0, 1, 0); PG8_LDB(B1, 1, 1); PG8_SCHED; PG8_LDA(At, 1, 0); PG8_STAGE(PG8_SA(0, 1), a2 + hstep, voffA);
;             PG8_WAIT_V(8); PG8_WAIT_L(0); PG8_BAR; PG8_MMA(0, 0, At, B0); PG8_MMA(0, 1, At, B1); PG8_BAR; PG8_SCHED;
;             PG8_LDA(At, 1, 1); PG8_STAGE(PG8_SB(1, 0), b3, voffB); PG8_STAGE(PG8_SB(1, 1), b3 + hstep, voffB); PG8_STAGE(PG8_SA(1, 0), a3, voffA);
;             PG8_WAIT_V(8); PG8_WAIT_L(0); PG8_BAR; PG8_MMA(1, 0, At, B0); PG8_MMA(1, 1, At, B1); PG8_BAR; PG8_SCHED;
;         }
	s_add_i32 s3, 0, 0x18000
	v_add_u32_e32 v74, s3, v232
	s_add_i32 s81, 0, 0x1c000
	ds_read_b128 v[58:61], v74
	ds_read_b128 v[62:65], v74 offset:1024
	ds_read_b128 v[66:69], v74 offset:2048
	ds_read_b128 v[80:83], v74 offset:3072
	v_add_u32_e32 v74, s81, v232
	ds_read_b128 v[84:87], v74
	ds_read_b128 v[88:91], v74 offset:1024
	ds_read_b128 v[92:95], v74 offset:2048
	ds_read_b128 v[152:155], v74 offset:3072
	s_add_u32 s74, s74, s12
	s_addc_u32 s75, s75, 0
	s_mov_b32 m0, s99
	ds_read_b128 v[164:167], v240 offset:32768
	ds_read_b128 v[168:171], v240 offset:33792
	ds_read_b128 v[172:175], v240 offset:34816
	ds_read_b128 v[176:179], v240 offset:35840
	ds_read_b128 v[180:183], v240 offset:36864
	ds_read_b128 v[184:187], v240 offset:37888
	ds_read_b128 v[188:191], v240 offset:38912
	ds_read_b128 v[208:211], v240 offset:39936
	global_load_lds_dwordx4 v202, s[74:75]
	s_mov_b32 m0, s78
	s_nop 0
	global_load_lds_dwordx4 v200, s[74:75]
	s_waitcnt vmcnt(8)
	s_waitcnt lgkmcnt(0)
	s_barrier
	s_waitcnt lgkmcnt(0)
	v_mfma_f32_16x16x32_bf16 v[160:163], v[58:61], v[164:167], v[160:163]
	v_mfma_f32_16x16x32_bf16 v[156:159], v[66:69], v[164:167], v[156:159]
	v_mfma_f32_16x16x32_bf16 v[136:139], v[66:69], v[172:175], v[136:139]
	v_mfma_f32_16x16x32_bf16 v[140:143], v[58:61], v[172:175], v[140:143]
	v_mfma_f32_16x16x32_bf16 v[124:127], v[58:61], v[180:183], v[124:127]
	v_mfma_f32_16x16x32_bf16 v[120:123], v[66:69], v[180:183], v[120:123]
	v_mfma_f32_16x16x32_bf16 v[104:107], v[66:69], v[188:191], v[104:107]
	v_mfma_f32_16x16x32_bf16 v[108:111], v[58:61], v[188:191], v[108:111]
	v_mfma_f32_16x16x32_bf16 v[160:163], v[62:65], v[168:171], v[160:163]
	v_mfma_f32_16x16x32_bf16 v[156:159], v[80:83], v[168:171], v[156:159]
	v_mfma_f32_16x16x32_bf16 v[136:139], v[80:83], v[176:179], v[136:139]
	v_mfma_f32_16x16x32_bf16 v[140:143], v[62:65], v[176:179], v[140:143]
	v_mfma_f32_16x16x32_bf16 v[124:127], v[62:65], v[184:187], v[124:127]
	v_mfma_f32_16x16x32_bf16 v[120:123], v[80:83], v[184:187], v[120:123]
	v_mfma_f32_16x16x32_bf16 v[104:107], v[80:83], v[208:211], v[104:107]
	v_mfma_f32_16x16x32_bf16 v[108:111], v[62:65], v[208:211], v[108:111]
	v_mfma_f32_16x16x32_bf16 v[148:151], v[84:87], v[164:167], v[148:151]
	v_mfma_f32_16x16x32_bf16 v[144:147], v[92:95], v[164:167], v[144:147]
	v_mfma_f32_16x16x32_bf16 v[128:131], v[92:95], v[172:175], v[128:131]
	v_mfma_f32_16x16x32_bf16 v[132:135], v[84:87], v[172:175], v[132:135]
	v_mfma_f32_16x16x32_bf16 v[116:119], v[84:87], v[180:183], v[116:119]
	v_mfma_f32_16x16x32_bf16 v[112:115], v[92:95], v[180:183], v[112:115]
	v_mfma_f32_16x16x32_bf16 v[96:99], v[92:95], v[188:191], v[96:99]
	v_mfma_f32_16x16x32_bf16 v[100:103], v[84:87], v[188:191], v[100:103]
	v_mfma_f32_16x16x32_bf16 v[148:151], v[88:91], v[168:171], v[148:151]
	v_mfma_f32_16x16x32_bf16 v[144:147], v[152:155], v[168:171], v[144:147]
	v_mfma_f32_16x16x32_bf16 v[128:131], v[152:155], v[176:179], v[128:131]
	v_mfma_f32_16x16x32_bf16 v[132:135], v[88:91], v[176:179], v[132:135]
	v_mfma_f32_16x16x32_bf16 v[116:119], v[88:91], v[184:187], v[116:119]
	v_mfma_f32_16x16x32_bf16 v[112:115], v[152:155], v[184:187], v[112:115]
	v_mfma_f32_16x16x32_bf16 v[96:99], v[152:155], v[208:211], v[96:99]
	v_mfma_f32_16x16x32_bf16 v[100:103], v[88:91], v[208:211], v[100:103]
	s_barrier
	s_add_i32 s3, s3, s94
	v_lshl_add_u64 v[74:75], v[212:213], 0, s[68:69]
	s_mov_b32 m0, s3
	ds_read_b128 v[164:167], v240 offset:49152
	ds_read_b128 v[168:171], v240 offset:50176
	ds_read_b128 v[172:175], v240 offset:51200
	ds_read_b128 v[176:179], v240 offset:52224
	ds_read_b128 v[180:183], v240 offset:53248
	ds_read_b128 v[184:187], v240 offset:54272
	ds_read_b128 v[188:191], v240 offset:55296
	ds_read_b128 v[208:211], v240 offset:56320
	global_load_lds_dwordx4 v[74:75], off
	v_lshl_add_u64 v[74:75], v[214:215], 0, s[68:69]
	s_add_i32 m0, s3, 0x2000
	s_add_i32 s3, s81, s94
	global_load_lds_dwordx4 v[74:75], off
	v_lshl_add_u64 v[74:75], v[216:217], 0, s[68:69]
	s_mov_b32 m0, s3
	s_nop 0
	global_load_lds_dwordx4 v[74:75], off
	v_lshl_add_u64 v[74:75], v[218:219], 0, s[68:69]
	s_add_i32 m0, s3, 0x2000
	s_nop 0
	global_load_lds_dwordx4 v[74:75], off
	v_lshl_add_u64 v[74:75], v[220:221], 0, s[68:69]
	s_mov_b32 m0, s53
	s_nop 0
	global_load_lds_dwordx4 v[74:75], off
	v_lshl_add_u64 v[74:75], v[224:225], 0, s[68:69]
	s_mov_b32 m0, s56
	s_nop 0
	global_load_lds_dwordx4 v[74:75], off
	s_waitcnt vmcnt(8)
	s_waitcnt lgkmcnt(0)
	s_barrier
	s_waitcnt lgkmcnt(0)
	v_mfma_f32_16x16x32_bf16 v[74:77], v[58:61], v[164:167], v[76:79]
	v_mfma_f32_16x16x32_bf16 v[70:73], v[66:69], v[164:167], v[70:73]
	v_mfma_f32_16x16x32_bf16 v[40:43], v[66:69], v[172:175], v[40:43]
	v_mfma_f32_16x16x32_bf16 v[44:47], v[58:61], v[172:175], v[44:47]
	v_mfma_f32_16x16x32_bf16 v[28:31], v[58:61], v[180:183], v[28:31]
	v_mfma_f32_16x16x32_bf16 v[24:27], v[66:69], v[180:183], v[24:27]
	v_mfma_f32_16x16x32_bf16 v[8:11], v[66:69], v[188:191], v[8:11]
	v_mfma_f32_16x16x32_bf16 v[12:15], v[58:61], v[188:191], v[12:15]
	v_mfma_f32_16x16x32_bf16 v[76:79], v[62:65], v[168:171], v[74:77]
	v_mfma_f32_16x16x32_bf16 v[72:75], v[80:83], v[168:171], v[70:73]
	v_mfma_f32_16x16x32_bf16 v[40:43], v[80:83], v[176:179], v[40:43]
	v_mfma_f32_16x16x32_bf16 v[44:47], v[62:65], v[176:179], v[44:47]
	v_mfma_f32_16x16x32_bf16 v[28:31], v[62:65], v[184:187], v[28:31]
	v_mfma_f32_16x16x32_bf16 v[24:27], v[80:83], v[184:187], v[24:27]
	v_mfma_f32_16x16x32_bf16 v[8:11], v[80:83], v[208:211], v[8:11]
	v_mfma_f32_16x16x32_bf16 v[12:15], v[62:65], v[208:211], v[12:15]
	v_mfma_f32_16x16x32_bf16 v[52:55], v[84:87], v[164:167], v[52:55]
	v_mfma_f32_16x16x32_bf16 v[48:51], v[92:95], v[164:167], v[48:51]
	v_mfma_f32_16x16x32_bf16 v[32:35], v[92:95], v[172:175], v[32:35]
	v_mfma_f32_16x16x32_bf16 v[36:39], v[84:87], v[172:175], v[36:39]
	v_mfma_f32_16x16x32_bf16 v[20:23], v[84:87], v[180:183], v[20:23]
	v_mfma_f32_16x16x32_bf16 v[16:19], v[92:95], v[180:183], v[16:19]
	v_mfma_f32_16x16x32_bf16 v[0:3], v[92:95], v[188:191], v[0:3]
	v_mfma_f32_16x16x32_bf16 v[4:7], v[84:87], v[188:191], v[4:7]
	v_mfma_f32_16x16x32_bf16 v[52:55], v[88:91], v[168:171], v[52:55]
	v_mfma_f32_16x16x32_bf16 v[48:51], v[152:155], v[168:171], v[48:51]
	v_mfma_f32_16x16x32_bf16 v[32:35], v[152:155], v[176:179], v[32:35]
	v_mfma_f32_16x16x32_bf16 v[36:39], v[88:91], v[176:179], v[36:39]
	v_mfma_f32_16x16x32_bf16 v[20:23], v[88:91], v[184:187], v[20:23]
	v_mfma_f32_16x16x32_bf16 v[16:19], v[152:155], v[184:187], v[16:19]
	v_mfma_f32_16x16x32_bf16 v[0:3], v[152:155], v[208:211], v[0:3]
	v_mfma_f32_16x16x32_bf16 v[4:7], v[88:91], v[208:211], v[4:7]
	s_barrier
	s_add_u32 vcc_lo, vcc_lo, 0x100
	s_addc_u32 vcc_hi, vcc_hi, 0
	s_add_u32 s61, s61, 0x100
	s_addc_u32 s67, s67, 0
	s_cmp_ge_u32 s80, s52
	s_mov_b32 s74, s80
	s_cbranch_scc0 .LBB0_567
	s_and_b64 vcc, exec, s[64:65]
	s_cbranch_vccz .LBB0_570
	s_barrier
